# K-loop LDS-DMA issue rebalanced 2+6 -> 4+4 per load segment (As[b][0] staged one segment later), SP2 waits vmcnt(6)
# baseline (speedup 1.0000x reference)
; #define PG8_STAGE(bufoff, gbase, voff) do { _Pragma("unroll") for (int _i = 0; _i < 2; ++_i) \
;         __builtin_amdgcn_global_load_lds((const unsigned*)((const char*)(gbase) + (voff)[_i]), (PG8_LAS unsigned*)(lds + (bufoff) + ldsw + _i * 8192), 16, 0, 0); } while (0)
; #define PG8_LDA(dst, b, h) do { _Pragma("unroll") for (int m = 0; m < 4; ++m) _Pragma("unroll") for (int k = 0; k < 2; ++k) dst[m][k] = *(const PG8_LAS bf16x8*)(lds + PG8_SA(b, h) + aoff + m * 2048 + k * 1024); } while (0)
; #define PG8_LDB(dst, b, h) do { _Pragma("unroll") for (int n = 0; n < 2; ++n) _Pragma("unroll") for (int k = 0; k < 2; ++k) dst[n][k] = *(const PG8_LAS bf16x8*)(lds + PG8_SB(b, h) + boff + n * 2048 + k * 1024); } while (0)
; #define PG8_MMA(ai, bj, At, Bt) do { __builtin_amdgcn_s_setprio(1); _Pragma("unroll") for (int m = 0; m < 4; ++m) _Pragma("unroll") for (int n = 0; n < 2; ++n) _Pragma("unroll") for (int k = 0; k < 2; ++k) \
;         acc[ai][bj][m][n] = __builtin_amdgcn_mfma_f32_16x16x32_bf16(Bt[n][k], At[m][k], acc[ai][bj][m][n], 0, 0, 0); __builtin_amdgcn_s_setprio(0); } while (0)
; #define PG8_WAIT_V(n) asm volatile("s_waitcnt vmcnt(" #n ")" ::: "memory")
; #define PG8_WAIT_L(n) asm volatile("s_waitcnt lgkmcnt(" #n ")" ::: "memory")
; #define PG8_BAR __builtin_amdgcn_s_barrier()
; #define PG8_SCHED __builtin_amdgcn_sched_barrier(0)
; template <class Epi, class Sched, bool ALIGN_EPI = false, bool SP2 = false>
; __device__ __forceinline__ void gemm_phase(PG8_LAS unsigned char* lds, const Gemm g, const Sched& S, const Epi& E) {
;     ...
;             PG8_LDB(B0, 0, 0); PG8_LDB(B1, 0, 1); PG8_SCHED; PG8_LDA(At, 0, 0); PG8_STAGE(PG8_SA(1, 1), a1 + hstep, voffA);
;             PG8_WAIT_V(8); PG8_WAIT_L(0); PG8_BAR; PG8_MMA(0, 0, At, B0); PG8_MMA(0, 1, At, B1); PG8_BAR; PG8_SCHED;
;             PG8_LDA(At, 0, 1); PG8_STAGE(PG8_SB(0, 0), b2, voffB); PG8_STAGE(PG8_SB(0, 1), b2 + hstep, voffB); PG8_STAGE(PG8_SA(0, 0), a2, voffA);
.LBB0_289:
	ds_read_b128 v[146:149], v156
	ds_read_b128 v[160:163], v156 offset:1024
	ds_read_b128 v[164:167], v156 offset:2048
	ds_read_b128 v[168:171], v156 offset:3072
	ds_read_b128 v[180:183], v157
	ds_read_b128 v[184:187], v157 offset:1024
	ds_read_b128 v[188:191], v157 offset:2048
	ds_read_b128 v[192:195], v157 offset:3072
	s_add_u32 s24, s22, 0xfff80080
	s_addc_u32 s25, s23, -1
	s_cmp_eq_u32 s50, 28
	s_cselect_b32 s27, s15, s25
	s_cselect_b32 s26, s46, s24
	s_cselect_b32 s25, s13, s49
	s_cselect_b32 s24, s47, s48
	s_mov_b32 s38, 0xfff80000
	s_mov_b32 s39, -1
	v_lshl_add_u64 v[150:151], s[22:23], 0, v[138:139]
	v_lshl_add_u64 v[150:151], v[150:151], 0, s[38:39]
	s_mov_b32 m0, s36
	s_nop 0
	global_load_lds_dwordx4 v[150:151], off
	v_lshl_add_u64 v[150:151], s[22:23], 0, v[140:141]
	v_lshl_add_u64 v[150:151], v[150:151], 0, s[38:39]
	s_mov_b32 m0, s37
	s_nop 0
	global_load_lds_dwordx4 v[150:151], off
	v_lshl_add_u64 v[150:151], s[22:23], 0, v[138:139]
	s_add_i32 m0, s21, 0xc000
	ds_read_b128 v[196:199], v158
	ds_read_b128 v[200:203], v158 offset:1024
	ds_read_b128 v[204:207], v158 offset:2048
	ds_read_b128 v[208:211], v158 offset:3072
	ds_read_b128 v[212:215], v158 offset:4096
	ds_read_b128 v[216:219], v158 offset:5120
	ds_read_b128 v[220:223], v158 offset:6144
	ds_read_b128 v[224:227], v158 offset:7168
	global_load_lds_dwordx4 v[150:151], off
	v_lshl_add_u64 v[150:151], s[22:23], 0, v[140:141]
	s_add_i32 m0, s21, 0xe000
	s_nop 0
	global_load_lds_dwordx4 v[150:151], off
	s_waitcnt vmcnt(8)
	s_waitcnt lgkmcnt(0)
	s_barrier
	s_setprio 1
	s_waitcnt lgkmcnt(0)
	v_mfma_f32_16x16x32_bf16 v[124:127], v[146:149], v[196:199], v[124:127]
	v_mfma_f32_16x16x32_bf16 v[120:123], v[164:167], v[196:199], v[120:123]
	v_mfma_f32_16x16x32_bf16 v[116:119], v[146:149], v[204:207], v[116:119]
	v_mfma_f32_16x16x32_bf16 v[108:111], v[164:167], v[204:207], v[108:111]
	v_mfma_f32_16x16x32_bf16 v[100:103], v[146:149], v[212:215], v[100:103]
	v_mfma_f32_16x16x32_bf16 v[92:95], v[164:167], v[212:215], v[92:95]
	v_mfma_f32_16x16x32_bf16 v[84:87], v[146:149], v[220:223], v[84:87]
	v_mfma_f32_16x16x32_bf16 v[76:79], v[164:167], v[220:223], v[76:79]
	v_mfma_f32_16x16x32_bf16 v[124:127], v[160:163], v[200:203], v[124:127]
	v_mfma_f32_16x16x32_bf16 v[120:123], v[168:171], v[200:203], v[120:123]
	v_mfma_f32_16x16x32_bf16 v[116:119], v[160:163], v[208:211], v[116:119]
	v_mfma_f32_16x16x32_bf16 v[108:111], v[168:171], v[208:211], v[108:111]
	v_mfma_f32_16x16x32_bf16 v[100:103], v[160:163], v[216:219], v[100:103]
	v_mfma_f32_16x16x32_bf16 v[92:95], v[168:171], v[216:219], v[92:95]
	v_mfma_f32_16x16x32_bf16 v[84:87], v[160:163], v[224:227], v[84:87]
	v_mfma_f32_16x16x32_bf16 v[76:79], v[168:171], v[224:227], v[76:79]
	s_setprio 0
	s_setprio 1
	v_mfma_f32_16x16x32_bf16 v[112:115], v[180:183], v[196:199], v[112:115]
	v_mfma_f32_16x16x32_bf16 v[104:107], v[188:191], v[196:199], v[104:107]
	v_mfma_f32_16x16x32_bf16 v[96:99], v[180:183], v[204:207], v[96:99]
	v_mfma_f32_16x16x32_bf16 v[88:91], v[188:191], v[204:207], v[88:91]
	v_mfma_f32_16x16x32_bf16 v[80:83], v[180:183], v[212:215], v[80:83]
	v_mfma_f32_16x16x32_bf16 v[72:75], v[188:191], v[212:215], v[72:75]
	v_mfma_f32_16x16x32_bf16 v[68:71], v[180:183], v[220:223], v[68:71]
	v_mfma_f32_16x16x32_bf16 v[64:67], v[188:191], v[220:223], v[64:67]
	v_mfma_f32_16x16x32_bf16 v[112:115], v[184:187], v[200:203], v[112:115]
	v_mfma_f32_16x16x32_bf16 v[104:107], v[192:195], v[200:203], v[104:107]
	v_mfma_f32_16x16x32_bf16 v[96:99], v[184:187], v[208:211], v[96:99]
	v_mfma_f32_16x16x32_bf16 v[88:91], v[192:195], v[208:211], v[88:91]
	v_mfma_f32_16x16x32_bf16 v[80:83], v[184:187], v[216:219], v[80:83]
	v_mfma_f32_16x16x32_bf16 v[72:75], v[192:195], v[216:219], v[72:75]
	v_mfma_f32_16x16x32_bf16 v[68:71], v[184:187], v[224:227], v[68:71]
	v_mfma_f32_16x16x32_bf16 v[64:67], v[192:195], v[224:227], v[64:67]
	s_setprio 0
	s_barrier
	s_add_i32 s51, s40, s30
	v_lshl_add_u64 v[150:151], s[24:25], 0, v[134:135]
	s_mov_b32 m0, s51
	ds_read_b128 v[196:199], v158 offset:16384
	ds_read_b128 v[200:203], v158 offset:17408
	ds_read_b128 v[204:207], v158 offset:18432
	ds_read_b128 v[208:211], v158 offset:19456
	ds_read_b128 v[212:215], v158 offset:20480
	ds_read_b128 v[216:219], v158 offset:21504
	ds_read_b128 v[220:223], v158 offset:22528
	ds_read_b128 v[224:227], v158 offset:23552
	global_load_lds_dwordx4 v[150:151], off
	s_add_i32 m0, s51, 0x2000
	s_add_u32 s52, s24, 0x80000
	v_lshl_add_u64 v[228:229], s[24:25], 0, v[130:131]
	s_addc_u32 s53, s25, 0
	s_add_i32 s51, s41, s30
	global_load_lds_dwordx4 v[228:229], off
	v_lshl_add_u64 v[230:231], s[52:53], 0, v[134:135]
	s_mov_b32 m0, s51
	v_lshl_add_u64 v[232:233], s[26:27], 0, v[132:133]
	global_load_lds_dwordx4 v[230:231], off
	v_lshl_add_u64 v[230:231], s[52:53], 0, v[130:131]
	s_add_i32 m0, s51, 0x2000
	s_nop 0
	global_load_lds_dwordx4 v[230:231], off
	v_lshl_add_u64 v[230:231], s[26:27], 0, v[136:137]
	s_waitcnt vmcnt(6)
	s_waitcnt lgkmcnt(0)
	s_barrier
; #define PG8_STAGE(bufoff, gbase, voff) do { _Pragma("unroll") for (int _i = 0; _i < 2; ++_i) \
;         __builtin_amdgcn_global_load_lds((const unsigned*)((const char*)(gbase) + (voff)[_i]), (PG8_LAS unsigned*)(lds + (bufoff) + ldsw + _i * 8192), 16, 0, 0); } while (0)
; #define PG8_LDA(dst, b, h) do { _Pragma("unroll") for (int m = 0; m < 4; ++m) _Pragma("unroll") for (int k = 0; k < 2; ++k) dst[m][k] = *(const PG8_LAS bf16x8*)(lds + PG8_SA(b, h) + aoff + m * 2048 + k * 1024); } while (0)
; #define PG8_LDB(dst, b, h) do { _Pragma("unroll") for (int n = 0; n < 2; ++n) _Pragma("unroll") for (int k = 0; k < 2; ++k) dst[n][k] = *(const PG8_LAS bf16x8*)(lds + PG8_SB(b, h) + boff + n * 2048 + k * 1024); } while (0)
; #define PG8_MMA(ai, bj, At, Bt) do { __builtin_amdgcn_s_setprio(1); _Pragma("unroll") for (int m = 0; m < 4; ++m) _Pragma("unroll") for (int n = 0; n < 2; ++n) _Pragma("unroll") for (int k = 0; k < 2; ++k) \
;         acc[ai][bj][m][n] = __builtin_amdgcn_mfma_f32_16x16x32_bf16(Bt[n][k], At[m][k], acc[ai][bj][m][n], 0, 0, 0); __builtin_amdgcn_s_setprio(0); } while (0)
; #define PG8_WAIT_V(n) asm volatile("s_waitcnt vmcnt(" #n ")" ::: "memory")
; #define PG8_WAIT_L(n) asm volatile("s_waitcnt lgkmcnt(" #n ")" ::: "memory")
; #define PG8_BAR __builtin_amdgcn_s_barrier()
; #define PG8_SCHED __builtin_amdgcn_sched_barrier(0)
; template <class Epi, class Sched, bool ALIGN_EPI = false, bool SP2 = false>
; __device__ __forceinline__ void gemm_phase(PG8_LAS unsigned char* lds, const Gemm g, const Sched& S, const Epi& E) {
;     ...
;             PG8_WAIT_V(8); PG8_WAIT_L(0); PG8_BAR; PG8_MMA(1, 0, At, B0); PG8_MMA(1, 1, At, B1); PG8_BAR; PG8_SCHED;
;             PG8_LDB(B0, 1, 0); PG8_LDB(B1, 1, 1); PG8_SCHED; PG8_LDA(At, 1, 0); PG8_STAGE(PG8_SA(0, 1), a2 + hstep, voffA);
;             PG8_WAIT_V(8); PG8_WAIT_L(0); PG8_BAR; PG8_MMA(0, 0, At, B0); PG8_MMA(0, 1, At, B1); PG8_BAR; PG8_SCHED;
	s_setprio 1
	s_waitcnt lgkmcnt(0)
	v_mfma_f32_16x16x32_bf16 v[60:63], v[146:149], v[196:199], v[60:63]
	v_mfma_f32_16x16x32_bf16 v[56:59], v[164:167], v[196:199], v[56:59]
	v_mfma_f32_16x16x32_bf16 v[52:55], v[146:149], v[204:207], v[52:55]
	v_mfma_f32_16x16x32_bf16 v[44:47], v[164:167], v[204:207], v[44:47]
	v_mfma_f32_16x16x32_bf16 v[36:39], v[146:149], v[212:215], v[36:39]
	v_mfma_f32_16x16x32_bf16 v[28:31], v[164:167], v[212:215], v[28:31]
	v_mfma_f32_16x16x32_bf16 v[20:23], v[146:149], v[220:223], v[20:23]
	v_mfma_f32_16x16x32_bf16 v[12:15], v[164:167], v[220:223], v[12:15]
	v_mfma_f32_16x16x32_bf16 v[60:63], v[160:163], v[200:203], v[60:63]
	v_mfma_f32_16x16x32_bf16 v[56:59], v[168:171], v[200:203], v[56:59]
	v_mfma_f32_16x16x32_bf16 v[52:55], v[160:163], v[208:211], v[52:55]
	v_mfma_f32_16x16x32_bf16 v[44:47], v[168:171], v[208:211], v[44:47]
	v_mfma_f32_16x16x32_bf16 v[36:39], v[160:163], v[216:219], v[36:39]
	v_mfma_f32_16x16x32_bf16 v[28:31], v[168:171], v[216:219], v[28:31]
	v_mfma_f32_16x16x32_bf16 v[20:23], v[160:163], v[224:227], v[20:23]
	v_mfma_f32_16x16x32_bf16 v[12:15], v[168:171], v[224:227], v[12:15]
	s_setprio 0
	s_setprio 1
	v_mfma_f32_16x16x32_bf16 v[48:51], v[180:183], v[196:199], v[48:51]
	v_mfma_f32_16x16x32_bf16 v[40:43], v[188:191], v[196:199], v[40:43]
	v_mfma_f32_16x16x32_bf16 v[32:35], v[180:183], v[204:207], v[32:35]
	v_mfma_f32_16x16x32_bf16 v[24:27], v[188:191], v[204:207], v[24:27]
	v_mfma_f32_16x16x32_bf16 v[16:19], v[180:183], v[212:215], v[16:19]
	v_mfma_f32_16x16x32_bf16 v[8:11], v[188:191], v[212:215], v[8:11]
	v_mfma_f32_16x16x32_bf16 v[4:7], v[180:183], v[220:223], v[4:7]
	v_mfma_f32_16x16x32_bf16 v[0:3], v[188:191], v[220:223], v[0:3]
	v_mfma_f32_16x16x32_bf16 v[48:51], v[184:187], v[200:203], v[48:51]
	v_mfma_f32_16x16x32_bf16 v[40:43], v[192:195], v[200:203], v[40:43]
	v_mfma_f32_16x16x32_bf16 v[32:35], v[184:187], v[208:211], v[32:35]
	v_mfma_f32_16x16x32_bf16 v[24:27], v[192:195], v[208:211], v[24:27]
	v_mfma_f32_16x16x32_bf16 v[16:19], v[184:187], v[216:219], v[16:19]
	v_mfma_f32_16x16x32_bf16 v[8:11], v[192:195], v[216:219], v[8:11]
	v_mfma_f32_16x16x32_bf16 v[4:7], v[184:187], v[224:227], v[4:7]
	v_mfma_f32_16x16x32_bf16 v[0:3], v[192:195], v[224:227], v[0:3]
	s_setprio 0
	s_barrier
	s_add_i32 s51, 0, 0x18000
	v_add_u32_e32 v159, s51, v153
	s_add_i32 s52, 0, 0x1c000
	ds_read_b128 v[146:149], v159
	ds_read_b128 v[160:163], v159 offset:1024
	ds_read_b128 v[164:167], v159 offset:2048
	ds_read_b128 v[168:171], v159 offset:3072
	v_add_u32_e32 v159, s52, v153
	ds_read_b128 v[180:183], v159
	ds_read_b128 v[184:187], v159 offset:1024
	ds_read_b128 v[188:191], v159 offset:2048
	ds_read_b128 v[192:195], v159 offset:3072
	s_add_u32 s26, s26, 0x80000
	s_addc_u32 s27, s27, 0
	s_mov_b32 m0, s21
	s_nop 0
	global_load_lds_dwordx4 v[230:231], off
	s_mov_b32 m0, s33
	s_nop 0
	global_load_lds_dwordx4 v[232:233], off
	s_mov_b32 m0, s34
	v_lshl_add_u64 v[234:235], s[26:27], 0, v[136:137]
	ds_read_b128 v[196:199], v158 offset:32768
	ds_read_b128 v[200:203], v158 offset:33792
	ds_read_b128 v[204:207], v158 offset:34816
	ds_read_b128 v[208:211], v158 offset:35840
	ds_read_b128 v[212:215], v158 offset:36864
	ds_read_b128 v[216:219], v158 offset:37888
	ds_read_b128 v[220:223], v158 offset:38912
	ds_read_b128 v[224:227], v158 offset:39936
	global_load_lds_dwordx4 v[234:235], off
	v_lshl_add_u64 v[234:235], s[26:27], 0, v[132:133]
	s_mov_b32 m0, s35
	s_nop 0
	global_load_lds_dwordx4 v[234:235], off
	s_waitcnt vmcnt(8)
	s_waitcnt lgkmcnt(0)
	s_barrier
	s_setprio 1
	s_waitcnt lgkmcnt(0)
	v_mfma_f32_16x16x32_bf16 v[124:127], v[146:149], v[196:199], v[124:127]
	v_mfma_f32_16x16x32_bf16 v[120:123], v[164:167], v[196:199], v[120:123]
	v_mfma_f32_16x16x32_bf16 v[116:119], v[146:149], v[204:207], v[116:119]
	v_mfma_f32_16x16x32_bf16 v[108:111], v[164:167], v[204:207], v[108:111]
	v_mfma_f32_16x16x32_bf16 v[100:103], v[146:149], v[212:215], v[100:103]
	v_mfma_f32_16x16x32_bf16 v[92:95], v[164:167], v[212:215], v[92:95]
	v_mfma_f32_16x16x32_bf16 v[84:87], v[146:149], v[220:223], v[84:87]
	v_mfma_f32_16x16x32_bf16 v[76:79], v[164:167], v[220:223], v[76:79]
	v_mfma_f32_16x16x32_bf16 v[124:127], v[160:163], v[200:203], v[124:127]
	v_mfma_f32_16x16x32_bf16 v[120:123], v[168:171], v[200:203], v[120:123]
	v_mfma_f32_16x16x32_bf16 v[116:119], v[160:163], v[208:211], v[116:119]
	v_mfma_f32_16x16x32_bf16 v[108:111], v[168:171], v[208:211], v[108:111]
	v_mfma_f32_16x16x32_bf16 v[100:103], v[160:163], v[216:219], v[100:103]
	v_mfma_f32_16x16x32_bf16 v[92:95], v[168:171], v[216:219], v[92:95]
	v_mfma_f32_16x16x32_bf16 v[84:87], v[160:163], v[224:227], v[84:87]
	v_mfma_f32_16x16x32_bf16 v[76:79], v[168:171], v[224:227], v[76:79]
	s_setprio 0
	s_setprio 1
	v_mfma_f32_16x16x32_bf16 v[112:115], v[180:183], v[196:199], v[112:115]
	v_mfma_f32_16x16x32_bf16 v[104:107], v[188:191], v[196:199], v[104:107]
	v_mfma_f32_16x16x32_bf16 v[96:99], v[180:183], v[204:207], v[96:99]
	v_mfma_f32_16x16x32_bf16 v[88:91], v[188:191], v[204:207], v[88:91]
	v_mfma_f32_16x16x32_bf16 v[80:83], v[180:183], v[212:215], v[80:83]
	v_mfma_f32_16x16x32_bf16 v[72:75], v[188:191], v[212:215], v[72:75]
	v_mfma_f32_16x16x32_bf16 v[68:71], v[180:183], v[220:223], v[68:71]
	v_mfma_f32_16x16x32_bf16 v[64:67], v[188:191], v[220:223], v[64:67]
	v_mfma_f32_16x16x32_bf16 v[112:115], v[184:187], v[200:203], v[112:115]
	v_mfma_f32_16x16x32_bf16 v[104:107], v[192:195], v[200:203], v[104:107]
	v_mfma_f32_16x16x32_bf16 v[96:99], v[184:187], v[208:211], v[96:99]
	v_mfma_f32_16x16x32_bf16 v[88:91], v[192:195], v[208:211], v[88:91]
	v_mfma_f32_16x16x32_bf16 v[80:83], v[184:187], v[216:219], v[80:83]
	v_mfma_f32_16x16x32_bf16 v[72:75], v[192:195], v[216:219], v[72:75]
	v_mfma_f32_16x16x32_bf16 v[68:71], v[184:187], v[224:227], v[68:71]
	v_mfma_f32_16x16x32_bf16 v[64:67], v[192:195], v[224:227], v[64:67]
	s_setprio 0
	s_barrier
; #define PG8_STAGE(bufoff, gbase, voff) do { _Pragma("unroll") for (int _i = 0; _i < 2; ++_i) \
;         __builtin_amdgcn_global_load_lds((const unsigned*)((const char*)(gbase) + (voff)[_i]), (PG8_LAS unsigned*)(lds + (bufoff) + ldsw + _i * 8192), 16, 0, 0); } while (0)
; #define PG8_LDA(dst, b, h) do { _Pragma("unroll") for (int m = 0; m < 4; ++m) _Pragma("unroll") for (int k = 0; k < 2; ++k) dst[m][k] = *(const PG8_LAS bf16x8*)(lds + PG8_SA(b, h) + aoff + m * 2048 + k * 1024); } while (0)
; #define PG8_MMA(ai, bj, At, Bt) do { __builtin_amdgcn_s_setprio(1); _Pragma("unroll") for (int m = 0; m < 4; ++m) _Pragma("unroll") for (int n = 0; n < 2; ++n) _Pragma("unroll") for (int k = 0; k < 2; ++k) \
;         acc[ai][bj][m][n] = __builtin_amdgcn_mfma_f32_16x16x32_bf16(Bt[n][k], At[m][k], acc[ai][bj][m][n], 0, 0, 0); __builtin_amdgcn_s_setprio(0); } while (0)
; #define PG8_WAIT_V(n) asm volatile("s_waitcnt vmcnt(" #n ")" ::: "memory")
; #define PG8_WAIT_L(n) asm volatile("s_waitcnt lgkmcnt(" #n ")" ::: "memory")
; #define PG8_BAR __builtin_amdgcn_s_barrier()
; #define PG8_SCHED __builtin_amdgcn_sched_barrier(0)
; template <class Epi, class Sched, bool ALIGN_EPI = false, bool SP2 = false>
; __device__ __forceinline__ void gemm_phase(PG8_LAS unsigned char* lds, const Gemm g, const Sched& S, const Epi& E) {
;     ...
;             PG8_LDA(At, 1, 1); PG8_STAGE(PG8_SB(1, 0), b3, voffB); PG8_STAGE(PG8_SB(1, 1), b3 + hstep, voffB); PG8_STAGE(PG8_SA(1, 0), a3, voffA);
;             PG8_WAIT_V(8); PG8_WAIT_L(0); PG8_BAR; PG8_MMA(1, 0, At, B0); PG8_MMA(1, 1, At, B1); PG8_BAR; PG8_SCHED;
	s_add_i32 s26, s51, s30
	v_lshl_add_u64 v[150:151], v[150:151], 0, s[2:3]
	s_mov_b32 m0, s26
	ds_read_b128 v[196:199], v158 offset:49152
	ds_read_b128 v[200:203], v158 offset:50176
	ds_read_b128 v[204:207], v158 offset:51200
	ds_read_b128 v[208:211], v158 offset:52224
	ds_read_b128 v[212:215], v158 offset:53248
	ds_read_b128 v[216:219], v158 offset:54272
	ds_read_b128 v[220:223], v158 offset:55296
	ds_read_b128 v[224:227], v158 offset:56320
	global_load_lds_dwordx4 v[150:151], off
	s_add_i32 m0, s26, 0x2000
	s_add_u32 s24, s24, 0x80080
	v_lshl_add_u64 v[150:151], v[228:229], 0, s[2:3]
	s_addc_u32 s25, s25, 0
	s_add_i32 s26, s52, s30
	global_load_lds_dwordx4 v[150:151], off
	v_lshl_add_u64 v[150:151], s[24:25], 0, v[134:135]
	s_mov_b32 m0, s26
	s_nop 0
	global_load_lds_dwordx4 v[150:151], off
	v_lshl_add_u64 v[150:151], s[24:25], 0, v[130:131]
	s_add_i32 m0, s26, 0x2000
	s_nop 0
	global_load_lds_dwordx4 v[150:151], off
	v_lshl_add_u64 v[150:151], v[230:231], 0, s[2:3]
	v_lshl_add_u64 v[150:151], v[232:233], 0, s[2:3]
	s_waitcnt vmcnt(6)
	s_waitcnt lgkmcnt(0)
	s_barrier
	s_setprio 1
	s_waitcnt lgkmcnt(0)
	v_mfma_f32_16x16x32_bf16 v[60:63], v[146:149], v[196:199], v[60:63]
	v_mfma_f32_16x16x32_bf16 v[56:59], v[164:167], v[196:199], v[56:59]
	v_mfma_f32_16x16x32_bf16 v[52:55], v[146:149], v[204:207], v[52:55]
	v_mfma_f32_16x16x32_bf16 v[44:47], v[164:167], v[204:207], v[44:47]
	v_mfma_f32_16x16x32_bf16 v[36:39], v[146:149], v[212:215], v[36:39]
	v_mfma_f32_16x16x32_bf16 v[28:31], v[164:167], v[212:215], v[28:31]
	v_mfma_f32_16x16x32_bf16 v[20:23], v[146:149], v[220:223], v[20:23]
	v_mfma_f32_16x16x32_bf16 v[12:15], v[164:167], v[220:223], v[12:15]
	v_mfma_f32_16x16x32_bf16 v[60:63], v[160:163], v[200:203], v[60:63]
	v_mfma_f32_16x16x32_bf16 v[56:59], v[168:171], v[200:203], v[56:59]
	v_mfma_f32_16x16x32_bf16 v[52:55], v[160:163], v[208:211], v[52:55]
	v_mfma_f32_16x16x32_bf16 v[44:47], v[168:171], v[208:211], v[44:47]
	v_mfma_f32_16x16x32_bf16 v[36:39], v[160:163], v[216:219], v[36:39]
	v_mfma_f32_16x16x32_bf16 v[28:31], v[168:171], v[216:219], v[28:31]
	v_mfma_f32_16x16x32_bf16 v[20:23], v[160:163], v[224:227], v[20:23]
	v_mfma_f32_16x16x32_bf16 v[12:15], v[168:171], v[224:227], v[12:15]
	s_setprio 0
	s_setprio 1
	v_mfma_f32_16x16x32_bf16 v[48:51], v[180:183], v[196:199], v[48:51]
	v_mfma_f32_16x16x32_bf16 v[40:43], v[188:191], v[196:199], v[40:43]
	v_mfma_f32_16x16x32_bf16 v[32:35], v[180:183], v[204:207], v[32:35]
	v_mfma_f32_16x16x32_bf16 v[24:27], v[188:191], v[204:207], v[24:27]
	v_mfma_f32_16x16x32_bf16 v[16:19], v[180:183], v[212:215], v[16:19]
	v_mfma_f32_16x16x32_bf16 v[8:11], v[188:191], v[212:215], v[8:11]
	v_mfma_f32_16x16x32_bf16 v[4:7], v[180:183], v[220:223], v[4:7]
	v_mfma_f32_16x16x32_bf16 v[0:3], v[188:191], v[220:223], v[0:3]
	v_mfma_f32_16x16x32_bf16 v[48:51], v[184:187], v[200:203], v[48:51]
	v_mfma_f32_16x16x32_bf16 v[40:43], v[192:195], v[200:203], v[40:43]
	v_mfma_f32_16x16x32_bf16 v[32:35], v[184:187], v[208:211], v[32:35]
	v_mfma_f32_16x16x32_bf16 v[24:27], v[192:195], v[208:211], v[24:27]
	v_mfma_f32_16x16x32_bf16 v[16:19], v[184:187], v[216:219], v[16:19]
	v_mfma_f32_16x16x32_bf16 v[8:11], v[192:195], v[216:219], v[8:11]
	v_mfma_f32_16x16x32_bf16 v[4:7], v[184:187], v[224:227], v[4:7]
	v_mfma_f32_16x16x32_bf16 v[0:3], v[192:195], v[224:227], v[0:3]
	s_setprio 0
	s_barrier
	s_add_i32 s50, s50, 2
	s_add_u32 s22, s22, 0x100
	s_addc_u32 s23, s23, 0
	s_add_u32 s48, s48, 0x100
	s_addc_u32 s49, s49, 0
	s_cmp_gt_u32 s50, 29
	s_cbranch_scc0 .LBB0_289
	s_and_b64 vcc, exec, s[4:5]
	s_cbranch_vccz .LBB0_292
	s_barrier

; #define PG8_STAGE(bufoff, gbase, voff) do { _Pragma("unroll") for (int _i = 0; _i < 2; ++_i) \
;         __builtin_amdgcn_global_load_lds((const unsigned*)((const char*)(gbase) + (voff)[_i]), (PG8_LAS unsigned*)(lds + (bufoff) + ldsw + _i * 8192), 16, 0, 0); } while (0)
; #define PG8_LDA(dst, b, h) do { _Pragma("unroll") for (int m = 0; m < 4; ++m) _Pragma("unroll") for (int k = 0; k < 2; ++k) dst[m][k] = *(const PG8_LAS bf16x8*)(lds + PG8_SA(b, h) + aoff + m * 2048 + k * 1024); } while (0)
; #define PG8_LDB(dst, b, h) do { _Pragma("unroll") for (int n = 0; n < 2; ++n) _Pragma("unroll") for (int k = 0; k < 2; ++k) dst[n][k] = *(const PG8_LAS bf16x8*)(lds + PG8_SB(b, h) + boff + n * 2048 + k * 1024); } while (0)
; #define PG8_MMA(ai, bj, At, Bt) do { __builtin_amdgcn_s_setprio(1); _Pragma("unroll") for (int m = 0; m < 4; ++m) _Pragma("unroll") for (int n = 0; n < 2; ++n) _Pragma("unroll") for (int k = 0; k < 2; ++k) \
;         acc[ai][bj][m][n] = __builtin_amdgcn_mfma_f32_16x16x32_bf16(Bt[n][k], At[m][k], acc[ai][bj][m][n], 0, 0, 0); __builtin_amdgcn_s_setprio(0); } while (0)
; #define PG8_WAIT_V(n) asm volatile("s_waitcnt vmcnt(" #n ")" ::: "memory")
; #define PG8_WAIT_L(n) asm volatile("s_waitcnt lgkmcnt(" #n ")" ::: "memory")
; #define PG8_BAR __builtin_amdgcn_s_barrier()
; #define PG8_SCHED __builtin_amdgcn_sched_barrier(0)
; template <class Epi, class Sched, bool ALIGN_EPI = false, bool SP2 = false>
; __device__ __forceinline__ void gemm_phase(PG8_LAS unsigned char* lds, const Gemm g, const Sched& S, const Epi& E) {
;     ...
;             PG8_LDB(B0, 0, 0); PG8_LDB(B1, 0, 1); PG8_SCHED; PG8_LDA(At, 0, 0); PG8_STAGE(PG8_SA(1, 1), a1 + hstep, voffA);
;             PG8_WAIT_V(8); PG8_WAIT_L(0); PG8_BAR; PG8_MMA(0, 0, At, B0); PG8_MMA(0, 1, At, B1); PG8_BAR; PG8_SCHED;
;             PG8_LDA(At, 0, 1); PG8_STAGE(PG8_SB(0, 0), b2, voffB); PG8_STAGE(PG8_SB(0, 1), b2 + hstep, voffB); PG8_STAGE(PG8_SA(0, 0), a2, voffA);
.LBB0_585:
	ds_read_b128 v[142:145], v149
	ds_read_b128 v[152:155], v149 offset:1024
	ds_read_b128 v[156:159], v149 offset:2048
	ds_read_b128 v[160:163], v149 offset:3072
	ds_read_b128 v[164:167], v150
	ds_read_b128 v[168:171], v150 offset:1024
	ds_read_b128 v[180:183], v150 offset:2048
	ds_read_b128 v[184:187], v150 offset:3072
	s_add_u32 s26, s24, 0xfff80080
	s_addc_u32 s27, s25, -1
	s_cmp_eq_u32 s51, 28
	s_cselect_b32 s29, s17, s27
	s_cselect_b32 s28, s23, s26
	s_cselect_b32 s27, s13, s50
	s_cselect_b32 s26, s48, s49
	s_mov_b32 s38, 0xfff80000
	s_mov_b32 s39, -1
	v_lshl_add_u64 v[220:221], s[24:25], 0, v[134:135]
	v_lshl_add_u64 v[220:221], v[220:221], 0, s[38:39]
	s_mov_b32 m0, s41
	s_nop 0
	global_load_lds_dwordx4 v[220:221], off
	v_lshl_add_u64 v[220:221], s[24:25], 0, v[136:137]
	v_lshl_add_u64 v[220:221], v[220:221], 0, s[38:39]
	s_mov_b32 m0, s44
	s_nop 0
	global_load_lds_dwordx4 v[220:221], off
	v_lshl_add_u64 v[220:221], s[24:25], 0, v[134:135]
	s_add_i32 m0, s34, 0xc000
	ds_read_b128 v[188:191], v151
	ds_read_b128 v[192:195], v151 offset:1024
	ds_read_b128 v[196:199], v151 offset:2048
	ds_read_b128 v[200:203], v151 offset:3072
	ds_read_b128 v[204:207], v151 offset:4096
	ds_read_b128 v[208:211], v151 offset:5120
	ds_read_b128 v[212:215], v151 offset:6144
	ds_read_b128 v[216:219], v151 offset:7168
	global_load_lds_dwordx4 v[220:221], off
	v_lshl_add_u64 v[220:221], s[24:25], 0, v[136:137]
	s_add_i32 m0, s34, 0xe000
	s_nop 0
	global_load_lds_dwordx4 v[220:221], off
	s_waitcnt vmcnt(8)
	s_waitcnt lgkmcnt(0)
	s_barrier
	s_setprio 1
	s_waitcnt lgkmcnt(0)
	v_mfma_f32_16x16x32_bf16 v[124:127], v[142:145], v[188:191], v[124:127]
	v_mfma_f32_16x16x32_bf16 v[120:123], v[156:159], v[188:191], v[120:123]
	v_mfma_f32_16x16x32_bf16 v[108:111], v[142:145], v[196:199], v[108:111]
	v_mfma_f32_16x16x32_bf16 v[104:107], v[156:159], v[196:199], v[104:107]
	v_mfma_f32_16x16x32_bf16 v[92:95], v[142:145], v[204:207], v[92:95]
	v_mfma_f32_16x16x32_bf16 v[88:91], v[156:159], v[204:207], v[88:91]
	v_mfma_f32_16x16x32_bf16 v[76:79], v[142:145], v[212:215], v[76:79]
	v_mfma_f32_16x16x32_bf16 v[72:75], v[156:159], v[212:215], v[72:75]
	v_mfma_f32_16x16x32_bf16 v[124:127], v[152:155], v[192:195], v[124:127]
	v_mfma_f32_16x16x32_bf16 v[120:123], v[160:163], v[192:195], v[120:123]
	v_mfma_f32_16x16x32_bf16 v[108:111], v[152:155], v[200:203], v[108:111]
	v_mfma_f32_16x16x32_bf16 v[104:107], v[160:163], v[200:203], v[104:107]
	v_mfma_f32_16x16x32_bf16 v[92:95], v[152:155], v[208:211], v[92:95]
	v_mfma_f32_16x16x32_bf16 v[88:91], v[160:163], v[208:211], v[88:91]
	v_mfma_f32_16x16x32_bf16 v[76:79], v[152:155], v[216:219], v[76:79]
	v_mfma_f32_16x16x32_bf16 v[72:75], v[160:163], v[216:219], v[72:75]
	s_setprio 0
	s_setprio 1
	v_mfma_f32_16x16x32_bf16 v[116:119], v[164:167], v[188:191], v[116:119]
	v_mfma_f32_16x16x32_bf16 v[112:115], v[180:183], v[188:191], v[112:115]
	v_mfma_f32_16x16x32_bf16 v[100:103], v[164:167], v[196:199], v[100:103]
	v_mfma_f32_16x16x32_bf16 v[96:99], v[180:183], v[196:199], v[96:99]
	v_mfma_f32_16x16x32_bf16 v[84:87], v[164:167], v[204:207], v[84:87]
	v_mfma_f32_16x16x32_bf16 v[80:83], v[180:183], v[204:207], v[80:83]
	v_mfma_f32_16x16x32_bf16 v[68:71], v[164:167], v[212:215], v[68:71]
	v_mfma_f32_16x16x32_bf16 v[64:67], v[180:183], v[212:215], v[64:67]
	v_mfma_f32_16x16x32_bf16 v[116:119], v[168:171], v[192:195], v[116:119]
	v_mfma_f32_16x16x32_bf16 v[112:115], v[184:187], v[192:195], v[112:115]
	v_mfma_f32_16x16x32_bf16 v[100:103], v[168:171], v[200:203], v[100:103]
	v_mfma_f32_16x16x32_bf16 v[96:99], v[184:187], v[200:203], v[96:99]
	v_mfma_f32_16x16x32_bf16 v[84:87], v[168:171], v[208:211], v[84:87]
	v_mfma_f32_16x16x32_bf16 v[80:83], v[184:187], v[208:211], v[80:83]
	v_mfma_f32_16x16x32_bf16 v[68:71], v[168:171], v[216:219], v[68:71]
	v_mfma_f32_16x16x32_bf16 v[64:67], v[184:187], v[216:219], v[64:67]
	s_setprio 0
	s_barrier
	s_add_i32 s52, s45, s33
	v_lshl_add_u64 v[220:221], s[26:27], 0, v[130:131]
	s_mov_b32 m0, s52
	ds_read_b128 v[188:191], v151 offset:16384
	ds_read_b128 v[192:195], v151 offset:17408
	ds_read_b128 v[196:199], v151 offset:18432
	ds_read_b128 v[200:203], v151 offset:19456
	ds_read_b128 v[204:207], v151 offset:20480
	ds_read_b128 v[208:211], v151 offset:21504
	ds_read_b128 v[212:215], v151 offset:22528
	ds_read_b128 v[216:219], v151 offset:23552
	global_load_lds_dwordx4 v[220:221], off
	s_add_i32 m0, s52, 0x2000
	s_add_u32 s52, s26, 0x80000
	v_lshl_add_u64 v[222:223], s[26:27], 0, v[132:133]
	s_addc_u32 s53, s27, 0
	s_add_i32 s54, s46, s33
	global_load_lds_dwordx4 v[222:223], off
	v_lshl_add_u64 v[224:225], s[52:53], 0, v[130:131]
	s_mov_b32 m0, s54
	v_lshl_add_u64 v[226:227], s[28:29], 0, v[132:133]
	global_load_lds_dwordx4 v[224:225], off
	v_lshl_add_u64 v[224:225], s[52:53], 0, v[132:133]
	s_add_i32 m0, s54, 0x2000
	s_nop 0
	global_load_lds_dwordx4 v[224:225], off
	v_lshl_add_u64 v[224:225], s[28:29], 0, v[130:131]
	s_waitcnt vmcnt(6)
	s_waitcnt lgkmcnt(0)
	s_barrier
; #define PG8_STAGE(bufoff, gbase, voff) do { _Pragma("unroll") for (int _i = 0; _i < 2; ++_i) \
;         __builtin_amdgcn_global_load_lds((const unsigned*)((const char*)(gbase) + (voff)[_i]), (PG8_LAS unsigned*)(lds + (bufoff) + ldsw + _i * 8192), 16, 0, 0); } while (0)
; #define PG8_LDA(dst, b, h) do { _Pragma("unroll") for (int m = 0; m < 4; ++m) _Pragma("unroll") for (int k = 0; k < 2; ++k) dst[m][k] = *(const PG8_LAS bf16x8*)(lds + PG8_SA(b, h) + aoff + m * 2048 + k * 1024); } while (0)
; #define PG8_LDB(dst, b, h) do { _Pragma("unroll") for (int n = 0; n < 2; ++n) _Pragma("unroll") for (int k = 0; k < 2; ++k) dst[n][k] = *(const PG8_LAS bf16x8*)(lds + PG8_SB(b, h) + boff + n * 2048 + k * 1024); } while (0)
; #define PG8_MMA(ai, bj, At, Bt) do { __builtin_amdgcn_s_setprio(1); _Pragma("unroll") for (int m = 0; m < 4; ++m) _Pragma("unroll") for (int n = 0; n < 2; ++n) _Pragma("unroll") for (int k = 0; k < 2; ++k) \
;         acc[ai][bj][m][n] = __builtin_amdgcn_mfma_f32_16x16x32_bf16(Bt[n][k], At[m][k], acc[ai][bj][m][n], 0, 0, 0); __builtin_amdgcn_s_setprio(0); } while (0)
; #define PG8_WAIT_V(n) asm volatile("s_waitcnt vmcnt(" #n ")" ::: "memory")
; #define PG8_WAIT_L(n) asm volatile("s_waitcnt lgkmcnt(" #n ")" ::: "memory")
; #define PG8_BAR __builtin_amdgcn_s_barrier()
; #define PG8_SCHED __builtin_amdgcn_sched_barrier(0)
; template <class Epi, class Sched, bool ALIGN_EPI = false, bool SP2 = false>
; __device__ __forceinline__ void gemm_phase(PG8_LAS unsigned char* lds, const Gemm g, const Sched& S, const Epi& E) {
;     ...
;             PG8_WAIT_V(8); PG8_WAIT_L(0); PG8_BAR; PG8_MMA(1, 0, At, B0); PG8_MMA(1, 1, At, B1); PG8_BAR; PG8_SCHED;
;             PG8_LDB(B0, 1, 0); PG8_LDB(B1, 1, 1); PG8_SCHED; PG8_LDA(At, 1, 0); PG8_STAGE(PG8_SA(0, 1), a2 + hstep, voffA);
;             PG8_WAIT_V(8); PG8_WAIT_L(0); PG8_BAR; PG8_MMA(0, 0, At, B0); PG8_MMA(0, 1, At, B1); PG8_BAR; PG8_SCHED;
	s_setprio 1
	s_waitcnt lgkmcnt(0)
	v_mfma_f32_16x16x32_bf16 v[60:63], v[142:145], v[188:191], v[60:63]
	v_mfma_f32_16x16x32_bf16 v[56:59], v[156:159], v[188:191], v[56:59]
	v_mfma_f32_16x16x32_bf16 v[44:47], v[142:145], v[196:199], v[44:47]
	v_mfma_f32_16x16x32_bf16 v[40:43], v[156:159], v[196:199], v[40:43]
	v_mfma_f32_16x16x32_bf16 v[28:31], v[142:145], v[204:207], v[28:31]
	v_mfma_f32_16x16x32_bf16 v[24:27], v[156:159], v[204:207], v[24:27]
	v_mfma_f32_16x16x32_bf16 v[12:15], v[142:145], v[212:215], v[12:15]
	v_mfma_f32_16x16x32_bf16 v[8:11], v[156:159], v[212:215], v[8:11]
	v_mfma_f32_16x16x32_bf16 v[60:63], v[152:155], v[192:195], v[60:63]
	v_mfma_f32_16x16x32_bf16 v[56:59], v[160:163], v[192:195], v[56:59]
	v_mfma_f32_16x16x32_bf16 v[44:47], v[152:155], v[200:203], v[44:47]
	v_mfma_f32_16x16x32_bf16 v[40:43], v[160:163], v[200:203], v[40:43]
	v_mfma_f32_16x16x32_bf16 v[28:31], v[152:155], v[208:211], v[28:31]
	v_mfma_f32_16x16x32_bf16 v[24:27], v[160:163], v[208:211], v[24:27]
	v_mfma_f32_16x16x32_bf16 v[12:15], v[152:155], v[216:219], v[12:15]
	v_mfma_f32_16x16x32_bf16 v[8:11], v[160:163], v[216:219], v[8:11]
	s_setprio 0
	s_setprio 1
	v_mfma_f32_16x16x32_bf16 v[52:55], v[164:167], v[188:191], v[52:55]
	v_mfma_f32_16x16x32_bf16 v[48:51], v[180:183], v[188:191], v[48:51]
	v_mfma_f32_16x16x32_bf16 v[36:39], v[164:167], v[196:199], v[36:39]
	v_mfma_f32_16x16x32_bf16 v[32:35], v[180:183], v[196:199], v[32:35]
	v_mfma_f32_16x16x32_bf16 v[20:23], v[164:167], v[204:207], v[20:23]
	v_mfma_f32_16x16x32_bf16 v[16:19], v[180:183], v[204:207], v[16:19]
	v_mfma_f32_16x16x32_bf16 v[4:7], v[164:167], v[212:215], v[4:7]
	v_mfma_f32_16x16x32_bf16 v[0:3], v[180:183], v[212:215], v[0:3]
	v_mfma_f32_16x16x32_bf16 v[52:55], v[168:171], v[192:195], v[52:55]
	v_mfma_f32_16x16x32_bf16 v[48:51], v[184:187], v[192:195], v[48:51]
	v_mfma_f32_16x16x32_bf16 v[36:39], v[168:171], v[200:203], v[36:39]
	v_mfma_f32_16x16x32_bf16 v[32:35], v[184:187], v[200:203], v[32:35]
	v_mfma_f32_16x16x32_bf16 v[20:23], v[168:171], v[208:211], v[20:23]
	v_mfma_f32_16x16x32_bf16 v[16:19], v[184:187], v[208:211], v[16:19]
	v_mfma_f32_16x16x32_bf16 v[4:7], v[168:171], v[216:219], v[4:7]
	v_mfma_f32_16x16x32_bf16 v[0:3], v[184:187], v[216:219], v[0:3]
	s_setprio 0
	s_barrier
	s_add_i32 s52, 0, 0x18000
	s_add_i32 s53, 0, 0x1c000
	v_add_u32_e32 v160, s52, v147
	v_add_u32_e32 v179, s53, v147
	ds_read_b128 v[142:145], v160
	ds_read_b128 v[152:155], v160 offset:1024
	ds_read_b128 v[156:159], v160 offset:2048
	ds_read_b128 v[160:163], v160 offset:3072
	ds_read_b128 v[164:167], v179
	ds_read_b128 v[168:171], v179 offset:1024
	ds_read_b128 v[180:183], v179 offset:2048
	ds_read_b128 v[184:187], v179 offset:3072
	s_add_u32 s28, s28, 0x80000
	s_addc_u32 s29, s29, 0
	s_mov_b32 m0, s34
	s_nop 0
	global_load_lds_dwordx4 v[224:225], off
	s_mov_b32 m0, s35
	s_nop 0
	global_load_lds_dwordx4 v[226:227], off
	s_mov_b32 m0, s36
	v_lshl_add_u64 v[228:229], s[28:29], 0, v[130:131]
	ds_read_b128 v[188:191], v151 offset:32768
	ds_read_b128 v[192:195], v151 offset:33792
	ds_read_b128 v[196:199], v151 offset:34816
	ds_read_b128 v[200:203], v151 offset:35840
	ds_read_b128 v[204:207], v151 offset:36864
	ds_read_b128 v[208:211], v151 offset:37888
	ds_read_b128 v[212:215], v151 offset:38912
	ds_read_b128 v[216:219], v151 offset:39936
	global_load_lds_dwordx4 v[228:229], off
	v_lshl_add_u64 v[228:229], s[28:29], 0, v[132:133]
	s_mov_b32 m0, s37
	s_nop 0
	global_load_lds_dwordx4 v[228:229], off
	s_waitcnt vmcnt(8)
	s_waitcnt lgkmcnt(0)
	s_barrier
	s_setprio 1
	s_waitcnt lgkmcnt(0)
	v_mfma_f32_16x16x32_bf16 v[124:127], v[142:145], v[188:191], v[124:127]
	v_mfma_f32_16x16x32_bf16 v[120:123], v[156:159], v[188:191], v[120:123]
	v_mfma_f32_16x16x32_bf16 v[108:111], v[142:145], v[196:199], v[108:111]
	v_mfma_f32_16x16x32_bf16 v[104:107], v[156:159], v[196:199], v[104:107]
	v_mfma_f32_16x16x32_bf16 v[92:95], v[142:145], v[204:207], v[92:95]
	v_mfma_f32_16x16x32_bf16 v[88:91], v[156:159], v[204:207], v[88:91]
	v_mfma_f32_16x16x32_bf16 v[76:79], v[142:145], v[212:215], v[76:79]
	v_mfma_f32_16x16x32_bf16 v[72:75], v[156:159], v[212:215], v[72:75]
	v_mfma_f32_16x16x32_bf16 v[124:127], v[152:155], v[192:195], v[124:127]
	v_mfma_f32_16x16x32_bf16 v[120:123], v[160:163], v[192:195], v[120:123]
	v_mfma_f32_16x16x32_bf16 v[108:111], v[152:155], v[200:203], v[108:111]
	v_mfma_f32_16x16x32_bf16 v[104:107], v[160:163], v[200:203], v[104:107]
	v_mfma_f32_16x16x32_bf16 v[92:95], v[152:155], v[208:211], v[92:95]
	v_mfma_f32_16x16x32_bf16 v[88:91], v[160:163], v[208:211], v[88:91]
	v_mfma_f32_16x16x32_bf16 v[76:79], v[152:155], v[216:219], v[76:79]
	v_mfma_f32_16x16x32_bf16 v[72:75], v[160:163], v[216:219], v[72:75]
	s_setprio 0
	s_setprio 1
	v_mfma_f32_16x16x32_bf16 v[116:119], v[164:167], v[188:191], v[116:119]
	v_mfma_f32_16x16x32_bf16 v[112:115], v[180:183], v[188:191], v[112:115]
	v_mfma_f32_16x16x32_bf16 v[100:103], v[164:167], v[196:199], v[100:103]
	v_mfma_f32_16x16x32_bf16 v[96:99], v[180:183], v[196:199], v[96:99]
	v_mfma_f32_16x16x32_bf16 v[84:87], v[164:167], v[204:207], v[84:87]
	v_mfma_f32_16x16x32_bf16 v[80:83], v[180:183], v[204:207], v[80:83]
	v_mfma_f32_16x16x32_bf16 v[68:71], v[164:167], v[212:215], v[68:71]
	v_mfma_f32_16x16x32_bf16 v[64:67], v[180:183], v[212:215], v[64:67]
	v_mfma_f32_16x16x32_bf16 v[116:119], v[168:171], v[192:195], v[116:119]
	v_mfma_f32_16x16x32_bf16 v[112:115], v[184:187], v[192:195], v[112:115]
	v_mfma_f32_16x16x32_bf16 v[100:103], v[168:171], v[200:203], v[100:103]
	v_mfma_f32_16x16x32_bf16 v[96:99], v[184:187], v[200:203], v[96:99]
	v_mfma_f32_16x16x32_bf16 v[84:87], v[168:171], v[208:211], v[84:87]
	v_mfma_f32_16x16x32_bf16 v[80:83], v[184:187], v[208:211], v[80:83]
	v_mfma_f32_16x16x32_bf16 v[68:71], v[168:171], v[216:219], v[68:71]
	v_mfma_f32_16x16x32_bf16 v[64:67], v[184:187], v[216:219], v[64:67]
	s_setprio 0
	s_barrier
; #define PG8_STAGE(bufoff, gbase, voff) do { _Pragma("unroll") for (int _i = 0; _i < 2; ++_i) \
;         __builtin_amdgcn_global_load_lds((const unsigned*)((const char*)(gbase) + (voff)[_i]), (PG8_LAS unsigned*)(lds + (bufoff) + ldsw + _i * 8192), 16, 0, 0); } while (0)
; #define PG8_LDA(dst, b, h) do { _Pragma("unroll") for (int m = 0; m < 4; ++m) _Pragma("unroll") for (int k = 0; k < 2; ++k) dst[m][k] = *(const PG8_LAS bf16x8*)(lds + PG8_SA(b, h) + aoff + m * 2048 + k * 1024); } while (0)
; #define PG8_MMA(ai, bj, At, Bt) do { __builtin_amdgcn_s_setprio(1); _Pragma("unroll") for (int m = 0; m < 4; ++m) _Pragma("unroll") for (int n = 0; n < 2; ++n) _Pragma("unroll") for (int k = 0; k < 2; ++k) \
;         acc[ai][bj][m][n] = __builtin_amdgcn_mfma_f32_16x16x32_bf16(Bt[n][k], At[m][k], acc[ai][bj][m][n], 0, 0, 0); __builtin_amdgcn_s_setprio(0); } while (0)
; #define PG8_WAIT_V(n) asm volatile("s_waitcnt vmcnt(" #n ")" ::: "memory")
; #define PG8_WAIT_L(n) asm volatile("s_waitcnt lgkmcnt(" #n ")" ::: "memory")
; #define PG8_BAR __builtin_amdgcn_s_barrier()
; #define PG8_SCHED __builtin_amdgcn_sched_barrier(0)
; template <class Epi, class Sched, bool ALIGN_EPI = false, bool SP2 = false>
; __device__ __forceinline__ void gemm_phase(PG8_LAS unsigned char* lds, const Gemm g, const Sched& S, const Epi& E) {
;     ...
;             PG8_LDA(At, 1, 1); PG8_STAGE(PG8_SB(1, 0), b3, voffB); PG8_STAGE(PG8_SB(1, 1), b3 + hstep, voffB); PG8_STAGE(PG8_SA(1, 0), a3, voffA);
;             PG8_WAIT_V(8); PG8_WAIT_L(0); PG8_BAR; PG8_MMA(1, 0, At, B0); PG8_MMA(1, 1, At, B1); PG8_BAR; PG8_SCHED;
	s_add_i32 s28, s52, s33
	v_lshl_add_u64 v[220:221], v[220:221], 0, s[4:5]
	s_mov_b32 m0, s28
	ds_read_b128 v[188:191], v151 offset:49152
	ds_read_b128 v[192:195], v151 offset:50176
	ds_read_b128 v[196:199], v151 offset:51200
	ds_read_b128 v[200:203], v151 offset:52224
	ds_read_b128 v[204:207], v151 offset:53248
	ds_read_b128 v[208:211], v151 offset:54272
	ds_read_b128 v[212:215], v151 offset:55296
	ds_read_b128 v[216:219], v151 offset:56320
	global_load_lds_dwordx4 v[220:221], off
	s_add_i32 m0, s28, 0x2000
	s_add_u32 s26, s26, 0x80080
	v_lshl_add_u64 v[220:221], v[222:223], 0, s[4:5]
	s_addc_u32 s27, s27, 0
	s_add_i32 s28, s53, s33
	global_load_lds_dwordx4 v[220:221], off
	v_lshl_add_u64 v[220:221], s[26:27], 0, v[130:131]
	s_mov_b32 m0, s28
	s_nop 0
	global_load_lds_dwordx4 v[220:221], off
	v_lshl_add_u64 v[220:221], s[26:27], 0, v[132:133]
	s_add_i32 m0, s28, 0x2000
	s_nop 0
	global_load_lds_dwordx4 v[220:221], off
	v_lshl_add_u64 v[220:221], v[224:225], 0, s[4:5]
	v_lshl_add_u64 v[220:221], v[226:227], 0, s[4:5]
	s_waitcnt vmcnt(6)
	s_waitcnt lgkmcnt(0)
	s_barrier
	s_setprio 1
	s_waitcnt lgkmcnt(0)
	v_mfma_f32_16x16x32_bf16 v[60:63], v[142:145], v[188:191], v[60:63]
	v_mfma_f32_16x16x32_bf16 v[56:59], v[156:159], v[188:191], v[56:59]
	v_mfma_f32_16x16x32_bf16 v[44:47], v[142:145], v[196:199], v[44:47]
	v_mfma_f32_16x16x32_bf16 v[40:43], v[156:159], v[196:199], v[40:43]
	v_mfma_f32_16x16x32_bf16 v[28:31], v[142:145], v[204:207], v[28:31]
	v_mfma_f32_16x16x32_bf16 v[24:27], v[156:159], v[204:207], v[24:27]
	v_mfma_f32_16x16x32_bf16 v[12:15], v[142:145], v[212:215], v[12:15]
	v_mfma_f32_16x16x32_bf16 v[8:11], v[156:159], v[212:215], v[8:11]
	v_mfma_f32_16x16x32_bf16 v[60:63], v[152:155], v[192:195], v[60:63]
	v_mfma_f32_16x16x32_bf16 v[56:59], v[160:163], v[192:195], v[56:59]
	v_mfma_f32_16x16x32_bf16 v[44:47], v[152:155], v[200:203], v[44:47]
	v_mfma_f32_16x16x32_bf16 v[40:43], v[160:163], v[200:203], v[40:43]
	v_mfma_f32_16x16x32_bf16 v[28:31], v[152:155], v[208:211], v[28:31]
	v_mfma_f32_16x16x32_bf16 v[24:27], v[160:163], v[208:211], v[24:27]
	v_mfma_f32_16x16x32_bf16 v[12:15], v[152:155], v[216:219], v[12:15]
	v_mfma_f32_16x16x32_bf16 v[8:11], v[160:163], v[216:219], v[8:11]
	s_setprio 0
	s_setprio 1
	v_mfma_f32_16x16x32_bf16 v[52:55], v[164:167], v[188:191], v[52:55]
	v_mfma_f32_16x16x32_bf16 v[48:51], v[180:183], v[188:191], v[48:51]
	v_mfma_f32_16x16x32_bf16 v[36:39], v[164:167], v[196:199], v[36:39]
	v_mfma_f32_16x16x32_bf16 v[32:35], v[180:183], v[196:199], v[32:35]
	v_mfma_f32_16x16x32_bf16 v[20:23], v[164:167], v[204:207], v[20:23]
	v_mfma_f32_16x16x32_bf16 v[16:19], v[180:183], v[204:207], v[16:19]
	v_mfma_f32_16x16x32_bf16 v[4:7], v[164:167], v[212:215], v[4:7]
	v_mfma_f32_16x16x32_bf16 v[0:3], v[180:183], v[212:215], v[0:3]
	v_mfma_f32_16x16x32_bf16 v[52:55], v[168:171], v[192:195], v[52:55]
	v_mfma_f32_16x16x32_bf16 v[48:51], v[184:187], v[192:195], v[48:51]
	v_mfma_f32_16x16x32_bf16 v[36:39], v[168:171], v[200:203], v[36:39]
	v_mfma_f32_16x16x32_bf16 v[32:35], v[184:187], v[200:203], v[32:35]
	v_mfma_f32_16x16x32_bf16 v[20:23], v[168:171], v[208:211], v[20:23]
	v_mfma_f32_16x16x32_bf16 v[16:19], v[184:187], v[208:211], v[16:19]
	v_mfma_f32_16x16x32_bf16 v[4:7], v[168:171], v[216:219], v[4:7]
	v_mfma_f32_16x16x32_bf16 v[0:3], v[184:187], v[216:219], v[0:3]
	s_setprio 0
	s_barrier
	s_add_i32 s51, s51, 2
	s_add_u32 s24, s24, 0x100
	s_addc_u32 s25, s25, 0
	s_add_u32 s49, s49, 0x100
	s_addc_u32 s50, s50, 0
	s_cmp_gt_u32 s51, 29
	s_cbranch_scc0 .LBB0_585
	s_and_b64 vcc, exec, s[6:7]
	s_cbranch_vccz .LBB0_588
	s_barrier

; #define PG8_STAGE(bufoff, gbase, voff) do { _Pragma("unroll") for (int _i = 0; _i < 2; ++_i) \
;         __builtin_amdgcn_global_load_lds((const unsigned*)((const char*)(gbase) + (voff)[_i]), (PG8_LAS unsigned*)(lds + (bufoff) + ldsw + _i * 8192), 16, 0, 0); } while (0)
; #define PG8_LDA(dst, b, h) do { _Pragma("unroll") for (int m = 0; m < 4; ++m) _Pragma("unroll") for (int k = 0; k < 2; ++k) dst[m][k] = *(const PG8_LAS bf16x8*)(lds + PG8_SA(b, h) + aoff + m * 2048 + k * 1024); } while (0)
; #define PG8_LDB(dst, b, h) do { _Pragma("unroll") for (int n = 0; n < 2; ++n) _Pragma("unroll") for (int k = 0; k < 2; ++k) dst[n][k] = *(const PG8_LAS bf16x8*)(lds + PG8_SB(b, h) + boff + n * 2048 + k * 1024); } while (0)
; #define PG8_MMA(ai, bj, At, Bt) do { __builtin_amdgcn_s_setprio(1); _Pragma("unroll") for (int m = 0; m < 4; ++m) _Pragma("unroll") for (int n = 0; n < 2; ++n) _Pragma("unroll") for (int k = 0; k < 2; ++k) \
;         acc[ai][bj][m][n] = __builtin_amdgcn_mfma_f32_16x16x32_bf16(Bt[n][k], At[m][k], acc[ai][bj][m][n], 0, 0, 0); __builtin_amdgcn_s_setprio(0); } while (0)
; #define PG8_WAIT_V(n) asm volatile("s_waitcnt vmcnt(" #n ")" ::: "memory")
; #define PG8_WAIT_L(n) asm volatile("s_waitcnt lgkmcnt(" #n ")" ::: "memory")
; #define PG8_BAR __builtin_amdgcn_s_barrier()
; #define PG8_SCHED __builtin_amdgcn_sched_barrier(0)
; template <class Epi, class Sched, bool ALIGN_EPI = false, bool SP2 = false>
; __device__ __forceinline__ void gemm_phase(PG8_LAS unsigned char* lds, const Gemm g, const Sched& S, const Epi& E) {
;     ...
;             PG8_LDB(B0, 0, 0); PG8_LDB(B1, 0, 1); PG8_SCHED; PG8_LDA(At, 0, 0); PG8_STAGE(PG8_SA(1, 1), a1 + hstep, voffA);
;             PG8_WAIT_V(8); PG8_WAIT_L(0); PG8_BAR; PG8_MMA(0, 0, At, B0); PG8_MMA(0, 1, At, B1); PG8_BAR; PG8_SCHED;
;             PG8_LDA(At, 0, 1); PG8_STAGE(PG8_SB(0, 0), b2, voffB); PG8_STAGE(PG8_SB(0, 1), b2 + hstep, voffB); PG8_STAGE(PG8_SA(0, 0), a2, voffA);
.LBB0_837:
	ds_read_b128 v[146:149], v158
	ds_read_b128 v[150:153], v158 offset:1024
	ds_read_b128 v[162:165], v158 offset:2048
	ds_read_b128 v[166:169], v158 offset:3072
	ds_read_b128 v[180:183], v159
	ds_read_b128 v[184:187], v159 offset:1024
	ds_read_b128 v[188:191], v159 offset:2048
	ds_read_b128 v[192:195], v159 offset:3072
	s_add_u32 s22, s20, 0xfff80080
	s_addc_u32 s23, s21, -1
	s_cmp_eq_u32 s50, 28
	s_cselect_b32 s25, s11, s23
	s_cselect_b32 s24, s46, s22
	s_cselect_b32 s23, s7, s49
	s_cselect_b32 s22, s47, s48
	s_mov_b32 s38, 0xfff80000
	s_mov_b32 s39, -1
	v_lshl_add_u64 v[170:171], s[20:21], 0, v[138:139]
	v_lshl_add_u64 v[170:171], v[170:171], 0, s[38:39]
	s_mov_b32 m0, s35
	s_nop 0
	global_load_lds_dwordx4 v[170:171], off
	v_lshl_add_u64 v[170:171], s[20:21], 0, v[140:141]
	v_lshl_add_u64 v[170:171], v[170:171], 0, s[38:39]
	s_mov_b32 m0, s36
	s_nop 0
	global_load_lds_dwordx4 v[170:171], off
	v_lshl_add_u64 v[170:171], s[20:21], 0, v[138:139]
	s_add_i32 m0, s30, 0xc000
	ds_read_b128 v[196:199], v160
	ds_read_b128 v[200:203], v160 offset:1024
	ds_read_b128 v[204:207], v160 offset:2048
	ds_read_b128 v[208:211], v160 offset:3072
	ds_read_b128 v[212:215], v160 offset:4096
	ds_read_b128 v[216:219], v160 offset:5120
	ds_read_b128 v[220:223], v160 offset:6144
	ds_read_b128 v[224:227], v160 offset:7168
	global_load_lds_dwordx4 v[170:171], off
	v_lshl_add_u64 v[170:171], s[20:21], 0, v[140:141]
	s_add_i32 m0, s30, 0xe000
	s_nop 0
	global_load_lds_dwordx4 v[170:171], off
	s_waitcnt vmcnt(8)
	s_waitcnt lgkmcnt(0)
	s_barrier
	s_setprio 1
	s_waitcnt lgkmcnt(0)
	v_mfma_f32_16x16x32_bf16 v[124:127], v[146:149], v[196:199], v[124:127]
	v_mfma_f32_16x16x32_bf16 v[116:119], v[162:165], v[196:199], v[116:119]
	v_mfma_f32_16x16x32_bf16 v[108:111], v[146:149], v[204:207], v[108:111]
	v_mfma_f32_16x16x32_bf16 v[100:103], v[162:165], v[204:207], v[100:103]
	v_mfma_f32_16x16x32_bf16 v[92:95], v[146:149], v[212:215], v[92:95]
	v_mfma_f32_16x16x32_bf16 v[84:87], v[162:165], v[212:215], v[84:87]
	v_mfma_f32_16x16x32_bf16 v[76:79], v[146:149], v[220:223], v[76:79]
	v_mfma_f32_16x16x32_bf16 v[68:71], v[162:165], v[220:223], v[68:71]
	v_mfma_f32_16x16x32_bf16 v[124:127], v[150:153], v[200:203], v[124:127]
	v_mfma_f32_16x16x32_bf16 v[116:119], v[166:169], v[200:203], v[116:119]
	v_mfma_f32_16x16x32_bf16 v[108:111], v[150:153], v[208:211], v[108:111]
	v_mfma_f32_16x16x32_bf16 v[100:103], v[166:169], v[208:211], v[100:103]
	v_mfma_f32_16x16x32_bf16 v[92:95], v[150:153], v[216:219], v[92:95]
	v_mfma_f32_16x16x32_bf16 v[84:87], v[166:169], v[216:219], v[84:87]
	v_mfma_f32_16x16x32_bf16 v[76:79], v[150:153], v[224:227], v[76:79]
	v_mfma_f32_16x16x32_bf16 v[68:71], v[166:169], v[224:227], v[68:71]
	s_setprio 0
	s_setprio 1
	v_mfma_f32_16x16x32_bf16 v[120:123], v[180:183], v[196:199], v[120:123]
	v_mfma_f32_16x16x32_bf16 v[112:115], v[188:191], v[196:199], v[112:115]
	v_mfma_f32_16x16x32_bf16 v[104:107], v[180:183], v[204:207], v[104:107]
	v_mfma_f32_16x16x32_bf16 v[96:99], v[188:191], v[204:207], v[96:99]
	v_mfma_f32_16x16x32_bf16 v[88:91], v[180:183], v[212:215], v[88:91]
	v_mfma_f32_16x16x32_bf16 v[80:83], v[188:191], v[212:215], v[80:83]
	v_mfma_f32_16x16x32_bf16 v[72:75], v[180:183], v[220:223], v[72:75]
	v_mfma_f32_16x16x32_bf16 v[64:67], v[188:191], v[220:223], v[64:67]
	v_mfma_f32_16x16x32_bf16 v[120:123], v[184:187], v[200:203], v[120:123]
	v_mfma_f32_16x16x32_bf16 v[112:115], v[192:195], v[200:203], v[112:115]
	v_mfma_f32_16x16x32_bf16 v[104:107], v[184:187], v[208:211], v[104:107]
	v_mfma_f32_16x16x32_bf16 v[96:99], v[192:195], v[208:211], v[96:99]
	v_mfma_f32_16x16x32_bf16 v[88:91], v[184:187], v[216:219], v[88:91]
	v_mfma_f32_16x16x32_bf16 v[80:83], v[192:195], v[216:219], v[80:83]
	v_mfma_f32_16x16x32_bf16 v[72:75], v[184:187], v[224:227], v[72:75]
	v_mfma_f32_16x16x32_bf16 v[64:67], v[192:195], v[224:227], v[64:67]
	s_setprio 0
	s_barrier
	s_add_i32 s51, s37, s26
	v_lshl_add_u64 v[170:171], s[22:23], 0, v[134:135]
	s_mov_b32 m0, s51
	ds_read_b128 v[196:199], v160 offset:16384
	ds_read_b128 v[200:203], v160 offset:17408
	ds_read_b128 v[204:207], v160 offset:18432
	ds_read_b128 v[208:211], v160 offset:19456
	ds_read_b128 v[212:215], v160 offset:20480
	ds_read_b128 v[216:219], v160 offset:21504
	ds_read_b128 v[220:223], v160 offset:22528
	ds_read_b128 v[224:227], v160 offset:23552
	global_load_lds_dwordx4 v[170:171], off
	s_add_i32 m0, s51, 0x2000
	s_add_u32 s52, s22, 0x80000
	v_lshl_add_u64 v[228:229], s[22:23], 0, v[130:131]
	s_addc_u32 s53, s23, 0
	s_add_i32 s51, s40, s26
	global_load_lds_dwordx4 v[228:229], off
	v_lshl_add_u64 v[230:231], s[52:53], 0, v[134:135]
	s_mov_b32 m0, s51
	v_lshl_add_u64 v[232:233], s[24:25], 0, v[132:133]
	global_load_lds_dwordx4 v[230:231], off
	v_lshl_add_u64 v[230:231], s[52:53], 0, v[130:131]
	s_add_i32 m0, s51, 0x2000
	s_nop 0
	global_load_lds_dwordx4 v[230:231], off
	v_lshl_add_u64 v[230:231], s[24:25], 0, v[136:137]
	s_waitcnt vmcnt(6)
	s_waitcnt lgkmcnt(0)
	s_barrier
; #define PG8_STAGE(bufoff, gbase, voff) do { _Pragma("unroll") for (int _i = 0; _i < 2; ++_i) \
;         __builtin_amdgcn_global_load_lds((const unsigned*)((const char*)(gbase) + (voff)[_i]), (PG8_LAS unsigned*)(lds + (bufoff) + ldsw + _i * 8192), 16, 0, 0); } while (0)
; #define PG8_LDA(dst, b, h) do { _Pragma("unroll") for (int m = 0; m < 4; ++m) _Pragma("unroll") for (int k = 0; k < 2; ++k) dst[m][k] = *(const PG8_LAS bf16x8*)(lds + PG8_SA(b, h) + aoff + m * 2048 + k * 1024); } while (0)
; #define PG8_LDB(dst, b, h) do { _Pragma("unroll") for (int n = 0; n < 2; ++n) _Pragma("unroll") for (int k = 0; k < 2; ++k) dst[n][k] = *(const PG8_LAS bf16x8*)(lds + PG8_SB(b, h) + boff + n * 2048 + k * 1024); } while (0)
; #define PG8_MMA(ai, bj, At, Bt) do { __builtin_amdgcn_s_setprio(1); _Pragma("unroll") for (int m = 0; m < 4; ++m) _Pragma("unroll") for (int n = 0; n < 2; ++n) _Pragma("unroll") for (int k = 0; k < 2; ++k) \
;         acc[ai][bj][m][n] = __builtin_amdgcn_mfma_f32_16x16x32_bf16(Bt[n][k], At[m][k], acc[ai][bj][m][n], 0, 0, 0); __builtin_amdgcn_s_setprio(0); } while (0)
; #define PG8_WAIT_V(n) asm volatile("s_waitcnt vmcnt(" #n ")" ::: "memory")
; #define PG8_WAIT_L(n) asm volatile("s_waitcnt lgkmcnt(" #n ")" ::: "memory")
; #define PG8_BAR __builtin_amdgcn_s_barrier()
; #define PG8_SCHED __builtin_amdgcn_sched_barrier(0)
; template <class Epi, class Sched, bool ALIGN_EPI = false, bool SP2 = false>
; __device__ __forceinline__ void gemm_phase(PG8_LAS unsigned char* lds, const Gemm g, const Sched& S, const Epi& E) {
;     ...
;             PG8_WAIT_V(8); PG8_WAIT_L(0); PG8_BAR; PG8_MMA(1, 0, At, B0); PG8_MMA(1, 1, At, B1); PG8_BAR; PG8_SCHED;
;             PG8_LDB(B0, 1, 0); PG8_LDB(B1, 1, 1); PG8_SCHED; PG8_LDA(At, 1, 0); PG8_STAGE(PG8_SA(0, 1), a2 + hstep, voffA);
;             PG8_WAIT_V(8); PG8_WAIT_L(0); PG8_BAR; PG8_MMA(0, 0, At, B0); PG8_MMA(0, 1, At, B1); PG8_BAR; PG8_SCHED;
	s_setprio 1
	s_waitcnt lgkmcnt(0)
	v_mfma_f32_16x16x32_bf16 v[60:63], v[146:149], v[196:199], v[60:63]
	v_mfma_f32_16x16x32_bf16 v[52:55], v[162:165], v[196:199], v[52:55]
	v_mfma_f32_16x16x32_bf16 v[44:47], v[146:149], v[204:207], v[44:47]
	v_mfma_f32_16x16x32_bf16 v[36:39], v[162:165], v[204:207], v[36:39]
	v_mfma_f32_16x16x32_bf16 v[28:31], v[146:149], v[212:215], v[28:31]
	v_mfma_f32_16x16x32_bf16 v[20:23], v[162:165], v[212:215], v[20:23]
	v_mfma_f32_16x16x32_bf16 v[12:15], v[146:149], v[220:223], v[12:15]
	v_mfma_f32_16x16x32_bf16 v[4:7], v[162:165], v[220:223], v[4:7]
	v_mfma_f32_16x16x32_bf16 v[60:63], v[150:153], v[200:203], v[60:63]
	v_mfma_f32_16x16x32_bf16 v[52:55], v[166:169], v[200:203], v[52:55]
	v_mfma_f32_16x16x32_bf16 v[44:47], v[150:153], v[208:211], v[44:47]
	v_mfma_f32_16x16x32_bf16 v[36:39], v[166:169], v[208:211], v[36:39]
	v_mfma_f32_16x16x32_bf16 v[28:31], v[150:153], v[216:219], v[28:31]
	v_mfma_f32_16x16x32_bf16 v[20:23], v[166:169], v[216:219], v[20:23]
	v_mfma_f32_16x16x32_bf16 v[12:15], v[150:153], v[224:227], v[12:15]
	v_mfma_f32_16x16x32_bf16 v[4:7], v[166:169], v[224:227], v[4:7]
	s_setprio 0
	s_setprio 1
	v_mfma_f32_16x16x32_bf16 v[56:59], v[180:183], v[196:199], v[56:59]
	v_mfma_f32_16x16x32_bf16 v[48:51], v[188:191], v[196:199], v[48:51]
	v_mfma_f32_16x16x32_bf16 v[40:43], v[180:183], v[204:207], v[40:43]
	v_mfma_f32_16x16x32_bf16 v[32:35], v[188:191], v[204:207], v[32:35]
	v_mfma_f32_16x16x32_bf16 v[24:27], v[180:183], v[212:215], v[24:27]
	v_mfma_f32_16x16x32_bf16 v[16:19], v[188:191], v[212:215], v[16:19]
	v_mfma_f32_16x16x32_bf16 v[8:11], v[180:183], v[220:223], v[8:11]
	v_mfma_f32_16x16x32_bf16 v[0:3], v[188:191], v[220:223], v[0:3]
	v_mfma_f32_16x16x32_bf16 v[56:59], v[184:187], v[200:203], v[56:59]
	v_mfma_f32_16x16x32_bf16 v[48:51], v[192:195], v[200:203], v[48:51]
	v_mfma_f32_16x16x32_bf16 v[40:43], v[184:187], v[208:211], v[40:43]
	v_mfma_f32_16x16x32_bf16 v[32:35], v[192:195], v[208:211], v[32:35]
	v_mfma_f32_16x16x32_bf16 v[24:27], v[184:187], v[216:219], v[24:27]
	v_mfma_f32_16x16x32_bf16 v[16:19], v[192:195], v[216:219], v[16:19]
	v_mfma_f32_16x16x32_bf16 v[8:11], v[184:187], v[224:227], v[8:11]
	v_mfma_f32_16x16x32_bf16 v[0:3], v[192:195], v[224:227], v[0:3]
	s_setprio 0
	s_barrier
	s_add_i32 s51, 0, 0x18000
	v_add_u32_e32 v161, s51, v155
	s_add_i32 s52, 0, 0x1c000
	ds_read_b128 v[146:149], v161
	ds_read_b128 v[150:153], v161 offset:1024
	ds_read_b128 v[162:165], v161 offset:2048
	ds_read_b128 v[166:169], v161 offset:3072
	v_add_u32_e32 v161, s52, v155
	ds_read_b128 v[180:183], v161
	ds_read_b128 v[184:187], v161 offset:1024
	ds_read_b128 v[188:191], v161 offset:2048
	ds_read_b128 v[192:195], v161 offset:3072
	s_add_u32 s24, s24, 0x80000
	s_addc_u32 s25, s25, 0
	s_mov_b32 m0, s30
	s_nop 0
	global_load_lds_dwordx4 v[230:231], off
	s_mov_b32 m0, s31
	s_nop 0
	global_load_lds_dwordx4 v[232:233], off
	s_mov_b32 m0, s33
	v_lshl_add_u64 v[234:235], s[24:25], 0, v[136:137]
	ds_read_b128 v[196:199], v160 offset:32768
	ds_read_b128 v[200:203], v160 offset:33792
	ds_read_b128 v[204:207], v160 offset:34816
	ds_read_b128 v[208:211], v160 offset:35840
	ds_read_b128 v[212:215], v160 offset:36864
	ds_read_b128 v[216:219], v160 offset:37888
	ds_read_b128 v[220:223], v160 offset:38912
	ds_read_b128 v[224:227], v160 offset:39936
	global_load_lds_dwordx4 v[234:235], off
	v_lshl_add_u64 v[234:235], s[24:25], 0, v[132:133]
	s_mov_b32 m0, s34
	s_nop 0
	global_load_lds_dwordx4 v[234:235], off
	s_waitcnt vmcnt(8)
	s_waitcnt lgkmcnt(0)
	s_barrier
	s_setprio 1
	s_waitcnt lgkmcnt(0)
	v_mfma_f32_16x16x32_bf16 v[124:127], v[146:149], v[196:199], v[124:127]
	v_mfma_f32_16x16x32_bf16 v[116:119], v[162:165], v[196:199], v[116:119]
	v_mfma_f32_16x16x32_bf16 v[108:111], v[146:149], v[204:207], v[108:111]
	v_mfma_f32_16x16x32_bf16 v[100:103], v[162:165], v[204:207], v[100:103]
	v_mfma_f32_16x16x32_bf16 v[92:95], v[146:149], v[212:215], v[92:95]
	v_mfma_f32_16x16x32_bf16 v[84:87], v[162:165], v[212:215], v[84:87]
	v_mfma_f32_16x16x32_bf16 v[76:79], v[146:149], v[220:223], v[76:79]
	v_mfma_f32_16x16x32_bf16 v[68:71], v[162:165], v[220:223], v[68:71]
	v_mfma_f32_16x16x32_bf16 v[124:127], v[150:153], v[200:203], v[124:127]
	v_mfma_f32_16x16x32_bf16 v[116:119], v[166:169], v[200:203], v[116:119]
	v_mfma_f32_16x16x32_bf16 v[108:111], v[150:153], v[208:211], v[108:111]
	v_mfma_f32_16x16x32_bf16 v[100:103], v[166:169], v[208:211], v[100:103]
	v_mfma_f32_16x16x32_bf16 v[92:95], v[150:153], v[216:219], v[92:95]
	v_mfma_f32_16x16x32_bf16 v[84:87], v[166:169], v[216:219], v[84:87]
	v_mfma_f32_16x16x32_bf16 v[76:79], v[150:153], v[224:227], v[76:79]
	v_mfma_f32_16x16x32_bf16 v[68:71], v[166:169], v[224:227], v[68:71]
	s_setprio 0
	s_setprio 1
	v_mfma_f32_16x16x32_bf16 v[120:123], v[180:183], v[196:199], v[120:123]
	v_mfma_f32_16x16x32_bf16 v[112:115], v[188:191], v[196:199], v[112:115]
	v_mfma_f32_16x16x32_bf16 v[104:107], v[180:183], v[204:207], v[104:107]
	v_mfma_f32_16x16x32_bf16 v[96:99], v[188:191], v[204:207], v[96:99]
	v_mfma_f32_16x16x32_bf16 v[88:91], v[180:183], v[212:215], v[88:91]
	v_mfma_f32_16x16x32_bf16 v[80:83], v[188:191], v[212:215], v[80:83]
	v_mfma_f32_16x16x32_bf16 v[72:75], v[180:183], v[220:223], v[72:75]
	v_mfma_f32_16x16x32_bf16 v[64:67], v[188:191], v[220:223], v[64:67]
	v_mfma_f32_16x16x32_bf16 v[120:123], v[184:187], v[200:203], v[120:123]
	v_mfma_f32_16x16x32_bf16 v[112:115], v[192:195], v[200:203], v[112:115]
	v_mfma_f32_16x16x32_bf16 v[104:107], v[184:187], v[208:211], v[104:107]
	v_mfma_f32_16x16x32_bf16 v[96:99], v[192:195], v[208:211], v[96:99]
	v_mfma_f32_16x16x32_bf16 v[88:91], v[184:187], v[216:219], v[88:91]
	v_mfma_f32_16x16x32_bf16 v[80:83], v[192:195], v[216:219], v[80:83]
	v_mfma_f32_16x16x32_bf16 v[72:75], v[184:187], v[224:227], v[72:75]
	v_mfma_f32_16x16x32_bf16 v[64:67], v[192:195], v[224:227], v[64:67]
	s_setprio 0
	s_barrier
; #define PG8_STAGE(bufoff, gbase, voff) do { _Pragma("unroll") for (int _i = 0; _i < 2; ++_i) \
;         __builtin_amdgcn_global_load_lds((const unsigned*)((const char*)(gbase) + (voff)[_i]), (PG8_LAS unsigned*)(lds + (bufoff) + ldsw + _i * 8192), 16, 0, 0); } while (0)
; #define PG8_LDA(dst, b, h) do { _Pragma("unroll") for (int m = 0; m < 4; ++m) _Pragma("unroll") for (int k = 0; k < 2; ++k) dst[m][k] = *(const PG8_LAS bf16x8*)(lds + PG8_SA(b, h) + aoff + m * 2048 + k * 1024); } while (0)
; #define PG8_MMA(ai, bj, At, Bt) do { __builtin_amdgcn_s_setprio(1); _Pragma("unroll") for (int m = 0; m < 4; ++m) _Pragma("unroll") for (int n = 0; n < 2; ++n) _Pragma("unroll") for (int k = 0; k < 2; ++k) \
;         acc[ai][bj][m][n] = __builtin_amdgcn_mfma_f32_16x16x32_bf16(Bt[n][k], At[m][k], acc[ai][bj][m][n], 0, 0, 0); __builtin_amdgcn_s_setprio(0); } while (0)
; #define PG8_WAIT_V(n) asm volatile("s_waitcnt vmcnt(" #n ")" ::: "memory")
; #define PG8_WAIT_L(n) asm volatile("s_waitcnt lgkmcnt(" #n ")" ::: "memory")
; #define PG8_BAR __builtin_amdgcn_s_barrier()
; #define PG8_SCHED __builtin_amdgcn_sched_barrier(0)
; template <class Epi, class Sched, bool ALIGN_EPI = false, bool SP2 = false>
; __device__ __forceinline__ void gemm_phase(PG8_LAS unsigned char* lds, const Gemm g, const Sched& S, const Epi& E) {
;     ...
;             PG8_LDA(At, 1, 1); PG8_STAGE(PG8_SB(1, 0), b3, voffB); PG8_STAGE(PG8_SB(1, 1), b3 + hstep, voffB); PG8_STAGE(PG8_SA(1, 0), a3, voffA);
;             PG8_WAIT_V(8); PG8_WAIT_L(0); PG8_BAR; PG8_MMA(1, 0, At, B0); PG8_MMA(1, 1, At, B1); PG8_BAR; PG8_SCHED;
	s_add_i32 s24, s51, s26
	v_lshl_add_u64 v[170:171], v[170:171], 0, s[2:3]
	s_mov_b32 m0, s24
	ds_read_b128 v[196:199], v160 offset:49152
	ds_read_b128 v[200:203], v160 offset:50176
	ds_read_b128 v[204:207], v160 offset:51200
	ds_read_b128 v[208:211], v160 offset:52224
	ds_read_b128 v[212:215], v160 offset:53248
	ds_read_b128 v[216:219], v160 offset:54272
	ds_read_b128 v[220:223], v160 offset:55296
	ds_read_b128 v[224:227], v160 offset:56320
	global_load_lds_dwordx4 v[170:171], off
	s_add_i32 m0, s24, 0x2000
	s_add_u32 s22, s22, 0x80080
	v_lshl_add_u64 v[170:171], v[228:229], 0, s[2:3]
	s_addc_u32 s23, s23, 0
	s_add_i32 s24, s52, s26
	global_load_lds_dwordx4 v[170:171], off
	v_lshl_add_u64 v[170:171], s[22:23], 0, v[134:135]
	s_mov_b32 m0, s24
	s_nop 0
	global_load_lds_dwordx4 v[170:171], off
	v_lshl_add_u64 v[170:171], s[22:23], 0, v[130:131]
	s_add_i32 m0, s24, 0x2000
	s_nop 0
	global_load_lds_dwordx4 v[170:171], off
	v_lshl_add_u64 v[170:171], v[230:231], 0, s[2:3]
	v_lshl_add_u64 v[170:171], v[232:233], 0, s[2:3]
	s_waitcnt vmcnt(6)
	s_waitcnt lgkmcnt(0)
	s_barrier
	s_setprio 1
	s_waitcnt lgkmcnt(0)
	v_mfma_f32_16x16x32_bf16 v[60:63], v[146:149], v[196:199], v[60:63]
	v_mfma_f32_16x16x32_bf16 v[52:55], v[162:165], v[196:199], v[52:55]
	v_mfma_f32_16x16x32_bf16 v[44:47], v[146:149], v[204:207], v[44:47]
	v_mfma_f32_16x16x32_bf16 v[36:39], v[162:165], v[204:207], v[36:39]
	v_mfma_f32_16x16x32_bf16 v[28:31], v[146:149], v[212:215], v[28:31]
	v_mfma_f32_16x16x32_bf16 v[20:23], v[162:165], v[212:215], v[20:23]
	v_mfma_f32_16x16x32_bf16 v[12:15], v[146:149], v[220:223], v[12:15]
	v_mfma_f32_16x16x32_bf16 v[4:7], v[162:165], v[220:223], v[4:7]
	v_mfma_f32_16x16x32_bf16 v[60:63], v[150:153], v[200:203], v[60:63]
	v_mfma_f32_16x16x32_bf16 v[52:55], v[166:169], v[200:203], v[52:55]
	v_mfma_f32_16x16x32_bf16 v[44:47], v[150:153], v[208:211], v[44:47]
	v_mfma_f32_16x16x32_bf16 v[36:39], v[166:169], v[208:211], v[36:39]
	v_mfma_f32_16x16x32_bf16 v[28:31], v[150:153], v[216:219], v[28:31]
	v_mfma_f32_16x16x32_bf16 v[20:23], v[166:169], v[216:219], v[20:23]
	v_mfma_f32_16x16x32_bf16 v[12:15], v[150:153], v[224:227], v[12:15]
	v_mfma_f32_16x16x32_bf16 v[4:7], v[166:169], v[224:227], v[4:7]
	s_setprio 0
	s_setprio 1
	v_mfma_f32_16x16x32_bf16 v[56:59], v[180:183], v[196:199], v[56:59]
	v_mfma_f32_16x16x32_bf16 v[48:51], v[188:191], v[196:199], v[48:51]
	v_mfma_f32_16x16x32_bf16 v[40:43], v[180:183], v[204:207], v[40:43]
	v_mfma_f32_16x16x32_bf16 v[32:35], v[188:191], v[204:207], v[32:35]
	v_mfma_f32_16x16x32_bf16 v[24:27], v[180:183], v[212:215], v[24:27]
	v_mfma_f32_16x16x32_bf16 v[16:19], v[188:191], v[212:215], v[16:19]
	v_mfma_f32_16x16x32_bf16 v[8:11], v[180:183], v[220:223], v[8:11]
	v_mfma_f32_16x16x32_bf16 v[0:3], v[188:191], v[220:223], v[0:3]
	v_mfma_f32_16x16x32_bf16 v[56:59], v[184:187], v[200:203], v[56:59]
	v_mfma_f32_16x16x32_bf16 v[48:51], v[192:195], v[200:203], v[48:51]
	v_mfma_f32_16x16x32_bf16 v[40:43], v[184:187], v[208:211], v[40:43]
	v_mfma_f32_16x16x32_bf16 v[32:35], v[192:195], v[208:211], v[32:35]
	v_mfma_f32_16x16x32_bf16 v[24:27], v[184:187], v[216:219], v[24:27]
	v_mfma_f32_16x16x32_bf16 v[16:19], v[192:195], v[216:219], v[16:19]
	v_mfma_f32_16x16x32_bf16 v[8:11], v[184:187], v[224:227], v[8:11]
	v_mfma_f32_16x16x32_bf16 v[0:3], v[192:195], v[224:227], v[0:3]
	s_setprio 0
	s_barrier
	s_add_i32 s50, s50, 2
	s_add_u32 s20, s20, 0x100
	s_addc_u32 s21, s21, 0
	s_add_u32 s48, s48, 0x100
	s_addc_u32 s49, s49, 0
	s_cmp_gt_u32 s50, 29
	s_cbranch_scc0 .LBB0_837
	s_and_b64 vcc, exec, s[4:5]
	s_cbranch_vccz .LBB0_840
	s_barrier

; #define PG8_STAGE(bufoff, gbase, voff) do { _Pragma("unroll") for (int _i = 0; _i < 2; ++_i) \
;         __builtin_amdgcn_global_load_lds((const unsigned*)((const char*)(gbase) + (voff)[_i]), (PG8_LAS unsigned*)(lds + (bufoff) + ldsw + _i * 8192), 16, 0, 0); } while (0)
; #define PG8_LDA(dst, b, h) do { _Pragma("unroll") for (int m = 0; m < 4; ++m) _Pragma("unroll") for (int k = 0; k < 2; ++k) dst[m][k] = *(const PG8_LAS bf16x8*)(lds + PG8_SA(b, h) + aoff + m * 2048 + k * 1024); } while (0)
; #define PG8_LDB(dst, b, h) do { _Pragma("unroll") for (int n = 0; n < 2; ++n) _Pragma("unroll") for (int k = 0; k < 2; ++k) dst[n][k] = *(const PG8_LAS bf16x8*)(lds + PG8_SB(b, h) + boff + n * 2048 + k * 1024); } while (0)
; #define PG8_MMA(ai, bj, At, Bt) do { __builtin_amdgcn_s_setprio(1); _Pragma("unroll") for (int m = 0; m < 4; ++m) _Pragma("unroll") for (int n = 0; n < 2; ++n) _Pragma("unroll") for (int k = 0; k < 2; ++k) \
;         acc[ai][bj][m][n] = __builtin_amdgcn_mfma_f32_16x16x32_bf16(Bt[n][k], At[m][k], acc[ai][bj][m][n], 0, 0, 0); __builtin_amdgcn_s_setprio(0); } while (0)
; #define PG8_WAIT_V(n) asm volatile("s_waitcnt vmcnt(" #n ")" ::: "memory")
; #define PG8_WAIT_L(n) asm volatile("s_waitcnt lgkmcnt(" #n ")" ::: "memory")
; #define PG8_BAR __builtin_amdgcn_s_barrier()
; #define PG8_SCHED __builtin_amdgcn_sched_barrier(0)
; template <class Epi, class Sched, bool ALIGN_EPI = false, bool SP2 = false>
; __device__ __forceinline__ void gemm_phase(PG8_LAS unsigned char* lds, const Gemm g, const Sched& S, const Epi& E) {
;     ...
;             PG8_LDB(B0, 0, 0); PG8_LDB(B1, 0, 1); PG8_SCHED; PG8_LDA(At, 0, 0); PG8_STAGE(PG8_SA(1, 1), a1 + hstep, voffA);
;             PG8_WAIT_V(8); PG8_WAIT_L(0); PG8_BAR; PG8_MMA(0, 0, At, B0); PG8_MMA(0, 1, At, B1); PG8_BAR; PG8_SCHED;
;             PG8_LDA(At, 0, 1); PG8_STAGE(PG8_SB(0, 0), b2, voffB); PG8_STAGE(PG8_SB(0, 1), b2 + hstep, voffB); PG8_STAGE(PG8_SA(0, 0), a2, voffA);
.LBB0_1080:
	ds_read_b128 v[142:145], v151
	ds_read_b128 v[154:157], v151 offset:1024
	ds_read_b128 v[158:161], v151 offset:2048
	ds_read_b128 v[162:165], v151 offset:3072
	ds_read_b128 v[166:169], v152
	ds_read_b128 v[180:183], v152 offset:1024
	ds_read_b128 v[184:187], v152 offset:2048
	ds_read_b128 v[188:191], v152 offset:3072
	s_add_u32 s20, s18, 0x100
	s_addc_u32 s21, s19, 0
	s_cmpk_eq_i32 s49, 0x54
	s_cselect_b32 s25, s13, s21
	s_cselect_b32 s24, s12, s20
	s_cselect_b32 s23, s17, s48
	s_cselect_b32 s22, s16, s47
	s_mov_b32 s38, 0xffea0000
	s_mov_b32 s39, -1
	v_lshl_add_u64 v[146:147], s[18:19], 0, v[134:135]
	v_lshl_add_u64 v[146:147], v[146:147], 0, s[38:39]
	s_mov_b32 m0, s35
	s_nop 0
	global_load_lds_dwordx4 v[146:147], off
	v_lshl_add_u64 v[146:147], s[18:19], 0, v[136:137]
	v_lshl_add_u64 v[146:147], v[146:147], 0, s[38:39]
	s_mov_b32 m0, s36
	s_nop 0
	global_load_lds_dwordx4 v[146:147], off
	v_lshl_add_u64 v[146:147], s[18:19], 0, v[134:135]
	s_add_i32 m0, s29, 0xc000
	ds_read_b128 v[192:195], v153
	ds_read_b128 v[196:199], v153 offset:1024
	ds_read_b128 v[200:203], v153 offset:2048
	ds_read_b128 v[204:207], v153 offset:3072
	ds_read_b128 v[208:211], v153 offset:4096
	ds_read_b128 v[212:215], v153 offset:5120
	ds_read_b128 v[216:219], v153 offset:6144
	ds_read_b128 v[220:223], v153 offset:7168
	global_load_lds_dwordx4 v[146:147], off
	v_lshl_add_u64 v[146:147], s[18:19], 0, v[136:137]
	s_add_i32 m0, s29, 0xe000
	s_nop 0
	global_load_lds_dwordx4 v[146:147], off
	s_waitcnt vmcnt(8)
	s_waitcnt lgkmcnt(0)
	s_barrier
	s_setprio 1
	s_waitcnt lgkmcnt(0)
	v_mfma_f32_16x16x32_bf16 v[124:127], v[142:145], v[192:195], v[124:127]
	v_mfma_f32_16x16x32_bf16 v[120:123], v[158:161], v[192:195], v[120:123]
	v_mfma_f32_16x16x32_bf16 v[108:111], v[142:145], v[200:203], v[108:111]
	v_mfma_f32_16x16x32_bf16 v[104:107], v[158:161], v[200:203], v[104:107]
	v_mfma_f32_16x16x32_bf16 v[92:95], v[142:145], v[208:211], v[92:95]
	v_mfma_f32_16x16x32_bf16 v[88:91], v[158:161], v[208:211], v[88:91]
	v_mfma_f32_16x16x32_bf16 v[76:79], v[142:145], v[216:219], v[76:79]
	v_mfma_f32_16x16x32_bf16 v[72:75], v[158:161], v[216:219], v[72:75]
	v_mfma_f32_16x16x32_bf16 v[124:127], v[154:157], v[196:199], v[124:127]
	v_mfma_f32_16x16x32_bf16 v[120:123], v[162:165], v[196:199], v[120:123]
	v_mfma_f32_16x16x32_bf16 v[108:111], v[154:157], v[204:207], v[108:111]
	v_mfma_f32_16x16x32_bf16 v[104:107], v[162:165], v[204:207], v[104:107]
	v_mfma_f32_16x16x32_bf16 v[92:95], v[154:157], v[212:215], v[92:95]
	v_mfma_f32_16x16x32_bf16 v[88:91], v[162:165], v[212:215], v[88:91]
	v_mfma_f32_16x16x32_bf16 v[76:79], v[154:157], v[220:223], v[76:79]
	v_mfma_f32_16x16x32_bf16 v[72:75], v[162:165], v[220:223], v[72:75]
	s_setprio 0
	s_setprio 1
	v_mfma_f32_16x16x32_bf16 v[116:119], v[166:169], v[192:195], v[116:119]
	v_mfma_f32_16x16x32_bf16 v[112:115], v[184:187], v[192:195], v[112:115]
	v_mfma_f32_16x16x32_bf16 v[100:103], v[166:169], v[200:203], v[100:103]
	v_mfma_f32_16x16x32_bf16 v[96:99], v[184:187], v[200:203], v[96:99]
	v_mfma_f32_16x16x32_bf16 v[84:87], v[166:169], v[208:211], v[84:87]
	v_mfma_f32_16x16x32_bf16 v[80:83], v[184:187], v[208:211], v[80:83]
	v_mfma_f32_16x16x32_bf16 v[68:71], v[166:169], v[216:219], v[68:71]
	v_mfma_f32_16x16x32_bf16 v[64:67], v[184:187], v[216:219], v[64:67]
	v_mfma_f32_16x16x32_bf16 v[116:119], v[180:183], v[196:199], v[116:119]
	v_mfma_f32_16x16x32_bf16 v[112:115], v[188:191], v[196:199], v[112:115]
	v_mfma_f32_16x16x32_bf16 v[100:103], v[180:183], v[204:207], v[100:103]
	v_mfma_f32_16x16x32_bf16 v[96:99], v[188:191], v[204:207], v[96:99]
	v_mfma_f32_16x16x32_bf16 v[84:87], v[180:183], v[212:215], v[84:87]
	v_mfma_f32_16x16x32_bf16 v[80:83], v[188:191], v[212:215], v[80:83]
	v_mfma_f32_16x16x32_bf16 v[68:71], v[180:183], v[220:223], v[68:71]
	v_mfma_f32_16x16x32_bf16 v[64:67], v[188:191], v[220:223], v[64:67]
	s_setprio 0
	s_barrier
	s_add_i32 s18, s37, s28
	v_lshl_add_u64 v[146:147], s[22:23], 0, v[130:131]
	s_mov_b32 m0, s18
	ds_read_b128 v[192:195], v153 offset:16384
	ds_read_b128 v[196:199], v153 offset:17408
	ds_read_b128 v[200:203], v153 offset:18432
	ds_read_b128 v[204:207], v153 offset:19456
	ds_read_b128 v[208:211], v153 offset:20480
	ds_read_b128 v[212:215], v153 offset:21504
	ds_read_b128 v[216:219], v153 offset:22528
	ds_read_b128 v[220:223], v153 offset:23552
	global_load_lds_dwordx4 v[146:147], off
	s_add_i32 m0, s18, 0x2000
	s_add_u32 s18, s22, 0x160000
	v_lshl_add_u64 v[170:171], s[22:23], 0, v[132:133]
	s_addc_u32 s19, s23, 0
	s_add_i32 s50, s40, s28
	global_load_lds_dwordx4 v[170:171], off
	v_lshl_add_u64 v[224:225], s[18:19], 0, v[130:131]
	s_mov_b32 m0, s50
	v_lshl_add_u64 v[226:227], s[24:25], 0, v[132:133]
	global_load_lds_dwordx4 v[224:225], off
	v_lshl_add_u64 v[224:225], s[18:19], 0, v[132:133]
	s_add_i32 m0, s50, 0x2000
	s_nop 0
	global_load_lds_dwordx4 v[224:225], off
	v_lshl_add_u64 v[224:225], s[24:25], 0, v[130:131]
	s_waitcnt vmcnt(6)
	s_waitcnt lgkmcnt(0)
	s_barrier
; #define PG8_STAGE(bufoff, gbase, voff) do { _Pragma("unroll") for (int _i = 0; _i < 2; ++_i) \
;         __builtin_amdgcn_global_load_lds((const unsigned*)((const char*)(gbase) + (voff)[_i]), (PG8_LAS unsigned*)(lds + (bufoff) + ldsw + _i * 8192), 16, 0, 0); } while (0)
; #define PG8_LDA(dst, b, h) do { _Pragma("unroll") for (int m = 0; m < 4; ++m) _Pragma("unroll") for (int k = 0; k < 2; ++k) dst[m][k] = *(const PG8_LAS bf16x8*)(lds + PG8_SA(b, h) + aoff + m * 2048 + k * 1024); } while (0)
; #define PG8_LDB(dst, b, h) do { _Pragma("unroll") for (int n = 0; n < 2; ++n) _Pragma("unroll") for (int k = 0; k < 2; ++k) dst[n][k] = *(const PG8_LAS bf16x8*)(lds + PG8_SB(b, h) + boff + n * 2048 + k * 1024); } while (0)
; #define PG8_MMA(ai, bj, At, Bt) do { __builtin_amdgcn_s_setprio(1); _Pragma("unroll") for (int m = 0; m < 4; ++m) _Pragma("unroll") for (int n = 0; n < 2; ++n) _Pragma("unroll") for (int k = 0; k < 2; ++k) \
;         acc[ai][bj][m][n] = __builtin_amdgcn_mfma_f32_16x16x32_bf16(Bt[n][k], At[m][k], acc[ai][bj][m][n], 0, 0, 0); __builtin_amdgcn_s_setprio(0); } while (0)
; #define PG8_WAIT_V(n) asm volatile("s_waitcnt vmcnt(" #n ")" ::: "memory")
; #define PG8_WAIT_L(n) asm volatile("s_waitcnt lgkmcnt(" #n ")" ::: "memory")
; #define PG8_BAR __builtin_amdgcn_s_barrier()
; #define PG8_SCHED __builtin_amdgcn_sched_barrier(0)
; template <class Epi, class Sched, bool ALIGN_EPI = false, bool SP2 = false>
; __device__ __forceinline__ void gemm_phase(PG8_LAS unsigned char* lds, const Gemm g, const Sched& S, const Epi& E) {
;     ...
;             PG8_WAIT_V(8); PG8_WAIT_L(0); PG8_BAR; PG8_MMA(1, 0, At, B0); PG8_MMA(1, 1, At, B1); PG8_BAR; PG8_SCHED;
;             PG8_LDB(B0, 1, 0); PG8_LDB(B1, 1, 1); PG8_SCHED; PG8_LDA(At, 1, 0); PG8_STAGE(PG8_SA(0, 1), a2 + hstep, voffA);
;             PG8_WAIT_V(8); PG8_WAIT_L(0); PG8_BAR; PG8_MMA(0, 0, At, B0); PG8_MMA(0, 1, At, B1); PG8_BAR; PG8_SCHED;
	s_setprio 1
	s_waitcnt lgkmcnt(0)
	v_mfma_f32_16x16x32_bf16 v[60:63], v[142:145], v[192:195], v[60:63]
	v_mfma_f32_16x16x32_bf16 v[56:59], v[158:161], v[192:195], v[56:59]
	v_mfma_f32_16x16x32_bf16 v[44:47], v[142:145], v[200:203], v[44:47]
	v_mfma_f32_16x16x32_bf16 v[40:43], v[158:161], v[200:203], v[40:43]
	v_mfma_f32_16x16x32_bf16 v[28:31], v[142:145], v[208:211], v[28:31]
	v_mfma_f32_16x16x32_bf16 v[24:27], v[158:161], v[208:211], v[24:27]
	v_mfma_f32_16x16x32_bf16 v[12:15], v[142:145], v[216:219], v[12:15]
	v_mfma_f32_16x16x32_bf16 v[8:11], v[158:161], v[216:219], v[8:11]
	v_mfma_f32_16x16x32_bf16 v[60:63], v[154:157], v[196:199], v[60:63]
	v_mfma_f32_16x16x32_bf16 v[56:59], v[162:165], v[196:199], v[56:59]
	v_mfma_f32_16x16x32_bf16 v[44:47], v[154:157], v[204:207], v[44:47]
	v_mfma_f32_16x16x32_bf16 v[40:43], v[162:165], v[204:207], v[40:43]
	v_mfma_f32_16x16x32_bf16 v[28:31], v[154:157], v[212:215], v[28:31]
	v_mfma_f32_16x16x32_bf16 v[24:27], v[162:165], v[212:215], v[24:27]
	v_mfma_f32_16x16x32_bf16 v[12:15], v[154:157], v[220:223], v[12:15]
	v_mfma_f32_16x16x32_bf16 v[8:11], v[162:165], v[220:223], v[8:11]
	s_setprio 0
	s_setprio 1
	v_mfma_f32_16x16x32_bf16 v[52:55], v[166:169], v[192:195], v[52:55]
	v_mfma_f32_16x16x32_bf16 v[48:51], v[184:187], v[192:195], v[48:51]
	v_mfma_f32_16x16x32_bf16 v[36:39], v[166:169], v[200:203], v[36:39]
	v_mfma_f32_16x16x32_bf16 v[32:35], v[184:187], v[200:203], v[32:35]
	v_mfma_f32_16x16x32_bf16 v[20:23], v[166:169], v[208:211], v[20:23]
	v_mfma_f32_16x16x32_bf16 v[16:19], v[184:187], v[208:211], v[16:19]
	v_mfma_f32_16x16x32_bf16 v[4:7], v[166:169], v[216:219], v[4:7]
	v_mfma_f32_16x16x32_bf16 v[0:3], v[184:187], v[216:219], v[0:3]
	v_mfma_f32_16x16x32_bf16 v[52:55], v[180:183], v[196:199], v[52:55]
	v_mfma_f32_16x16x32_bf16 v[48:51], v[188:191], v[196:199], v[48:51]
	v_mfma_f32_16x16x32_bf16 v[36:39], v[180:183], v[204:207], v[36:39]
	v_mfma_f32_16x16x32_bf16 v[32:35], v[188:191], v[204:207], v[32:35]
	v_mfma_f32_16x16x32_bf16 v[20:23], v[180:183], v[212:215], v[20:23]
	v_mfma_f32_16x16x32_bf16 v[16:19], v[188:191], v[212:215], v[16:19]
	v_mfma_f32_16x16x32_bf16 v[4:7], v[180:183], v[220:223], v[4:7]
	v_mfma_f32_16x16x32_bf16 v[0:3], v[188:191], v[220:223], v[0:3]
	s_setprio 0
	s_barrier
	s_add_i32 s50, 0, 0x18000
	s_add_i32 s51, 0, 0x1c000
	v_add_u32_e32 v162, s50, v149
	v_add_u32_e32 v179, s51, v149
	ds_read_b128 v[142:145], v162
	ds_read_b128 v[154:157], v162 offset:1024
	ds_read_b128 v[158:161], v162 offset:2048
	ds_read_b128 v[162:165], v162 offset:3072
	ds_read_b128 v[166:169], v179
	ds_read_b128 v[180:183], v179 offset:1024
	ds_read_b128 v[184:187], v179 offset:2048
	ds_read_b128 v[188:191], v179 offset:3072
	s_add_u32 s18, s24, 0x160000
	s_addc_u32 s19, s25, 0
	s_mov_b32 m0, s29
	s_nop 0
	global_load_lds_dwordx4 v[224:225], off
	s_mov_b32 m0, s30
	s_nop 0
	global_load_lds_dwordx4 v[226:227], off
	s_mov_b32 m0, s31
	v_lshl_add_u64 v[228:229], s[18:19], 0, v[130:131]
	ds_read_b128 v[192:195], v153 offset:32768
	ds_read_b128 v[196:199], v153 offset:33792
	ds_read_b128 v[200:203], v153 offset:34816
	ds_read_b128 v[204:207], v153 offset:35840
	ds_read_b128 v[208:211], v153 offset:36864
	ds_read_b128 v[212:215], v153 offset:37888
	ds_read_b128 v[216:219], v153 offset:38912
	ds_read_b128 v[220:223], v153 offset:39936
	global_load_lds_dwordx4 v[228:229], off
	v_lshl_add_u64 v[228:229], s[18:19], 0, v[132:133]
	s_mov_b32 m0, s33
	s_nop 0
	global_load_lds_dwordx4 v[228:229], off
	s_waitcnt vmcnt(8)
	s_waitcnt lgkmcnt(0)
	s_barrier
	s_setprio 1
	s_waitcnt lgkmcnt(0)
	v_mfma_f32_16x16x32_bf16 v[124:127], v[142:145], v[192:195], v[124:127]
	v_mfma_f32_16x16x32_bf16 v[120:123], v[158:161], v[192:195], v[120:123]
	v_mfma_f32_16x16x32_bf16 v[108:111], v[142:145], v[200:203], v[108:111]
	v_mfma_f32_16x16x32_bf16 v[104:107], v[158:161], v[200:203], v[104:107]
	v_mfma_f32_16x16x32_bf16 v[92:95], v[142:145], v[208:211], v[92:95]
	v_mfma_f32_16x16x32_bf16 v[88:91], v[158:161], v[208:211], v[88:91]
	v_mfma_f32_16x16x32_bf16 v[76:79], v[142:145], v[216:219], v[76:79]
	v_mfma_f32_16x16x32_bf16 v[72:75], v[158:161], v[216:219], v[72:75]
	v_mfma_f32_16x16x32_bf16 v[124:127], v[154:157], v[196:199], v[124:127]
	v_mfma_f32_16x16x32_bf16 v[120:123], v[162:165], v[196:199], v[120:123]
	v_mfma_f32_16x16x32_bf16 v[108:111], v[154:157], v[204:207], v[108:111]
	v_mfma_f32_16x16x32_bf16 v[104:107], v[162:165], v[204:207], v[104:107]
	v_mfma_f32_16x16x32_bf16 v[92:95], v[154:157], v[212:215], v[92:95]
	v_mfma_f32_16x16x32_bf16 v[88:91], v[162:165], v[212:215], v[88:91]
	v_mfma_f32_16x16x32_bf16 v[76:79], v[154:157], v[220:223], v[76:79]
	v_mfma_f32_16x16x32_bf16 v[72:75], v[162:165], v[220:223], v[72:75]
	s_setprio 0
	s_setprio 1
	v_mfma_f32_16x16x32_bf16 v[116:119], v[166:169], v[192:195], v[116:119]
	v_mfma_f32_16x16x32_bf16 v[112:115], v[184:187], v[192:195], v[112:115]
	v_mfma_f32_16x16x32_bf16 v[100:103], v[166:169], v[200:203], v[100:103]
	v_mfma_f32_16x16x32_bf16 v[96:99], v[184:187], v[200:203], v[96:99]
	v_mfma_f32_16x16x32_bf16 v[84:87], v[166:169], v[208:211], v[84:87]
	v_mfma_f32_16x16x32_bf16 v[80:83], v[184:187], v[208:211], v[80:83]
	v_mfma_f32_16x16x32_bf16 v[68:71], v[166:169], v[216:219], v[68:71]
	v_mfma_f32_16x16x32_bf16 v[64:67], v[184:187], v[216:219], v[64:67]
	v_mfma_f32_16x16x32_bf16 v[116:119], v[180:183], v[196:199], v[116:119]
	v_mfma_f32_16x16x32_bf16 v[112:115], v[188:191], v[196:199], v[112:115]
	v_mfma_f32_16x16x32_bf16 v[100:103], v[180:183], v[204:207], v[100:103]
	v_mfma_f32_16x16x32_bf16 v[96:99], v[188:191], v[204:207], v[96:99]
	v_mfma_f32_16x16x32_bf16 v[84:87], v[180:183], v[212:215], v[84:87]
	v_mfma_f32_16x16x32_bf16 v[80:83], v[188:191], v[212:215], v[80:83]
	v_mfma_f32_16x16x32_bf16 v[68:71], v[180:183], v[220:223], v[68:71]
	v_mfma_f32_16x16x32_bf16 v[64:67], v[188:191], v[220:223], v[64:67]
	s_setprio 0
	s_barrier
; #define PG8_STAGE(bufoff, gbase, voff) do { _Pragma("unroll") for (int _i = 0; _i < 2; ++_i) \
;         __builtin_amdgcn_global_load_lds((const unsigned*)((const char*)(gbase) + (voff)[_i]), (PG8_LAS unsigned*)(lds + (bufoff) + ldsw + _i * 8192), 16, 0, 0); } while (0)
; #define PG8_LDA(dst, b, h) do { _Pragma("unroll") for (int m = 0; m < 4; ++m) _Pragma("unroll") for (int k = 0; k < 2; ++k) dst[m][k] = *(const PG8_LAS bf16x8*)(lds + PG8_SA(b, h) + aoff + m * 2048 + k * 1024); } while (0)
; #define PG8_MMA(ai, bj, At, Bt) do { __builtin_amdgcn_s_setprio(1); _Pragma("unroll") for (int m = 0; m < 4; ++m) _Pragma("unroll") for (int n = 0; n < 2; ++n) _Pragma("unroll") for (int k = 0; k < 2; ++k) \
;         acc[ai][bj][m][n] = __builtin_amdgcn_mfma_f32_16x16x32_bf16(Bt[n][k], At[m][k], acc[ai][bj][m][n], 0, 0, 0); __builtin_amdgcn_s_setprio(0); } while (0)
; #define PG8_WAIT_V(n) asm volatile("s_waitcnt vmcnt(" #n ")" ::: "memory")
; #define PG8_WAIT_L(n) asm volatile("s_waitcnt lgkmcnt(" #n ")" ::: "memory")
; #define PG8_BAR __builtin_amdgcn_s_barrier()
; #define PG8_SCHED __builtin_amdgcn_sched_barrier(0)
; template <class Epi, class Sched, bool ALIGN_EPI = false, bool SP2 = false>
; __device__ __forceinline__ void gemm_phase(PG8_LAS unsigned char* lds, const Gemm g, const Sched& S, const Epi& E) {
;     ...
;             PG8_LDA(At, 1, 1); PG8_STAGE(PG8_SB(1, 0), b3, voffB); PG8_STAGE(PG8_SB(1, 1), b3 + hstep, voffB); PG8_STAGE(PG8_SA(1, 0), a3, voffA);
;             PG8_WAIT_V(8); PG8_WAIT_L(0); PG8_BAR; PG8_MMA(1, 0, At, B0); PG8_MMA(1, 1, At, B1); PG8_BAR; PG8_SCHED;
	s_add_i32 s18, s50, s28
	v_lshl_add_u64 v[146:147], v[146:147], 0, s[4:5]
	s_mov_b32 m0, s18
	ds_read_b128 v[192:195], v153 offset:49152
	ds_read_b128 v[196:199], v153 offset:50176
	ds_read_b128 v[200:203], v153 offset:51200
	ds_read_b128 v[204:207], v153 offset:52224
	ds_read_b128 v[208:211], v153 offset:53248
	ds_read_b128 v[212:215], v153 offset:54272
	ds_read_b128 v[216:219], v153 offset:55296
	ds_read_b128 v[220:223], v153 offset:56320
	global_load_lds_dwordx4 v[146:147], off
	s_add_i32 m0, s18, 0x2000
	s_add_u32 s18, s22, 0x160080
	v_lshl_add_u64 v[146:147], v[170:171], 0, s[4:5]
	s_addc_u32 s19, s23, 0
	s_add_i32 s22, s51, s28
	global_load_lds_dwordx4 v[146:147], off
	v_lshl_add_u64 v[146:147], s[18:19], 0, v[130:131]
	s_mov_b32 m0, s22
	s_nop 0
	global_load_lds_dwordx4 v[146:147], off
	v_lshl_add_u64 v[146:147], s[18:19], 0, v[132:133]
	s_add_i32 m0, s22, 0x2000
	s_nop 0
	global_load_lds_dwordx4 v[146:147], off
	v_lshl_add_u64 v[146:147], v[224:225], 0, s[4:5]
	v_lshl_add_u64 v[146:147], v[226:227], 0, s[4:5]
	s_waitcnt vmcnt(6)
	s_waitcnt lgkmcnt(0)
	s_barrier
	s_setprio 1
	s_waitcnt lgkmcnt(0)
	v_mfma_f32_16x16x32_bf16 v[60:63], v[142:145], v[192:195], v[60:63]
	v_mfma_f32_16x16x32_bf16 v[56:59], v[158:161], v[192:195], v[56:59]
	v_mfma_f32_16x16x32_bf16 v[44:47], v[142:145], v[200:203], v[44:47]
	v_mfma_f32_16x16x32_bf16 v[40:43], v[158:161], v[200:203], v[40:43]
	v_mfma_f32_16x16x32_bf16 v[28:31], v[142:145], v[208:211], v[28:31]
	v_mfma_f32_16x16x32_bf16 v[24:27], v[158:161], v[208:211], v[24:27]
	v_mfma_f32_16x16x32_bf16 v[12:15], v[142:145], v[216:219], v[12:15]
	v_mfma_f32_16x16x32_bf16 v[8:11], v[158:161], v[216:219], v[8:11]
	v_mfma_f32_16x16x32_bf16 v[60:63], v[154:157], v[196:199], v[60:63]
	v_mfma_f32_16x16x32_bf16 v[56:59], v[162:165], v[196:199], v[56:59]
	v_mfma_f32_16x16x32_bf16 v[44:47], v[154:157], v[204:207], v[44:47]
	v_mfma_f32_16x16x32_bf16 v[40:43], v[162:165], v[204:207], v[40:43]
	v_mfma_f32_16x16x32_bf16 v[28:31], v[154:157], v[212:215], v[28:31]
	v_mfma_f32_16x16x32_bf16 v[24:27], v[162:165], v[212:215], v[24:27]
	v_mfma_f32_16x16x32_bf16 v[12:15], v[154:157], v[220:223], v[12:15]
	v_mfma_f32_16x16x32_bf16 v[8:11], v[162:165], v[220:223], v[8:11]
	s_setprio 0
	s_setprio 1
	v_mfma_f32_16x16x32_bf16 v[52:55], v[166:169], v[192:195], v[52:55]
	v_mfma_f32_16x16x32_bf16 v[48:51], v[184:187], v[192:195], v[48:51]
	v_mfma_f32_16x16x32_bf16 v[36:39], v[166:169], v[200:203], v[36:39]
	v_mfma_f32_16x16x32_bf16 v[32:35], v[184:187], v[200:203], v[32:35]
	v_mfma_f32_16x16x32_bf16 v[20:23], v[166:169], v[208:211], v[20:23]
	v_mfma_f32_16x16x32_bf16 v[16:19], v[184:187], v[208:211], v[16:19]
	v_mfma_f32_16x16x32_bf16 v[4:7], v[166:169], v[216:219], v[4:7]
	v_mfma_f32_16x16x32_bf16 v[0:3], v[184:187], v[216:219], v[0:3]
	v_mfma_f32_16x16x32_bf16 v[52:55], v[180:183], v[196:199], v[52:55]
	v_mfma_f32_16x16x32_bf16 v[48:51], v[188:191], v[196:199], v[48:51]
	v_mfma_f32_16x16x32_bf16 v[36:39], v[180:183], v[204:207], v[36:39]
	v_mfma_f32_16x16x32_bf16 v[32:35], v[188:191], v[204:207], v[32:35]
	v_mfma_f32_16x16x32_bf16 v[20:23], v[180:183], v[212:215], v[20:23]
	v_mfma_f32_16x16x32_bf16 v[16:19], v[188:191], v[212:215], v[16:19]
	v_mfma_f32_16x16x32_bf16 v[4:7], v[180:183], v[220:223], v[4:7]
	v_mfma_f32_16x16x32_bf16 v[0:3], v[188:191], v[220:223], v[0:3]
	s_setprio 0
	s_barrier
	s_add_i32 s49, s49, 2
	s_add_u32 s47, s47, 0x100
	s_addc_u32 s48, s48, 0
	s_cmpk_gt_u32 s49, 0x55
	s_mov_b64 s[18:19], s[20:21]
	s_cbranch_scc0 .LBB0_1080
	s_and_b64 vcc, exec, s[6:7]
	s_cbranch_vccz .LBB0_1083
	s_barrier

; #define PG8_STAGE(bufoff, gbase, voff) do { _Pragma("unroll") for (int _i = 0; _i < 2; ++_i) \
;         __builtin_amdgcn_global_load_lds((const unsigned*)((const char*)(gbase) + (voff)[_i]), (PG8_LAS unsigned*)(lds + (bufoff) + ldsw + _i * 8192), 16, 0, 0); } while (0)
; #define PG8_LDA(dst, b, h) do { _Pragma("unroll") for (int m = 0; m < 4; ++m) _Pragma("unroll") for (int k = 0; k < 2; ++k) dst[m][k] = *(const PG8_LAS bf16x8*)(lds + PG8_SA(b, h) + aoff + m * 2048 + k * 1024); } while (0)
; #define PG8_LDB(dst, b, h) do { _Pragma("unroll") for (int n = 0; n < 2; ++n) _Pragma("unroll") for (int k = 0; k < 2; ++k) dst[n][k] = *(const PG8_LAS bf16x8*)(lds + PG8_SB(b, h) + boff + n * 2048 + k * 1024); } while (0)
; #define PG8_MMA(ai, bj, At, Bt) do { __builtin_amdgcn_s_setprio(1); _Pragma("unroll") for (int m = 0; m < 4; ++m) _Pragma("unroll") for (int n = 0; n < 2; ++n) _Pragma("unroll") for (int k = 0; k < 2; ++k) \
;         acc[ai][bj][m][n] = __builtin_amdgcn_mfma_f32_16x16x32_bf16(Bt[n][k], At[m][k], acc[ai][bj][m][n], 0, 0, 0); __builtin_amdgcn_s_setprio(0); } while (0)
; #define PG8_WAIT_V(n) asm volatile("s_waitcnt vmcnt(" #n ")" ::: "memory")
; #define PG8_WAIT_L(n) asm volatile("s_waitcnt lgkmcnt(" #n ")" ::: "memory")
; #define PG8_BAR __builtin_amdgcn_s_barrier()
; #define PG8_SCHED __builtin_amdgcn_sched_barrier(0)
; template <class Epi, class Sched, bool ALIGN_EPI = false, bool SP2 = false>
; __device__ __forceinline__ void gemm_phase(PG8_LAS unsigned char* lds, const Gemm g, const Sched& S, const Epi& E) {
;     ...
;             PG8_LDB(B0, 0, 0); PG8_LDB(B1, 0, 1); PG8_SCHED; PG8_LDA(At, 0, 0); PG8_STAGE(PG8_SA(1, 1), a1 + hstep, voffA);
;             PG8_WAIT_V(8); PG8_WAIT_L(0); PG8_BAR; PG8_MMA(0, 0, At, B0); PG8_MMA(0, 1, At, B1); PG8_BAR; PG8_SCHED;
;             PG8_LDA(At, 0, 1); PG8_STAGE(PG8_SB(0, 0), b2, voffB); PG8_STAGE(PG8_SB(0, 1), b2 + hstep, voffB); PG8_STAGE(PG8_SA(0, 0), a2, voffA);
.LBB0_1181:
	ds_read_b128 v[146:149], v154
	ds_read_b128 v[158:161], v154 offset:1024
	ds_read_b128 v[162:165], v154 offset:2048
	ds_read_b128 v[166:169], v154 offset:3072
	ds_read_b128 v[180:183], v155
	ds_read_b128 v[184:187], v155 offset:1024
	ds_read_b128 v[188:191], v155 offset:2048
	ds_read_b128 v[192:195], v155 offset:3072
	s_add_u32 s22, s20, 0xfff80080
	s_addc_u32 s23, s21, -1
	s_cmp_eq_u32 s48, 28
	s_cselect_b32 s25, s11, s23
	s_cselect_b32 s24, s44, s22
	s_cselect_b32 s23, s7, s47
	s_cselect_b32 s22, s45, s46
	s_mov_b32 s38, 0xfff80000
	s_mov_b32 s39, -1
	v_lshl_add_u64 v[170:171], s[20:21], 0, v[138:139]
	v_lshl_add_u64 v[170:171], v[170:171], 0, s[38:39]
	s_mov_b32 m0, s33
	s_nop 0
	global_load_lds_dwordx4 v[170:171], off
	v_lshl_add_u64 v[170:171], s[20:21], 0, v[140:141]
	v_lshl_add_u64 v[170:171], v[170:171], 0, s[38:39]
	s_mov_b32 m0, s34
	s_nop 0
	global_load_lds_dwordx4 v[170:171], off
	v_lshl_add_u64 v[170:171], s[20:21], 0, v[138:139]
	s_add_i32 m0, s17, 0xc000
	ds_read_b128 v[196:199], v156
	ds_read_b128 v[200:203], v156 offset:1024
	ds_read_b128 v[204:207], v156 offset:2048
	ds_read_b128 v[208:211], v156 offset:3072
	ds_read_b128 v[212:215], v156 offset:4096
	ds_read_b128 v[216:219], v156 offset:5120
	ds_read_b128 v[220:223], v156 offset:6144
	ds_read_b128 v[224:227], v156 offset:7168
	global_load_lds_dwordx4 v[170:171], off
	v_lshl_add_u64 v[170:171], s[20:21], 0, v[140:141]
	s_add_i32 m0, s17, 0xe000
	s_nop 0
	global_load_lds_dwordx4 v[170:171], off
	s_waitcnt vmcnt(8)
	s_waitcnt lgkmcnt(0)
	s_barrier
	s_setprio 1
	s_waitcnt lgkmcnt(0)
	v_mfma_f32_16x16x32_bf16 v[124:127], v[146:149], v[196:199], v[124:127]
	v_mfma_f32_16x16x32_bf16 v[120:123], v[162:165], v[196:199], v[120:123]
	v_mfma_f32_16x16x32_bf16 v[112:115], v[146:149], v[204:207], v[112:115]
	v_mfma_f32_16x16x32_bf16 v[104:107], v[162:165], v[204:207], v[104:107]
	v_mfma_f32_16x16x32_bf16 v[96:99], v[146:149], v[212:215], v[96:99]
	v_mfma_f32_16x16x32_bf16 v[88:91], v[162:165], v[212:215], v[88:91]
	v_mfma_f32_16x16x32_bf16 v[80:83], v[146:149], v[220:223], v[80:83]
	v_mfma_f32_16x16x32_bf16 v[72:75], v[162:165], v[220:223], v[72:75]
	v_mfma_f32_16x16x32_bf16 v[124:127], v[158:161], v[200:203], v[124:127]
	v_mfma_f32_16x16x32_bf16 v[120:123], v[166:169], v[200:203], v[120:123]
	v_mfma_f32_16x16x32_bf16 v[112:115], v[158:161], v[208:211], v[112:115]
	v_mfma_f32_16x16x32_bf16 v[104:107], v[166:169], v[208:211], v[104:107]
	v_mfma_f32_16x16x32_bf16 v[96:99], v[158:161], v[216:219], v[96:99]
	v_mfma_f32_16x16x32_bf16 v[88:91], v[166:169], v[216:219], v[88:91]
	v_mfma_f32_16x16x32_bf16 v[80:83], v[158:161], v[224:227], v[80:83]
	v_mfma_f32_16x16x32_bf16 v[72:75], v[166:169], v[224:227], v[72:75]
	s_setprio 0
	s_setprio 1
	v_mfma_f32_16x16x32_bf16 v[116:119], v[180:183], v[196:199], v[116:119]
	v_mfma_f32_16x16x32_bf16 v[108:111], v[188:191], v[196:199], v[108:111]
	v_mfma_f32_16x16x32_bf16 v[100:103], v[180:183], v[204:207], v[100:103]
	v_mfma_f32_16x16x32_bf16 v[92:95], v[188:191], v[204:207], v[92:95]
	v_mfma_f32_16x16x32_bf16 v[84:87], v[180:183], v[212:215], v[84:87]
	v_mfma_f32_16x16x32_bf16 v[76:79], v[188:191], v[212:215], v[76:79]
	v_mfma_f32_16x16x32_bf16 v[68:71], v[180:183], v[220:223], v[68:71]
	v_mfma_f32_16x16x32_bf16 v[64:67], v[188:191], v[220:223], v[64:67]
	v_mfma_f32_16x16x32_bf16 v[116:119], v[184:187], v[200:203], v[116:119]
	v_mfma_f32_16x16x32_bf16 v[108:111], v[192:195], v[200:203], v[108:111]
	v_mfma_f32_16x16x32_bf16 v[100:103], v[184:187], v[208:211], v[100:103]
	v_mfma_f32_16x16x32_bf16 v[92:95], v[192:195], v[208:211], v[92:95]
	v_mfma_f32_16x16x32_bf16 v[84:87], v[184:187], v[216:219], v[84:87]
	v_mfma_f32_16x16x32_bf16 v[76:79], v[192:195], v[216:219], v[76:79]
	v_mfma_f32_16x16x32_bf16 v[68:71], v[184:187], v[224:227], v[68:71]
	v_mfma_f32_16x16x32_bf16 v[64:67], v[192:195], v[224:227], v[64:67]
	s_setprio 0
	s_barrier
	s_add_i32 s49, s35, s28
	v_lshl_add_u64 v[170:171], s[22:23], 0, v[132:133]
	s_mov_b32 m0, s49
	ds_read_b128 v[196:199], v156 offset:16384
	ds_read_b128 v[200:203], v156 offset:17408
	ds_read_b128 v[204:207], v156 offset:18432
	ds_read_b128 v[208:211], v156 offset:19456
	ds_read_b128 v[212:215], v156 offset:20480
	ds_read_b128 v[216:219], v156 offset:21504
	ds_read_b128 v[220:223], v156 offset:22528
	ds_read_b128 v[224:227], v156 offset:23552
	global_load_lds_dwordx4 v[170:171], off
	s_add_i32 m0, s49, 0x2000
	s_add_u32 s50, s22, 0x80000
	v_lshl_add_u64 v[228:229], s[22:23], 0, v[136:137]
	s_addc_u32 s51, s23, 0
	s_add_i32 s49, s36, s28
	global_load_lds_dwordx4 v[228:229], off
	v_lshl_add_u64 v[230:231], s[50:51], 0, v[132:133]
	s_mov_b32 m0, s49
	v_lshl_add_u64 v[232:233], s[24:25], 0, v[134:135]
	global_load_lds_dwordx4 v[230:231], off
	v_lshl_add_u64 v[230:231], s[50:51], 0, v[136:137]
	s_add_i32 m0, s49, 0x2000
	s_nop 0
	global_load_lds_dwordx4 v[230:231], off
	v_lshl_add_u64 v[230:231], s[24:25], 0, v[130:131]
	s_waitcnt vmcnt(6)
	s_waitcnt lgkmcnt(0)
	s_barrier
; #define PG8_STAGE(bufoff, gbase, voff) do { _Pragma("unroll") for (int _i = 0; _i < 2; ++_i) \
;         __builtin_amdgcn_global_load_lds((const unsigned*)((const char*)(gbase) + (voff)[_i]), (PG8_LAS unsigned*)(lds + (bufoff) + ldsw + _i * 8192), 16, 0, 0); } while (0)
; #define PG8_LDA(dst, b, h) do { _Pragma("unroll") for (int m = 0; m < 4; ++m) _Pragma("unroll") for (int k = 0; k < 2; ++k) dst[m][k] = *(const PG8_LAS bf16x8*)(lds + PG8_SA(b, h) + aoff + m * 2048 + k * 1024); } while (0)
; #define PG8_LDB(dst, b, h) do { _Pragma("unroll") for (int n = 0; n < 2; ++n) _Pragma("unroll") for (int k = 0; k < 2; ++k) dst[n][k] = *(const PG8_LAS bf16x8*)(lds + PG8_SB(b, h) + boff + n * 2048 + k * 1024); } while (0)
; #define PG8_MMA(ai, bj, At, Bt) do { __builtin_amdgcn_s_setprio(1); _Pragma("unroll") for (int m = 0; m < 4; ++m) _Pragma("unroll") for (int n = 0; n < 2; ++n) _Pragma("unroll") for (int k = 0; k < 2; ++k) \
;         acc[ai][bj][m][n] = __builtin_amdgcn_mfma_f32_16x16x32_bf16(Bt[n][k], At[m][k], acc[ai][bj][m][n], 0, 0, 0); __builtin_amdgcn_s_setprio(0); } while (0)
; #define PG8_WAIT_V(n) asm volatile("s_waitcnt vmcnt(" #n ")" ::: "memory")
; #define PG8_WAIT_L(n) asm volatile("s_waitcnt lgkmcnt(" #n ")" ::: "memory")
; #define PG8_BAR __builtin_amdgcn_s_barrier()
; #define PG8_SCHED __builtin_amdgcn_sched_barrier(0)
; template <class Epi, class Sched, bool ALIGN_EPI = false, bool SP2 = false>
; __device__ __forceinline__ void gemm_phase(PG8_LAS unsigned char* lds, const Gemm g, const Sched& S, const Epi& E) {
;     ...
;             PG8_WAIT_V(8); PG8_WAIT_L(0); PG8_BAR; PG8_MMA(1, 0, At, B0); PG8_MMA(1, 1, At, B1); PG8_BAR; PG8_SCHED;
;             PG8_LDB(B0, 1, 0); PG8_LDB(B1, 1, 1); PG8_SCHED; PG8_LDA(At, 1, 0); PG8_STAGE(PG8_SA(0, 1), a2 + hstep, voffA);
;             PG8_WAIT_V(8); PG8_WAIT_L(0); PG8_BAR; PG8_MMA(0, 0, At, B0); PG8_MMA(0, 1, At, B1); PG8_BAR; PG8_SCHED;
	s_setprio 1
	s_waitcnt lgkmcnt(0)
	v_mfma_f32_16x16x32_bf16 v[60:63], v[146:149], v[196:199], v[60:63]
	v_mfma_f32_16x16x32_bf16 v[56:59], v[162:165], v[196:199], v[56:59]
	v_mfma_f32_16x16x32_bf16 v[52:55], v[146:149], v[204:207], v[52:55]
	v_mfma_f32_16x16x32_bf16 v[44:47], v[162:165], v[204:207], v[44:47]
	v_mfma_f32_16x16x32_bf16 v[36:39], v[146:149], v[212:215], v[36:39]
	v_mfma_f32_16x16x32_bf16 v[28:31], v[162:165], v[212:215], v[28:31]
	v_mfma_f32_16x16x32_bf16 v[20:23], v[146:149], v[220:223], v[20:23]
	v_mfma_f32_16x16x32_bf16 v[12:15], v[162:165], v[220:223], v[12:15]
	v_mfma_f32_16x16x32_bf16 v[60:63], v[158:161], v[200:203], v[60:63]
	v_mfma_f32_16x16x32_bf16 v[56:59], v[166:169], v[200:203], v[56:59]
	v_mfma_f32_16x16x32_bf16 v[52:55], v[158:161], v[208:211], v[52:55]
	v_mfma_f32_16x16x32_bf16 v[44:47], v[166:169], v[208:211], v[44:47]
	v_mfma_f32_16x16x32_bf16 v[36:39], v[158:161], v[216:219], v[36:39]
	v_mfma_f32_16x16x32_bf16 v[28:31], v[166:169], v[216:219], v[28:31]
	v_mfma_f32_16x16x32_bf16 v[20:23], v[158:161], v[224:227], v[20:23]
	v_mfma_f32_16x16x32_bf16 v[12:15], v[166:169], v[224:227], v[12:15]
	s_setprio 0
	s_setprio 1
	v_mfma_f32_16x16x32_bf16 v[48:51], v[180:183], v[196:199], v[48:51]
	v_mfma_f32_16x16x32_bf16 v[40:43], v[188:191], v[196:199], v[40:43]
	v_mfma_f32_16x16x32_bf16 v[32:35], v[180:183], v[204:207], v[32:35]
	v_mfma_f32_16x16x32_bf16 v[24:27], v[188:191], v[204:207], v[24:27]
	v_mfma_f32_16x16x32_bf16 v[16:19], v[180:183], v[212:215], v[16:19]
	v_mfma_f32_16x16x32_bf16 v[8:11], v[188:191], v[212:215], v[8:11]
	v_mfma_f32_16x16x32_bf16 v[4:7], v[180:183], v[220:223], v[4:7]
	v_mfma_f32_16x16x32_bf16 v[0:3], v[188:191], v[220:223], v[0:3]
	v_mfma_f32_16x16x32_bf16 v[48:51], v[184:187], v[200:203], v[48:51]
	v_mfma_f32_16x16x32_bf16 v[40:43], v[192:195], v[200:203], v[40:43]
	v_mfma_f32_16x16x32_bf16 v[32:35], v[184:187], v[208:211], v[32:35]
	v_mfma_f32_16x16x32_bf16 v[24:27], v[192:195], v[208:211], v[24:27]
	v_mfma_f32_16x16x32_bf16 v[16:19], v[184:187], v[216:219], v[16:19]
	v_mfma_f32_16x16x32_bf16 v[8:11], v[192:195], v[216:219], v[8:11]
	v_mfma_f32_16x16x32_bf16 v[4:7], v[184:187], v[224:227], v[4:7]
	v_mfma_f32_16x16x32_bf16 v[0:3], v[192:195], v[224:227], v[0:3]
	s_setprio 0
	s_barrier
	s_add_i32 s49, 0, 0x18000
	v_add_u32_e32 v157, s49, v151
	s_add_i32 s50, 0, 0x1c000
	ds_read_b128 v[146:149], v157
	ds_read_b128 v[158:161], v157 offset:1024
	ds_read_b128 v[162:165], v157 offset:2048
	ds_read_b128 v[166:169], v157 offset:3072
	v_add_u32_e32 v157, s50, v151
	ds_read_b128 v[180:183], v157
	ds_read_b128 v[184:187], v157 offset:1024
	ds_read_b128 v[188:191], v157 offset:2048
	ds_read_b128 v[192:195], v157 offset:3072
	s_add_u32 s24, s24, 0x80000
	s_addc_u32 s25, s25, 0
	s_mov_b32 m0, s17
	s_nop 0
	global_load_lds_dwordx4 v[230:231], off
	s_mov_b32 m0, s29
	s_nop 0
	global_load_lds_dwordx4 v[232:233], off
	s_mov_b32 m0, s30
	v_lshl_add_u64 v[234:235], s[24:25], 0, v[130:131]
	ds_read_b128 v[196:199], v156 offset:32768
	ds_read_b128 v[200:203], v156 offset:33792
	ds_read_b128 v[204:207], v156 offset:34816
	ds_read_b128 v[208:211], v156 offset:35840
	ds_read_b128 v[212:215], v156 offset:36864
	ds_read_b128 v[216:219], v156 offset:37888
	ds_read_b128 v[220:223], v156 offset:38912
	ds_read_b128 v[224:227], v156 offset:39936
	global_load_lds_dwordx4 v[234:235], off
	v_lshl_add_u64 v[234:235], s[24:25], 0, v[134:135]
	s_mov_b32 m0, s31
	s_nop 0
	global_load_lds_dwordx4 v[234:235], off
	s_waitcnt vmcnt(8)
	s_waitcnt lgkmcnt(0)
	s_barrier
	s_setprio 1
	s_waitcnt lgkmcnt(0)
	v_mfma_f32_16x16x32_bf16 v[124:127], v[146:149], v[196:199], v[124:127]
	v_mfma_f32_16x16x32_bf16 v[120:123], v[162:165], v[196:199], v[120:123]
	v_mfma_f32_16x16x32_bf16 v[112:115], v[146:149], v[204:207], v[112:115]
	v_mfma_f32_16x16x32_bf16 v[104:107], v[162:165], v[204:207], v[104:107]
	v_mfma_f32_16x16x32_bf16 v[96:99], v[146:149], v[212:215], v[96:99]
	v_mfma_f32_16x16x32_bf16 v[88:91], v[162:165], v[212:215], v[88:91]
	v_mfma_f32_16x16x32_bf16 v[80:83], v[146:149], v[220:223], v[80:83]
	v_mfma_f32_16x16x32_bf16 v[72:75], v[162:165], v[220:223], v[72:75]
	v_mfma_f32_16x16x32_bf16 v[124:127], v[158:161], v[200:203], v[124:127]
	v_mfma_f32_16x16x32_bf16 v[120:123], v[166:169], v[200:203], v[120:123]
	v_mfma_f32_16x16x32_bf16 v[112:115], v[158:161], v[208:211], v[112:115]
	v_mfma_f32_16x16x32_bf16 v[104:107], v[166:169], v[208:211], v[104:107]
	v_mfma_f32_16x16x32_bf16 v[96:99], v[158:161], v[216:219], v[96:99]
	v_mfma_f32_16x16x32_bf16 v[88:91], v[166:169], v[216:219], v[88:91]
	v_mfma_f32_16x16x32_bf16 v[80:83], v[158:161], v[224:227], v[80:83]
	v_mfma_f32_16x16x32_bf16 v[72:75], v[166:169], v[224:227], v[72:75]
	s_setprio 0
	s_setprio 1
	v_mfma_f32_16x16x32_bf16 v[116:119], v[180:183], v[196:199], v[116:119]
	v_mfma_f32_16x16x32_bf16 v[108:111], v[188:191], v[196:199], v[108:111]
	v_mfma_f32_16x16x32_bf16 v[100:103], v[180:183], v[204:207], v[100:103]
	v_mfma_f32_16x16x32_bf16 v[92:95], v[188:191], v[204:207], v[92:95]
	v_mfma_f32_16x16x32_bf16 v[84:87], v[180:183], v[212:215], v[84:87]
	v_mfma_f32_16x16x32_bf16 v[76:79], v[188:191], v[212:215], v[76:79]
	v_mfma_f32_16x16x32_bf16 v[68:71], v[180:183], v[220:223], v[68:71]
	v_mfma_f32_16x16x32_bf16 v[64:67], v[188:191], v[220:223], v[64:67]
	v_mfma_f32_16x16x32_bf16 v[116:119], v[184:187], v[200:203], v[116:119]
	v_mfma_f32_16x16x32_bf16 v[108:111], v[192:195], v[200:203], v[108:111]
	v_mfma_f32_16x16x32_bf16 v[100:103], v[184:187], v[208:211], v[100:103]
	v_mfma_f32_16x16x32_bf16 v[92:95], v[192:195], v[208:211], v[92:95]
	v_mfma_f32_16x16x32_bf16 v[84:87], v[184:187], v[216:219], v[84:87]
	v_mfma_f32_16x16x32_bf16 v[76:79], v[192:195], v[216:219], v[76:79]
	v_mfma_f32_16x16x32_bf16 v[68:71], v[184:187], v[224:227], v[68:71]
	v_mfma_f32_16x16x32_bf16 v[64:67], v[192:195], v[224:227], v[64:67]
	s_setprio 0
	s_barrier
; #define PG8_STAGE(bufoff, gbase, voff) do { _Pragma("unroll") for (int _i = 0; _i < 2; ++_i) \
;         __builtin_amdgcn_global_load_lds((const unsigned*)((const char*)(gbase) + (voff)[_i]), (PG8_LAS unsigned*)(lds + (bufoff) + ldsw + _i * 8192), 16, 0, 0); } while (0)
; #define PG8_LDA(dst, b, h) do { _Pragma("unroll") for (int m = 0; m < 4; ++m) _Pragma("unroll") for (int k = 0; k < 2; ++k) dst[m][k] = *(const PG8_LAS bf16x8*)(lds + PG8_SA(b, h) + aoff + m * 2048 + k * 1024); } while (0)
; #define PG8_MMA(ai, bj, At, Bt) do { __builtin_amdgcn_s_setprio(1); _Pragma("unroll") for (int m = 0; m < 4; ++m) _Pragma("unroll") for (int n = 0; n < 2; ++n) _Pragma("unroll") for (int k = 0; k < 2; ++k) \
;         acc[ai][bj][m][n] = __builtin_amdgcn_mfma_f32_16x16x32_bf16(Bt[n][k], At[m][k], acc[ai][bj][m][n], 0, 0, 0); __builtin_amdgcn_s_setprio(0); } while (0)
; #define PG8_WAIT_V(n) asm volatile("s_waitcnt vmcnt(" #n ")" ::: "memory")
; #define PG8_WAIT_L(n) asm volatile("s_waitcnt lgkmcnt(" #n ")" ::: "memory")
; #define PG8_BAR __builtin_amdgcn_s_barrier()
; #define PG8_SCHED __builtin_amdgcn_sched_barrier(0)
; template <class Epi, class Sched, bool ALIGN_EPI = false, bool SP2 = false>
; __device__ __forceinline__ void gemm_phase(PG8_LAS unsigned char* lds, const Gemm g, const Sched& S, const Epi& E) {
;     ...
;             PG8_LDA(At, 1, 1); PG8_STAGE(PG8_SB(1, 0), b3, voffB); PG8_STAGE(PG8_SB(1, 1), b3 + hstep, voffB); PG8_STAGE(PG8_SA(1, 0), a3, voffA);
;             PG8_WAIT_V(8); PG8_WAIT_L(0); PG8_BAR; PG8_MMA(1, 0, At, B0); PG8_MMA(1, 1, At, B1); PG8_BAR; PG8_SCHED;
	s_add_i32 s24, s49, s28
	v_lshl_add_u64 v[170:171], v[170:171], 0, s[2:3]
	s_mov_b32 m0, s24
	ds_read_b128 v[196:199], v156 offset:49152
	ds_read_b128 v[200:203], v156 offset:50176
	ds_read_b128 v[204:207], v156 offset:51200
	ds_read_b128 v[208:211], v156 offset:52224
	ds_read_b128 v[212:215], v156 offset:53248
	ds_read_b128 v[216:219], v156 offset:54272
	ds_read_b128 v[220:223], v156 offset:55296
	ds_read_b128 v[224:227], v156 offset:56320
	global_load_lds_dwordx4 v[170:171], off
	s_add_i32 m0, s24, 0x2000
	s_add_u32 s22, s22, 0x80080
	v_lshl_add_u64 v[170:171], v[228:229], 0, s[2:3]
	s_addc_u32 s23, s23, 0
	s_add_i32 s24, s50, s28
	global_load_lds_dwordx4 v[170:171], off
	v_lshl_add_u64 v[170:171], s[22:23], 0, v[132:133]
	s_mov_b32 m0, s24
	s_nop 0
	global_load_lds_dwordx4 v[170:171], off
	v_lshl_add_u64 v[170:171], s[22:23], 0, v[136:137]
	s_add_i32 m0, s24, 0x2000
	s_nop 0
	global_load_lds_dwordx4 v[170:171], off
	v_lshl_add_u64 v[170:171], v[230:231], 0, s[2:3]
	v_lshl_add_u64 v[170:171], v[232:233], 0, s[2:3]
	s_waitcnt vmcnt(6)
	s_waitcnt lgkmcnt(0)
	s_barrier
	s_setprio 1
	s_waitcnt lgkmcnt(0)
	v_mfma_f32_16x16x32_bf16 v[60:63], v[146:149], v[196:199], v[60:63]
	v_mfma_f32_16x16x32_bf16 v[56:59], v[162:165], v[196:199], v[56:59]
	v_mfma_f32_16x16x32_bf16 v[52:55], v[146:149], v[204:207], v[52:55]
	v_mfma_f32_16x16x32_bf16 v[44:47], v[162:165], v[204:207], v[44:47]
	v_mfma_f32_16x16x32_bf16 v[36:39], v[146:149], v[212:215], v[36:39]
	v_mfma_f32_16x16x32_bf16 v[28:31], v[162:165], v[212:215], v[28:31]
	v_mfma_f32_16x16x32_bf16 v[20:23], v[146:149], v[220:223], v[20:23]
	v_mfma_f32_16x16x32_bf16 v[12:15], v[162:165], v[220:223], v[12:15]
	v_mfma_f32_16x16x32_bf16 v[60:63], v[158:161], v[200:203], v[60:63]
	v_mfma_f32_16x16x32_bf16 v[56:59], v[166:169], v[200:203], v[56:59]
	v_mfma_f32_16x16x32_bf16 v[52:55], v[158:161], v[208:211], v[52:55]
	v_mfma_f32_16x16x32_bf16 v[44:47], v[166:169], v[208:211], v[44:47]
	v_mfma_f32_16x16x32_bf16 v[36:39], v[158:161], v[216:219], v[36:39]
	v_mfma_f32_16x16x32_bf16 v[28:31], v[166:169], v[216:219], v[28:31]
	v_mfma_f32_16x16x32_bf16 v[20:23], v[158:161], v[224:227], v[20:23]
	v_mfma_f32_16x16x32_bf16 v[12:15], v[166:169], v[224:227], v[12:15]
	s_setprio 0
	s_setprio 1
	v_mfma_f32_16x16x32_bf16 v[48:51], v[180:183], v[196:199], v[48:51]
	v_mfma_f32_16x16x32_bf16 v[40:43], v[188:191], v[196:199], v[40:43]
	v_mfma_f32_16x16x32_bf16 v[32:35], v[180:183], v[204:207], v[32:35]
	v_mfma_f32_16x16x32_bf16 v[24:27], v[188:191], v[204:207], v[24:27]
	v_mfma_f32_16x16x32_bf16 v[16:19], v[180:183], v[212:215], v[16:19]
	v_mfma_f32_16x16x32_bf16 v[8:11], v[188:191], v[212:215], v[8:11]
	v_mfma_f32_16x16x32_bf16 v[4:7], v[180:183], v[220:223], v[4:7]
	v_mfma_f32_16x16x32_bf16 v[0:3], v[188:191], v[220:223], v[0:3]
	v_mfma_f32_16x16x32_bf16 v[48:51], v[184:187], v[200:203], v[48:51]
	v_mfma_f32_16x16x32_bf16 v[40:43], v[192:195], v[200:203], v[40:43]
	v_mfma_f32_16x16x32_bf16 v[32:35], v[184:187], v[208:211], v[32:35]
	v_mfma_f32_16x16x32_bf16 v[24:27], v[192:195], v[208:211], v[24:27]
	v_mfma_f32_16x16x32_bf16 v[16:19], v[184:187], v[216:219], v[16:19]
	v_mfma_f32_16x16x32_bf16 v[8:11], v[192:195], v[216:219], v[8:11]
	v_mfma_f32_16x16x32_bf16 v[4:7], v[184:187], v[224:227], v[4:7]
	v_mfma_f32_16x16x32_bf16 v[0:3], v[192:195], v[224:227], v[0:3]
	s_setprio 0
	s_barrier
	s_add_i32 s48, s48, 2
	s_add_u32 s20, s20, 0x100
	s_addc_u32 s21, s21, 0
	s_add_u32 s46, s46, 0x100
	s_addc_u32 s47, s47, 0
	s_cmp_gt_u32 s48, 29
	s_cbranch_scc0 .LBB0_1181
	s_and_b64 vcc, exec, s[4:5]
	s_cbranch_vccz .LBB0_1184
	s_barrier

; #define PG8_STAGE(bufoff, gbase, voff) do { _Pragma("unroll") for (int _i = 0; _i < 2; ++_i) \
;         __builtin_amdgcn_global_load_lds((const unsigned*)((const char*)(gbase) + (voff)[_i]), (PG8_LAS unsigned*)(lds + (bufoff) + ldsw + _i * 8192), 16, 0, 0); } while (0)
; #define PG8_LDA(dst, b, h) do { _Pragma("unroll") for (int m = 0; m < 4; ++m) _Pragma("unroll") for (int k = 0; k < 2; ++k) dst[m][k] = *(const PG8_LAS bf16x8*)(lds + PG8_SA(b, h) + aoff + m * 2048 + k * 1024); } while (0)
; #define PG8_LDB(dst, b, h) do { _Pragma("unroll") for (int n = 0; n < 2; ++n) _Pragma("unroll") for (int k = 0; k < 2; ++k) dst[n][k] = *(const PG8_LAS bf16x8*)(lds + PG8_SB(b, h) + boff + n * 2048 + k * 1024); } while (0)
; #define PG8_MMA(ai, bj, At, Bt) do { __builtin_amdgcn_s_setprio(1); _Pragma("unroll") for (int m = 0; m < 4; ++m) _Pragma("unroll") for (int n = 0; n < 2; ++n) _Pragma("unroll") for (int k = 0; k < 2; ++k) \
;         acc[ai][bj][m][n] = __builtin_amdgcn_mfma_f32_16x16x32_bf16(Bt[n][k], At[m][k], acc[ai][bj][m][n], 0, 0, 0); __builtin_amdgcn_s_setprio(0); } while (0)
; #define PG8_WAIT_V(n) asm volatile("s_waitcnt vmcnt(" #n ")" ::: "memory")
; #define PG8_WAIT_L(n) asm volatile("s_waitcnt lgkmcnt(" #n ")" ::: "memory")
; #define PG8_BAR __builtin_amdgcn_s_barrier()
; #define PG8_SCHED __builtin_amdgcn_sched_barrier(0)
; template <class Epi, class Sched, bool ALIGN_EPI = false, bool SP2 = false>
; __device__ __forceinline__ void gemm_phase(PG8_LAS unsigned char* lds, const Gemm g, const Sched& S, const Epi& E) {
;     ...
;             PG8_LDB(B0, 0, 0); PG8_LDB(B1, 0, 1); PG8_SCHED; PG8_LDA(At, 0, 0); PG8_STAGE(PG8_SA(1, 1), a1 + hstep, voffA);
;             PG8_WAIT_V(8); PG8_WAIT_L(0); PG8_BAR; PG8_MMA(0, 0, At, B0); PG8_MMA(0, 1, At, B1); PG8_BAR; PG8_SCHED;
;             PG8_LDA(At, 0, 1); PG8_STAGE(PG8_SB(0, 0), b2, voffB); PG8_STAGE(PG8_SB(0, 1), b2 + hstep, voffB); PG8_STAGE(PG8_SA(0, 0), a2, voffA);
.LBB0_1457:
	ds_read_b128 v[142:145], v151
	ds_read_b128 v[154:157], v151 offset:1024
	ds_read_b128 v[158:161], v151 offset:2048
	ds_read_b128 v[162:165], v151 offset:3072
	ds_read_b128 v[166:169], v152
	ds_read_b128 v[178:181], v152 offset:1024
	ds_read_b128 v[182:185], v152 offset:2048
	ds_read_b128 v[186:189], v152 offset:3072
	s_add_u32 s24, s22, 0x100
	s_addc_u32 s25, s23, 0
	s_cmp_eq_u32 s47, 28
	s_cselect_b32 s29, s15, s25
	s_cselect_b32 s28, s21, s24
	s_cselect_b32 s27, s13, s46
	s_cselect_b32 s26, s44, s45
	s_mov_b32 s60, 0xfff80000
	s_mov_b32 s61, -1
	v_lshl_add_u64 v[146:147], s[22:23], 0, v[134:135]
	v_lshl_add_u64 v[146:147], v[146:147], 0, s[60:61]
	s_mov_b32 m0, s39
	s_nop 0
	global_load_lds_dwordx4 v[146:147], off
	v_lshl_add_u64 v[146:147], s[22:23], 0, v[136:137]
	v_lshl_add_u64 v[146:147], v[146:147], 0, s[60:61]
	s_mov_b32 m0, s40
	s_nop 0
	global_load_lds_dwordx4 v[146:147], off
	v_lshl_add_u64 v[146:147], s[22:23], 0, v[134:135]
	s_add_i32 m0, s34, 0xc000
	ds_read_b128 v[190:193], v153
	ds_read_b128 v[194:197], v153 offset:1024
	ds_read_b128 v[198:201], v153 offset:2048
	ds_read_b128 v[202:205], v153 offset:3072
	ds_read_b128 v[206:209], v153 offset:4096
	ds_read_b128 v[210:213], v153 offset:5120
	ds_read_b128 v[214:217], v153 offset:6144
	ds_read_b128 v[218:221], v153 offset:7168
	global_load_lds_dwordx4 v[146:147], off
	v_lshl_add_u64 v[146:147], s[22:23], 0, v[136:137]
	s_add_i32 m0, s34, 0xe000
	s_nop 0
	global_load_lds_dwordx4 v[146:147], off
	s_waitcnt vmcnt(8)
	s_waitcnt lgkmcnt(0)
	s_barrier
	s_setprio 1
	s_waitcnt lgkmcnt(0)
	v_mfma_f32_16x16x32_bf16 v[124:127], v[142:145], v[190:193], v[124:127]
	v_mfma_f32_16x16x32_bf16 v[120:123], v[158:161], v[190:193], v[120:123]
	v_mfma_f32_16x16x32_bf16 v[108:111], v[142:145], v[198:201], v[108:111]
	v_mfma_f32_16x16x32_bf16 v[104:107], v[158:161], v[198:201], v[104:107]
	v_mfma_f32_16x16x32_bf16 v[92:95], v[142:145], v[206:209], v[92:95]
	v_mfma_f32_16x16x32_bf16 v[88:91], v[158:161], v[206:209], v[88:91]
	v_mfma_f32_16x16x32_bf16 v[76:79], v[142:145], v[214:217], v[76:79]
	v_mfma_f32_16x16x32_bf16 v[72:75], v[158:161], v[214:217], v[72:75]
	v_mfma_f32_16x16x32_bf16 v[124:127], v[154:157], v[194:197], v[124:127]
	v_mfma_f32_16x16x32_bf16 v[120:123], v[162:165], v[194:197], v[120:123]
	v_mfma_f32_16x16x32_bf16 v[108:111], v[154:157], v[202:205], v[108:111]
	v_mfma_f32_16x16x32_bf16 v[104:107], v[162:165], v[202:205], v[104:107]
	v_mfma_f32_16x16x32_bf16 v[92:95], v[154:157], v[210:213], v[92:95]
	v_mfma_f32_16x16x32_bf16 v[88:91], v[162:165], v[210:213], v[88:91]
	v_mfma_f32_16x16x32_bf16 v[76:79], v[154:157], v[218:221], v[76:79]
	v_mfma_f32_16x16x32_bf16 v[72:75], v[162:165], v[218:221], v[72:75]
	s_setprio 0
	s_setprio 1
	v_mfma_f32_16x16x32_bf16 v[116:119], v[166:169], v[190:193], v[116:119]
	v_mfma_f32_16x16x32_bf16 v[112:115], v[182:185], v[190:193], v[112:115]
	v_mfma_f32_16x16x32_bf16 v[100:103], v[166:169], v[198:201], v[100:103]
	v_mfma_f32_16x16x32_bf16 v[96:99], v[182:185], v[198:201], v[96:99]
	v_mfma_f32_16x16x32_bf16 v[84:87], v[166:169], v[206:209], v[84:87]
	v_mfma_f32_16x16x32_bf16 v[80:83], v[182:185], v[206:209], v[80:83]
	v_mfma_f32_16x16x32_bf16 v[68:71], v[166:169], v[214:217], v[68:71]
	v_mfma_f32_16x16x32_bf16 v[64:67], v[182:185], v[214:217], v[64:67]
	v_mfma_f32_16x16x32_bf16 v[116:119], v[178:181], v[194:197], v[116:119]
	v_mfma_f32_16x16x32_bf16 v[112:115], v[186:189], v[194:197], v[112:115]
	v_mfma_f32_16x16x32_bf16 v[100:103], v[178:181], v[202:205], v[100:103]
	v_mfma_f32_16x16x32_bf16 v[96:99], v[186:189], v[202:205], v[96:99]
	v_mfma_f32_16x16x32_bf16 v[84:87], v[178:181], v[210:213], v[84:87]
	v_mfma_f32_16x16x32_bf16 v[80:83], v[186:189], v[210:213], v[80:83]
	v_mfma_f32_16x16x32_bf16 v[68:71], v[178:181], v[218:221], v[68:71]
	v_mfma_f32_16x16x32_bf16 v[64:67], v[186:189], v[218:221], v[64:67]
	s_setprio 0
	s_barrier
	s_add_i32 s22, s41, s33
	v_lshl_add_u64 v[146:147], s[26:27], 0, v[130:131]
	s_mov_b32 m0, s22
	ds_read_b128 v[190:193], v153 offset:16384
	ds_read_b128 v[194:197], v153 offset:17408
	ds_read_b128 v[198:201], v153 offset:18432
	ds_read_b128 v[202:205], v153 offset:19456
	ds_read_b128 v[206:209], v153 offset:20480
	ds_read_b128 v[210:213], v153 offset:21504
	ds_read_b128 v[214:217], v153 offset:22528
	ds_read_b128 v[218:221], v153 offset:23552
	global_load_lds_dwordx4 v[146:147], off
	s_add_i32 m0, s22, 0x2000
	s_add_u32 s22, s26, 0x80000
	v_lshl_add_u64 v[170:171], s[26:27], 0, v[132:133]
	s_addc_u32 s23, s27, 0
	s_add_i32 s48, s42, s33
	global_load_lds_dwordx4 v[170:171], off
	v_lshl_add_u64 v[222:223], s[22:23], 0, v[130:131]
	s_mov_b32 m0, s48
	v_lshl_add_u64 v[224:225], s[28:29], 0, v[132:133]
	global_load_lds_dwordx4 v[222:223], off
	v_lshl_add_u64 v[222:223], s[22:23], 0, v[132:133]
	s_add_i32 m0, s48, 0x2000
	s_nop 0
	global_load_lds_dwordx4 v[222:223], off
	v_lshl_add_u64 v[222:223], s[28:29], 0, v[130:131]
	s_waitcnt vmcnt(6)
	s_waitcnt lgkmcnt(0)
	s_barrier
; #define PG8_STAGE(bufoff, gbase, voff) do { _Pragma("unroll") for (int _i = 0; _i < 2; ++_i) \
;         __builtin_amdgcn_global_load_lds((const unsigned*)((const char*)(gbase) + (voff)[_i]), (PG8_LAS unsigned*)(lds + (bufoff) + ldsw + _i * 8192), 16, 0, 0); } while (0)
; #define PG8_LDA(dst, b, h) do { _Pragma("unroll") for (int m = 0; m < 4; ++m) _Pragma("unroll") for (int k = 0; k < 2; ++k) dst[m][k] = *(const PG8_LAS bf16x8*)(lds + PG8_SA(b, h) + aoff + m * 2048 + k * 1024); } while (0)
; #define PG8_LDB(dst, b, h) do { _Pragma("unroll") for (int n = 0; n < 2; ++n) _Pragma("unroll") for (int k = 0; k < 2; ++k) dst[n][k] = *(const PG8_LAS bf16x8*)(lds + PG8_SB(b, h) + boff + n * 2048 + k * 1024); } while (0)
; #define PG8_MMA(ai, bj, At, Bt) do { __builtin_amdgcn_s_setprio(1); _Pragma("unroll") for (int m = 0; m < 4; ++m) _Pragma("unroll") for (int n = 0; n < 2; ++n) _Pragma("unroll") for (int k = 0; k < 2; ++k) \
;         acc[ai][bj][m][n] = __builtin_amdgcn_mfma_f32_16x16x32_bf16(Bt[n][k], At[m][k], acc[ai][bj][m][n], 0, 0, 0); __builtin_amdgcn_s_setprio(0); } while (0)
; #define PG8_WAIT_V(n) asm volatile("s_waitcnt vmcnt(" #n ")" ::: "memory")
; #define PG8_WAIT_L(n) asm volatile("s_waitcnt lgkmcnt(" #n ")" ::: "memory")
; #define PG8_BAR __builtin_amdgcn_s_barrier()
; #define PG8_SCHED __builtin_amdgcn_sched_barrier(0)
; template <class Epi, class Sched, bool ALIGN_EPI = false, bool SP2 = false>
; __device__ __forceinline__ void gemm_phase(PG8_LAS unsigned char* lds, const Gemm g, const Sched& S, const Epi& E) {
;     ...
;             PG8_WAIT_V(8); PG8_WAIT_L(0); PG8_BAR; PG8_MMA(1, 0, At, B0); PG8_MMA(1, 1, At, B1); PG8_BAR; PG8_SCHED;
;             PG8_LDB(B0, 1, 0); PG8_LDB(B1, 1, 1); PG8_SCHED; PG8_LDA(At, 1, 0); PG8_STAGE(PG8_SA(0, 1), a2 + hstep, voffA);
;             PG8_WAIT_V(8); PG8_WAIT_L(0); PG8_BAR; PG8_MMA(0, 0, At, B0); PG8_MMA(0, 1, At, B1); PG8_BAR; PG8_SCHED;
	s_setprio 1
	s_waitcnt lgkmcnt(0)
	v_mfma_f32_16x16x32_bf16 v[60:63], v[142:145], v[190:193], v[60:63]
	v_mfma_f32_16x16x32_bf16 v[56:59], v[158:161], v[190:193], v[56:59]
	v_mfma_f32_16x16x32_bf16 v[44:47], v[142:145], v[198:201], v[44:47]
	v_mfma_f32_16x16x32_bf16 v[40:43], v[158:161], v[198:201], v[40:43]
	v_mfma_f32_16x16x32_bf16 v[28:31], v[142:145], v[206:209], v[28:31]
	v_mfma_f32_16x16x32_bf16 v[24:27], v[158:161], v[206:209], v[24:27]
	v_mfma_f32_16x16x32_bf16 v[12:15], v[142:145], v[214:217], v[12:15]
	v_mfma_f32_16x16x32_bf16 v[8:11], v[158:161], v[214:217], v[8:11]
	v_mfma_f32_16x16x32_bf16 v[60:63], v[154:157], v[194:197], v[60:63]
	v_mfma_f32_16x16x32_bf16 v[56:59], v[162:165], v[194:197], v[56:59]
	v_mfma_f32_16x16x32_bf16 v[44:47], v[154:157], v[202:205], v[44:47]
	v_mfma_f32_16x16x32_bf16 v[40:43], v[162:165], v[202:205], v[40:43]
	v_mfma_f32_16x16x32_bf16 v[28:31], v[154:157], v[210:213], v[28:31]
	v_mfma_f32_16x16x32_bf16 v[24:27], v[162:165], v[210:213], v[24:27]
	v_mfma_f32_16x16x32_bf16 v[12:15], v[154:157], v[218:221], v[12:15]
	v_mfma_f32_16x16x32_bf16 v[8:11], v[162:165], v[218:221], v[8:11]
	s_setprio 0
	s_setprio 1
	v_mfma_f32_16x16x32_bf16 v[52:55], v[166:169], v[190:193], v[52:55]
	v_mfma_f32_16x16x32_bf16 v[48:51], v[182:185], v[190:193], v[48:51]
	v_mfma_f32_16x16x32_bf16 v[36:39], v[166:169], v[198:201], v[36:39]
	v_mfma_f32_16x16x32_bf16 v[32:35], v[182:185], v[198:201], v[32:35]
	v_mfma_f32_16x16x32_bf16 v[20:23], v[166:169], v[206:209], v[20:23]
	v_mfma_f32_16x16x32_bf16 v[16:19], v[182:185], v[206:209], v[16:19]
	v_mfma_f32_16x16x32_bf16 v[4:7], v[166:169], v[214:217], v[4:7]
	v_mfma_f32_16x16x32_bf16 v[0:3], v[182:185], v[214:217], v[0:3]
	v_mfma_f32_16x16x32_bf16 v[52:55], v[178:181], v[194:197], v[52:55]
	v_mfma_f32_16x16x32_bf16 v[48:51], v[186:189], v[194:197], v[48:51]
	v_mfma_f32_16x16x32_bf16 v[36:39], v[178:181], v[202:205], v[36:39]
	v_mfma_f32_16x16x32_bf16 v[32:35], v[186:189], v[202:205], v[32:35]
	v_mfma_f32_16x16x32_bf16 v[20:23], v[178:181], v[210:213], v[20:23]
	v_mfma_f32_16x16x32_bf16 v[16:19], v[186:189], v[210:213], v[16:19]
	v_mfma_f32_16x16x32_bf16 v[4:7], v[178:181], v[218:221], v[4:7]
	v_mfma_f32_16x16x32_bf16 v[0:3], v[186:189], v[218:221], v[0:3]
	s_setprio 0
	s_barrier
	s_add_i32 s48, 0, 0x18000
	s_add_i32 s49, 0, 0x1c000
	v_add_u32_e32 v162, s48, v149
	v_add_u32_e32 v186, s49, v149
	ds_read_b128 v[142:145], v162
	ds_read_b128 v[154:157], v162 offset:1024
	ds_read_b128 v[158:161], v162 offset:2048
	ds_read_b128 v[162:165], v162 offset:3072
	ds_read_b128 v[166:169], v186
	ds_read_b128 v[178:181], v186 offset:1024
	ds_read_b128 v[182:185], v186 offset:2048
	ds_read_b128 v[186:189], v186 offset:3072
	s_add_u32 s22, s28, 0x80000
	s_addc_u32 s23, s29, 0
	s_mov_b32 m0, s34
	s_nop 0
	global_load_lds_dwordx4 v[222:223], off
	s_mov_b32 m0, s35
	s_nop 0
	global_load_lds_dwordx4 v[224:225], off
	s_mov_b32 m0, s36
	v_lshl_add_u64 v[226:227], s[22:23], 0, v[130:131]
	ds_read_b128 v[190:193], v153 offset:32768
	ds_read_b128 v[194:197], v153 offset:33792
	ds_read_b128 v[198:201], v153 offset:34816
	ds_read_b128 v[202:205], v153 offset:35840
	ds_read_b128 v[206:209], v153 offset:36864
	ds_read_b128 v[210:213], v153 offset:37888
	ds_read_b128 v[214:217], v153 offset:38912
	ds_read_b128 v[218:221], v153 offset:39936
	global_load_lds_dwordx4 v[226:227], off
	v_lshl_add_u64 v[226:227], s[22:23], 0, v[132:133]
	s_mov_b32 m0, s37
	s_nop 0
	global_load_lds_dwordx4 v[226:227], off
	s_waitcnt vmcnt(8)
	s_waitcnt lgkmcnt(0)
	s_barrier
	s_setprio 1
	s_waitcnt lgkmcnt(0)
	v_mfma_f32_16x16x32_bf16 v[124:127], v[142:145], v[190:193], v[124:127]
	v_mfma_f32_16x16x32_bf16 v[120:123], v[158:161], v[190:193], v[120:123]
	v_mfma_f32_16x16x32_bf16 v[108:111], v[142:145], v[198:201], v[108:111]
	v_mfma_f32_16x16x32_bf16 v[104:107], v[158:161], v[198:201], v[104:107]
	v_mfma_f32_16x16x32_bf16 v[92:95], v[142:145], v[206:209], v[92:95]
	v_mfma_f32_16x16x32_bf16 v[88:91], v[158:161], v[206:209], v[88:91]
	v_mfma_f32_16x16x32_bf16 v[76:79], v[142:145], v[214:217], v[76:79]
	v_mfma_f32_16x16x32_bf16 v[72:75], v[158:161], v[214:217], v[72:75]
	v_mfma_f32_16x16x32_bf16 v[124:127], v[154:157], v[194:197], v[124:127]
	v_mfma_f32_16x16x32_bf16 v[120:123], v[162:165], v[194:197], v[120:123]
	v_mfma_f32_16x16x32_bf16 v[108:111], v[154:157], v[202:205], v[108:111]
	v_mfma_f32_16x16x32_bf16 v[104:107], v[162:165], v[202:205], v[104:107]
	v_mfma_f32_16x16x32_bf16 v[92:95], v[154:157], v[210:213], v[92:95]
	v_mfma_f32_16x16x32_bf16 v[88:91], v[162:165], v[210:213], v[88:91]
	v_mfma_f32_16x16x32_bf16 v[76:79], v[154:157], v[218:221], v[76:79]
	v_mfma_f32_16x16x32_bf16 v[72:75], v[162:165], v[218:221], v[72:75]
	s_setprio 0
	s_setprio 1
	v_mfma_f32_16x16x32_bf16 v[116:119], v[166:169], v[190:193], v[116:119]
	v_mfma_f32_16x16x32_bf16 v[112:115], v[182:185], v[190:193], v[112:115]
	v_mfma_f32_16x16x32_bf16 v[100:103], v[166:169], v[198:201], v[100:103]
	v_mfma_f32_16x16x32_bf16 v[96:99], v[182:185], v[198:201], v[96:99]
	v_mfma_f32_16x16x32_bf16 v[84:87], v[166:169], v[206:209], v[84:87]
	v_mfma_f32_16x16x32_bf16 v[80:83], v[182:185], v[206:209], v[80:83]
	v_mfma_f32_16x16x32_bf16 v[68:71], v[166:169], v[214:217], v[68:71]
	v_mfma_f32_16x16x32_bf16 v[64:67], v[182:185], v[214:217], v[64:67]
	v_mfma_f32_16x16x32_bf16 v[116:119], v[178:181], v[194:197], v[116:119]
	v_mfma_f32_16x16x32_bf16 v[112:115], v[186:189], v[194:197], v[112:115]
	v_mfma_f32_16x16x32_bf16 v[100:103], v[178:181], v[202:205], v[100:103]
	v_mfma_f32_16x16x32_bf16 v[96:99], v[186:189], v[202:205], v[96:99]
	v_mfma_f32_16x16x32_bf16 v[84:87], v[178:181], v[210:213], v[84:87]
	v_mfma_f32_16x16x32_bf16 v[80:83], v[186:189], v[210:213], v[80:83]
	v_mfma_f32_16x16x32_bf16 v[68:71], v[178:181], v[218:221], v[68:71]
	v_mfma_f32_16x16x32_bf16 v[64:67], v[186:189], v[218:221], v[64:67]
	s_setprio 0
	s_barrier
; #define PG8_STAGE(bufoff, gbase, voff) do { _Pragma("unroll") for (int _i = 0; _i < 2; ++_i) \
;         __builtin_amdgcn_global_load_lds((const unsigned*)((const char*)(gbase) + (voff)[_i]), (PG8_LAS unsigned*)(lds + (bufoff) + ldsw + _i * 8192), 16, 0, 0); } while (0)
; #define PG8_LDA(dst, b, h) do { _Pragma("unroll") for (int m = 0; m < 4; ++m) _Pragma("unroll") for (int k = 0; k < 2; ++k) dst[m][k] = *(const PG8_LAS bf16x8*)(lds + PG8_SA(b, h) + aoff + m * 2048 + k * 1024); } while (0)
; #define PG8_MMA(ai, bj, At, Bt) do { __builtin_amdgcn_s_setprio(1); _Pragma("unroll") for (int m = 0; m < 4; ++m) _Pragma("unroll") for (int n = 0; n < 2; ++n) _Pragma("unroll") for (int k = 0; k < 2; ++k) \
;         acc[ai][bj][m][n] = __builtin_amdgcn_mfma_f32_16x16x32_bf16(Bt[n][k], At[m][k], acc[ai][bj][m][n], 0, 0, 0); __builtin_amdgcn_s_setprio(0); } while (0)
; #define PG8_WAIT_V(n) asm volatile("s_waitcnt vmcnt(" #n ")" ::: "memory")
; #define PG8_WAIT_L(n) asm volatile("s_waitcnt lgkmcnt(" #n ")" ::: "memory")
; #define PG8_BAR __builtin_amdgcn_s_barrier()
; #define PG8_SCHED __builtin_amdgcn_sched_barrier(0)
; template <class Epi, class Sched, bool ALIGN_EPI = false, bool SP2 = false>
; __device__ __forceinline__ void gemm_phase(PG8_LAS unsigned char* lds, const Gemm g, const Sched& S, const Epi& E) {
;     ...
;             PG8_LDA(At, 1, 1); PG8_STAGE(PG8_SB(1, 0), b3, voffB); PG8_STAGE(PG8_SB(1, 1), b3 + hstep, voffB); PG8_STAGE(PG8_SA(1, 0), a3, voffA);
;             PG8_WAIT_V(8); PG8_WAIT_L(0); PG8_BAR; PG8_MMA(1, 0, At, B0); PG8_MMA(1, 1, At, B1); PG8_BAR; PG8_SCHED;
	s_add_i32 s22, s48, s33
	v_lshl_add_u64 v[146:147], v[146:147], 0, s[4:5]
	s_mov_b32 m0, s22
	ds_read_b128 v[190:193], v153 offset:49152
	ds_read_b128 v[194:197], v153 offset:50176
	ds_read_b128 v[198:201], v153 offset:51200
	ds_read_b128 v[202:205], v153 offset:52224
	ds_read_b128 v[206:209], v153 offset:53248
	ds_read_b128 v[210:213], v153 offset:54272
	ds_read_b128 v[214:217], v153 offset:55296
	ds_read_b128 v[218:221], v153 offset:56320
	global_load_lds_dwordx4 v[146:147], off
	s_add_i32 m0, s22, 0x2000
	s_add_u32 s22, s26, 0x80080
	v_lshl_add_u64 v[146:147], v[170:171], 0, s[4:5]
	s_addc_u32 s23, s27, 0
	s_add_i32 s26, s49, s33
	global_load_lds_dwordx4 v[146:147], off
	v_lshl_add_u64 v[146:147], s[22:23], 0, v[130:131]
	s_mov_b32 m0, s26
	s_nop 0
	global_load_lds_dwordx4 v[146:147], off
	v_lshl_add_u64 v[146:147], s[22:23], 0, v[132:133]
	s_add_i32 m0, s26, 0x2000
	s_nop 0
	global_load_lds_dwordx4 v[146:147], off
	v_lshl_add_u64 v[146:147], v[222:223], 0, s[4:5]
	v_lshl_add_u64 v[146:147], v[224:225], 0, s[4:5]
	s_waitcnt vmcnt(6)
	s_waitcnt lgkmcnt(0)
	s_barrier
	s_setprio 1
	s_waitcnt lgkmcnt(0)
	v_mfma_f32_16x16x32_bf16 v[60:63], v[142:145], v[190:193], v[60:63]
	v_mfma_f32_16x16x32_bf16 v[56:59], v[158:161], v[190:193], v[56:59]
	v_mfma_f32_16x16x32_bf16 v[44:47], v[142:145], v[198:201], v[44:47]
	v_mfma_f32_16x16x32_bf16 v[40:43], v[158:161], v[198:201], v[40:43]
	v_mfma_f32_16x16x32_bf16 v[28:31], v[142:145], v[206:209], v[28:31]
	v_mfma_f32_16x16x32_bf16 v[24:27], v[158:161], v[206:209], v[24:27]
	v_mfma_f32_16x16x32_bf16 v[12:15], v[142:145], v[214:217], v[12:15]
	v_mfma_f32_16x16x32_bf16 v[8:11], v[158:161], v[214:217], v[8:11]
	v_mfma_f32_16x16x32_bf16 v[60:63], v[154:157], v[194:197], v[60:63]
	v_mfma_f32_16x16x32_bf16 v[56:59], v[162:165], v[194:197], v[56:59]
	v_mfma_f32_16x16x32_bf16 v[44:47], v[154:157], v[202:205], v[44:47]
	v_mfma_f32_16x16x32_bf16 v[40:43], v[162:165], v[202:205], v[40:43]
	v_mfma_f32_16x16x32_bf16 v[28:31], v[154:157], v[210:213], v[28:31]
	v_mfma_f32_16x16x32_bf16 v[24:27], v[162:165], v[210:213], v[24:27]
	v_mfma_f32_16x16x32_bf16 v[12:15], v[154:157], v[218:221], v[12:15]
	v_mfma_f32_16x16x32_bf16 v[8:11], v[162:165], v[218:221], v[8:11]
	s_setprio 0
	s_setprio 1
	v_mfma_f32_16x16x32_bf16 v[52:55], v[166:169], v[190:193], v[52:55]
	v_mfma_f32_16x16x32_bf16 v[48:51], v[182:185], v[190:193], v[48:51]
	v_mfma_f32_16x16x32_bf16 v[36:39], v[166:169], v[198:201], v[36:39]
	v_mfma_f32_16x16x32_bf16 v[32:35], v[182:185], v[198:201], v[32:35]
	v_mfma_f32_16x16x32_bf16 v[20:23], v[166:169], v[206:209], v[20:23]
	v_mfma_f32_16x16x32_bf16 v[16:19], v[182:185], v[206:209], v[16:19]
	v_mfma_f32_16x16x32_bf16 v[4:7], v[166:169], v[214:217], v[4:7]
	v_mfma_f32_16x16x32_bf16 v[0:3], v[182:185], v[214:217], v[0:3]
	v_mfma_f32_16x16x32_bf16 v[52:55], v[178:181], v[194:197], v[52:55]
	v_mfma_f32_16x16x32_bf16 v[48:51], v[186:189], v[194:197], v[48:51]
	v_mfma_f32_16x16x32_bf16 v[36:39], v[178:181], v[202:205], v[36:39]
	v_mfma_f32_16x16x32_bf16 v[32:35], v[186:189], v[202:205], v[32:35]
	v_mfma_f32_16x16x32_bf16 v[20:23], v[178:181], v[210:213], v[20:23]
	v_mfma_f32_16x16x32_bf16 v[16:19], v[186:189], v[210:213], v[16:19]
	v_mfma_f32_16x16x32_bf16 v[4:7], v[178:181], v[218:221], v[4:7]
	v_mfma_f32_16x16x32_bf16 v[0:3], v[186:189], v[218:221], v[0:3]
	s_setprio 0
	s_barrier
	s_add_i32 s47, s47, 2
	s_add_u32 s45, s45, 0x100
	s_addc_u32 s46, s46, 0
	s_cmp_gt_u32 s47, 29
	s_mov_b64 s[22:23], s[24:25]
	s_cbranch_scc0 .LBB0_1457
	s_and_b64 vcc, exec, s[6:7]
	s_cbranch_vccz .LBB0_1460
	s_barrier

; #define PG8_STAGE(bufoff, gbase, voff) do { _Pragma("unroll") for (int _i = 0; _i < 2; ++_i) \
;         __builtin_amdgcn_global_load_lds((const unsigned*)((const char*)(gbase) + (voff)[_i]), (PG8_LAS unsigned*)(lds + (bufoff) + ldsw + _i * 8192), 16, 0, 0); } while (0)
; #define PG8_LDA(dst, b, h) do { _Pragma("unroll") for (int m = 0; m < 4; ++m) _Pragma("unroll") for (int k = 0; k < 2; ++k) dst[m][k] = *(const PG8_LAS bf16x8*)(lds + PG8_SA(b, h) + aoff + m * 2048 + k * 1024); } while (0)
; #define PG8_LDB(dst, b, h) do { _Pragma("unroll") for (int n = 0; n < 2; ++n) _Pragma("unroll") for (int k = 0; k < 2; ++k) dst[n][k] = *(const PG8_LAS bf16x8*)(lds + PG8_SB(b, h) + boff + n * 2048 + k * 1024); } while (0)
; #define PG8_MMA(ai, bj, At, Bt) do { __builtin_amdgcn_s_setprio(1); _Pragma("unroll") for (int m = 0; m < 4; ++m) _Pragma("unroll") for (int n = 0; n < 2; ++n) _Pragma("unroll") for (int k = 0; k < 2; ++k) \
;         acc[ai][bj][m][n] = __builtin_amdgcn_mfma_f32_16x16x32_bf16(Bt[n][k], At[m][k], acc[ai][bj][m][n], 0, 0, 0); __builtin_amdgcn_s_setprio(0); } while (0)
; #define PG8_WAIT_V(n) asm volatile("s_waitcnt vmcnt(" #n ")" ::: "memory")
; #define PG8_WAIT_L(n) asm volatile("s_waitcnt lgkmcnt(" #n ")" ::: "memory")
; #define PG8_BAR __builtin_amdgcn_s_barrier()
; #define PG8_SCHED __builtin_amdgcn_sched_barrier(0)
; template <class Epi, class Sched, bool ALIGN_EPI = false, bool SP2 = false>
; __device__ __forceinline__ void gemm_phase(PG8_LAS unsigned char* lds, const Gemm g, const Sched& S, const Epi& E) {
;     ...
;             PG8_LDB(B0, 0, 0); PG8_LDB(B1, 0, 1); PG8_SCHED; PG8_LDA(At, 0, 0); PG8_STAGE(PG8_SA(1, 1), a1 + hstep, voffA);
;             PG8_WAIT_V(8); PG8_WAIT_L(0); PG8_BAR; PG8_MMA(0, 0, At, B0); PG8_MMA(0, 1, At, B1); PG8_BAR; PG8_SCHED;
;             PG8_LDA(At, 0, 1); PG8_STAGE(PG8_SB(0, 0), b2, voffB); PG8_STAGE(PG8_SB(0, 1), b2 + hstep, voffB); PG8_STAGE(PG8_SA(0, 0), a2, voffA);
.LBB0_1712:
	ds_read_b128 v[144:147], v156
	ds_read_b128 v[148:151], v156 offset:1024
	ds_read_b128 v[160:163], v156 offset:2048
	ds_read_b128 v[164:167], v156 offset:3072
	ds_read_b128 v[168:171], v157
	ds_read_b128 v[174:177], v157 offset:1024
	ds_read_b128 v[178:181], v157 offset:2048
	ds_read_b128 v[182:185], v157 offset:3072
	s_add_u32 s20, s18, 0xfff80080
	s_addc_u32 s21, s19, -1
	s_cmp_eq_u32 s44, 28
	s_cselect_b32 s23, s11, s21
	s_cselect_b32 s22, s40, s20
	s_cselect_b32 s21, s9, s43
	s_cselect_b32 s20, s41, s42
	s_mov_b32 s48, 0xfff80000
	s_mov_b32 s49, -1
	v_lshl_add_u64 v[218:219], s[18:19], 0, v[136:137]
	v_lshl_add_u64 v[218:219], v[218:219], 0, s[48:49]
	s_mov_b32 m0, s31
	s_nop 0
	global_load_lds_dwordx4 v[218:219], off
	v_lshl_add_u64 v[218:219], s[18:19], 0, v[138:139]
	v_lshl_add_u64 v[218:219], v[218:219], 0, s[48:49]
	s_mov_b32 m0, s33
	s_nop 0
	global_load_lds_dwordx4 v[218:219], off
	v_lshl_add_u64 v[218:219], s[18:19], 0, v[136:137]
	s_add_i32 m0, s17, 0xc000
	ds_read_b128 v[186:189], v158
	ds_read_b128 v[190:193], v158 offset:1024
	ds_read_b128 v[194:197], v158 offset:2048
	ds_read_b128 v[198:201], v158 offset:3072
	ds_read_b128 v[202:205], v158 offset:4096
	ds_read_b128 v[206:209], v158 offset:5120
	ds_read_b128 v[210:213], v158 offset:6144
	ds_read_b128 v[214:217], v158 offset:7168
	global_load_lds_dwordx4 v[218:219], off
	v_lshl_add_u64 v[218:219], s[18:19], 0, v[138:139]
	s_add_i32 m0, s17, 0xe000
	s_nop 0
	global_load_lds_dwordx4 v[218:219], off
	s_waitcnt vmcnt(8)
	s_waitcnt lgkmcnt(0)
	s_barrier
	s_setprio 1
	s_waitcnt lgkmcnt(0)
	v_mfma_f32_16x16x32_bf16 v[124:127], v[144:147], v[186:189], v[124:127]
	v_mfma_f32_16x16x32_bf16 v[120:123], v[160:163], v[186:189], v[120:123]
	v_mfma_f32_16x16x32_bf16 v[108:111], v[144:147], v[194:197], v[108:111]
	v_mfma_f32_16x16x32_bf16 v[104:107], v[160:163], v[194:197], v[104:107]
	v_mfma_f32_16x16x32_bf16 v[92:95], v[144:147], v[202:205], v[92:95]
	v_mfma_f32_16x16x32_bf16 v[88:91], v[160:163], v[202:205], v[88:91]
	v_mfma_f32_16x16x32_bf16 v[76:79], v[144:147], v[210:213], v[76:79]
	v_mfma_f32_16x16x32_bf16 v[72:75], v[160:163], v[210:213], v[72:75]
	v_mfma_f32_16x16x32_bf16 v[124:127], v[148:151], v[190:193], v[124:127]
	v_mfma_f32_16x16x32_bf16 v[120:123], v[164:167], v[190:193], v[120:123]
	v_mfma_f32_16x16x32_bf16 v[108:111], v[148:151], v[198:201], v[108:111]
	v_mfma_f32_16x16x32_bf16 v[104:107], v[164:167], v[198:201], v[104:107]
	v_mfma_f32_16x16x32_bf16 v[92:95], v[148:151], v[206:209], v[92:95]
	v_mfma_f32_16x16x32_bf16 v[88:91], v[164:167], v[206:209], v[88:91]
	v_mfma_f32_16x16x32_bf16 v[76:79], v[148:151], v[214:217], v[76:79]
	v_mfma_f32_16x16x32_bf16 v[72:75], v[164:167], v[214:217], v[72:75]
	s_setprio 0
	s_setprio 1
	v_mfma_f32_16x16x32_bf16 v[116:119], v[168:171], v[186:189], v[116:119]
	v_mfma_f32_16x16x32_bf16 v[112:115], v[178:181], v[186:189], v[112:115]
	v_mfma_f32_16x16x32_bf16 v[100:103], v[168:171], v[194:197], v[100:103]
	v_mfma_f32_16x16x32_bf16 v[96:99], v[178:181], v[194:197], v[96:99]
	v_mfma_f32_16x16x32_bf16 v[84:87], v[168:171], v[202:205], v[84:87]
	v_mfma_f32_16x16x32_bf16 v[80:83], v[178:181], v[202:205], v[80:83]
	v_mfma_f32_16x16x32_bf16 v[68:71], v[168:171], v[210:213], v[68:71]
	v_mfma_f32_16x16x32_bf16 v[64:67], v[178:181], v[210:213], v[64:67]
	v_mfma_f32_16x16x32_bf16 v[116:119], v[174:177], v[190:193], v[116:119]
	v_mfma_f32_16x16x32_bf16 v[112:115], v[182:185], v[190:193], v[112:115]
	v_mfma_f32_16x16x32_bf16 v[100:103], v[174:177], v[198:201], v[100:103]
	v_mfma_f32_16x16x32_bf16 v[96:99], v[182:185], v[198:201], v[96:99]
	v_mfma_f32_16x16x32_bf16 v[84:87], v[174:177], v[206:209], v[84:87]
	v_mfma_f32_16x16x32_bf16 v[80:83], v[182:185], v[206:209], v[80:83]
	v_mfma_f32_16x16x32_bf16 v[68:71], v[174:177], v[214:217], v[68:71]
	v_mfma_f32_16x16x32_bf16 v[64:67], v[182:185], v[214:217], v[64:67]
	s_setprio 0
	s_barrier
	s_add_i32 s45, s34, s26
	v_lshl_add_u64 v[218:219], s[20:21], 0, v[132:133]
	s_mov_b32 m0, s45
	ds_read_b128 v[186:189], v158 offset:16384
	ds_read_b128 v[190:193], v158 offset:17408
	ds_read_b128 v[194:197], v158 offset:18432
	ds_read_b128 v[198:201], v158 offset:19456
	ds_read_b128 v[202:205], v158 offset:20480
	ds_read_b128 v[206:209], v158 offset:21504
	ds_read_b128 v[210:213], v158 offset:22528
	ds_read_b128 v[214:217], v158 offset:23552
	global_load_lds_dwordx4 v[218:219], off
	s_add_i32 m0, s45, 0x2000
	s_add_u32 s46, s20, 0x80000
	v_lshl_add_u64 v[220:221], s[20:21], 0, v[128:129]
	s_addc_u32 s47, s21, 0
	s_add_i32 s45, s35, s26
	global_load_lds_dwordx4 v[220:221], off
	v_lshl_add_u64 v[222:223], s[46:47], 0, v[132:133]
	s_mov_b32 m0, s45
	v_lshl_add_u64 v[224:225], s[22:23], 0, v[130:131]
	global_load_lds_dwordx4 v[222:223], off
	v_lshl_add_u64 v[222:223], s[46:47], 0, v[128:129]
	s_add_i32 m0, s45, 0x2000
	s_nop 0
	global_load_lds_dwordx4 v[222:223], off
	v_lshl_add_u64 v[222:223], s[22:23], 0, v[134:135]
	s_waitcnt vmcnt(6)
	s_waitcnt lgkmcnt(0)
	s_barrier
; #define PG8_STAGE(bufoff, gbase, voff) do { _Pragma("unroll") for (int _i = 0; _i < 2; ++_i) \
;         __builtin_amdgcn_global_load_lds((const unsigned*)((const char*)(gbase) + (voff)[_i]), (PG8_LAS unsigned*)(lds + (bufoff) + ldsw + _i * 8192), 16, 0, 0); } while (0)
; #define PG8_LDA(dst, b, h) do { _Pragma("unroll") for (int m = 0; m < 4; ++m) _Pragma("unroll") for (int k = 0; k < 2; ++k) dst[m][k] = *(const PG8_LAS bf16x8*)(lds + PG8_SA(b, h) + aoff + m * 2048 + k * 1024); } while (0)
; #define PG8_LDB(dst, b, h) do { _Pragma("unroll") for (int n = 0; n < 2; ++n) _Pragma("unroll") for (int k = 0; k < 2; ++k) dst[n][k] = *(const PG8_LAS bf16x8*)(lds + PG8_SB(b, h) + boff + n * 2048 + k * 1024); } while (0)
; #define PG8_MMA(ai, bj, At, Bt) do { __builtin_amdgcn_s_setprio(1); _Pragma("unroll") for (int m = 0; m < 4; ++m) _Pragma("unroll") for (int n = 0; n < 2; ++n) _Pragma("unroll") for (int k = 0; k < 2; ++k) \
;         acc[ai][bj][m][n] = __builtin_amdgcn_mfma_f32_16x16x32_bf16(Bt[n][k], At[m][k], acc[ai][bj][m][n], 0, 0, 0); __builtin_amdgcn_s_setprio(0); } while (0)
; #define PG8_WAIT_V(n) asm volatile("s_waitcnt vmcnt(" #n ")" ::: "memory")
; #define PG8_WAIT_L(n) asm volatile("s_waitcnt lgkmcnt(" #n ")" ::: "memory")
; #define PG8_BAR __builtin_amdgcn_s_barrier()
; #define PG8_SCHED __builtin_amdgcn_sched_barrier(0)
; template <class Epi, class Sched, bool ALIGN_EPI = false, bool SP2 = false>
; __device__ __forceinline__ void gemm_phase(PG8_LAS unsigned char* lds, const Gemm g, const Sched& S, const Epi& E) {
;     ...
;             PG8_WAIT_V(8); PG8_WAIT_L(0); PG8_BAR; PG8_MMA(1, 0, At, B0); PG8_MMA(1, 1, At, B1); PG8_BAR; PG8_SCHED;
;             PG8_LDB(B0, 1, 0); PG8_LDB(B1, 1, 1); PG8_SCHED; PG8_LDA(At, 1, 0); PG8_STAGE(PG8_SA(0, 1), a2 + hstep, voffA);
;             PG8_WAIT_V(8); PG8_WAIT_L(0); PG8_BAR; PG8_MMA(0, 0, At, B0); PG8_MMA(0, 1, At, B1); PG8_BAR; PG8_SCHED;
	s_setprio 1
	s_waitcnt lgkmcnt(0)
	v_mfma_f32_16x16x32_bf16 v[60:63], v[144:147], v[186:189], v[60:63]
	v_mfma_f32_16x16x32_bf16 v[56:59], v[160:163], v[186:189], v[56:59]
	v_mfma_f32_16x16x32_bf16 v[44:47], v[144:147], v[194:197], v[44:47]
	v_mfma_f32_16x16x32_bf16 v[40:43], v[160:163], v[194:197], v[40:43]
	v_mfma_f32_16x16x32_bf16 v[28:31], v[144:147], v[202:205], v[28:31]
	v_mfma_f32_16x16x32_bf16 v[24:27], v[160:163], v[202:205], v[24:27]
	v_mfma_f32_16x16x32_bf16 v[12:15], v[144:147], v[210:213], v[12:15]
	v_mfma_f32_16x16x32_bf16 v[8:11], v[160:163], v[210:213], v[8:11]
	v_mfma_f32_16x16x32_bf16 v[60:63], v[148:151], v[190:193], v[60:63]
	v_mfma_f32_16x16x32_bf16 v[56:59], v[164:167], v[190:193], v[56:59]
	v_mfma_f32_16x16x32_bf16 v[44:47], v[148:151], v[198:201], v[44:47]
	v_mfma_f32_16x16x32_bf16 v[40:43], v[164:167], v[198:201], v[40:43]
	v_mfma_f32_16x16x32_bf16 v[28:31], v[148:151], v[206:209], v[28:31]
	v_mfma_f32_16x16x32_bf16 v[24:27], v[164:167], v[206:209], v[24:27]
	v_mfma_f32_16x16x32_bf16 v[12:15], v[148:151], v[214:217], v[12:15]
	v_mfma_f32_16x16x32_bf16 v[8:11], v[164:167], v[214:217], v[8:11]
	s_setprio 0
	s_setprio 1
	v_mfma_f32_16x16x32_bf16 v[52:55], v[168:171], v[186:189], v[52:55]
	v_mfma_f32_16x16x32_bf16 v[48:51], v[178:181], v[186:189], v[48:51]
	v_mfma_f32_16x16x32_bf16 v[36:39], v[168:171], v[194:197], v[36:39]
	v_mfma_f32_16x16x32_bf16 v[32:35], v[178:181], v[194:197], v[32:35]
	v_mfma_f32_16x16x32_bf16 v[20:23], v[168:171], v[202:205], v[20:23]
	v_mfma_f32_16x16x32_bf16 v[16:19], v[178:181], v[202:205], v[16:19]
	v_mfma_f32_16x16x32_bf16 v[4:7], v[168:171], v[210:213], v[4:7]
	v_mfma_f32_16x16x32_bf16 v[0:3], v[178:181], v[210:213], v[0:3]
	v_mfma_f32_16x16x32_bf16 v[52:55], v[174:177], v[190:193], v[52:55]
	v_mfma_f32_16x16x32_bf16 v[48:51], v[182:185], v[190:193], v[48:51]
	v_mfma_f32_16x16x32_bf16 v[36:39], v[174:177], v[198:201], v[36:39]
	v_mfma_f32_16x16x32_bf16 v[32:35], v[182:185], v[198:201], v[32:35]
	v_mfma_f32_16x16x32_bf16 v[20:23], v[174:177], v[206:209], v[20:23]
	v_mfma_f32_16x16x32_bf16 v[16:19], v[182:185], v[206:209], v[16:19]
	v_mfma_f32_16x16x32_bf16 v[4:7], v[174:177], v[214:217], v[4:7]
	v_mfma_f32_16x16x32_bf16 v[0:3], v[182:185], v[214:217], v[0:3]
	s_setprio 0
	s_barrier
	s_add_i32 s45, 0, 0x18000
	v_add_u32_e32 v159, s45, v153
	s_add_i32 s46, 0, 0x1c000
	ds_read_b128 v[144:147], v159
	ds_read_b128 v[148:151], v159 offset:1024
	ds_read_b128 v[160:163], v159 offset:2048
	ds_read_b128 v[164:167], v159 offset:3072
	v_add_u32_e32 v159, s46, v153
	ds_read_b128 v[168:171], v159
	ds_read_b128 v[174:177], v159 offset:1024
	ds_read_b128 v[178:181], v159 offset:2048
	ds_read_b128 v[182:185], v159 offset:3072
	s_add_u32 s22, s22, 0x80000
	s_addc_u32 s23, s23, 0
	s_mov_b32 m0, s17
	s_nop 0
	global_load_lds_dwordx4 v[222:223], off
	s_mov_b32 m0, s28
	s_nop 0
	global_load_lds_dwordx4 v[224:225], off
	s_mov_b32 m0, s29
	v_lshl_add_u64 v[226:227], s[22:23], 0, v[134:135]
	ds_read_b128 v[186:189], v158 offset:32768
	ds_read_b128 v[190:193], v158 offset:33792
	ds_read_b128 v[194:197], v158 offset:34816
	ds_read_b128 v[198:201], v158 offset:35840
	ds_read_b128 v[202:205], v158 offset:36864
	ds_read_b128 v[206:209], v158 offset:37888
	ds_read_b128 v[210:213], v158 offset:38912
	ds_read_b128 v[214:217], v158 offset:39936
	global_load_lds_dwordx4 v[226:227], off
	v_lshl_add_u64 v[226:227], s[22:23], 0, v[130:131]
	s_mov_b32 m0, s30
	s_nop 0
	global_load_lds_dwordx4 v[226:227], off
	s_waitcnt vmcnt(8)
	s_waitcnt lgkmcnt(0)
	s_barrier
	s_setprio 1
	s_waitcnt lgkmcnt(0)
	v_mfma_f32_16x16x32_bf16 v[124:127], v[144:147], v[186:189], v[124:127]
	v_mfma_f32_16x16x32_bf16 v[120:123], v[160:163], v[186:189], v[120:123]
	v_mfma_f32_16x16x32_bf16 v[108:111], v[144:147], v[194:197], v[108:111]
	v_mfma_f32_16x16x32_bf16 v[104:107], v[160:163], v[194:197], v[104:107]
	v_mfma_f32_16x16x32_bf16 v[92:95], v[144:147], v[202:205], v[92:95]
	v_mfma_f32_16x16x32_bf16 v[88:91], v[160:163], v[202:205], v[88:91]
	v_mfma_f32_16x16x32_bf16 v[76:79], v[144:147], v[210:213], v[76:79]
	v_mfma_f32_16x16x32_bf16 v[72:75], v[160:163], v[210:213], v[72:75]
	v_mfma_f32_16x16x32_bf16 v[124:127], v[148:151], v[190:193], v[124:127]
	v_mfma_f32_16x16x32_bf16 v[120:123], v[164:167], v[190:193], v[120:123]
	v_mfma_f32_16x16x32_bf16 v[108:111], v[148:151], v[198:201], v[108:111]
	v_mfma_f32_16x16x32_bf16 v[104:107], v[164:167], v[198:201], v[104:107]
	v_mfma_f32_16x16x32_bf16 v[92:95], v[148:151], v[206:209], v[92:95]
	v_mfma_f32_16x16x32_bf16 v[88:91], v[164:167], v[206:209], v[88:91]
	v_mfma_f32_16x16x32_bf16 v[76:79], v[148:151], v[214:217], v[76:79]
	v_mfma_f32_16x16x32_bf16 v[72:75], v[164:167], v[214:217], v[72:75]
	s_setprio 0
	s_setprio 1
	v_mfma_f32_16x16x32_bf16 v[116:119], v[168:171], v[186:189], v[116:119]
	v_mfma_f32_16x16x32_bf16 v[112:115], v[178:181], v[186:189], v[112:115]
	v_mfma_f32_16x16x32_bf16 v[100:103], v[168:171], v[194:197], v[100:103]
	v_mfma_f32_16x16x32_bf16 v[96:99], v[178:181], v[194:197], v[96:99]
	v_mfma_f32_16x16x32_bf16 v[84:87], v[168:171], v[202:205], v[84:87]
	v_mfma_f32_16x16x32_bf16 v[80:83], v[178:181], v[202:205], v[80:83]
	v_mfma_f32_16x16x32_bf16 v[68:71], v[168:171], v[210:213], v[68:71]
	v_mfma_f32_16x16x32_bf16 v[64:67], v[178:181], v[210:213], v[64:67]
	v_mfma_f32_16x16x32_bf16 v[116:119], v[174:177], v[190:193], v[116:119]
	v_mfma_f32_16x16x32_bf16 v[112:115], v[182:185], v[190:193], v[112:115]
	v_mfma_f32_16x16x32_bf16 v[100:103], v[174:177], v[198:201], v[100:103]
	v_mfma_f32_16x16x32_bf16 v[96:99], v[182:185], v[198:201], v[96:99]
	v_mfma_f32_16x16x32_bf16 v[84:87], v[174:177], v[206:209], v[84:87]
	v_mfma_f32_16x16x32_bf16 v[80:83], v[182:185], v[206:209], v[80:83]
	v_mfma_f32_16x16x32_bf16 v[68:71], v[174:177], v[214:217], v[68:71]
	v_mfma_f32_16x16x32_bf16 v[64:67], v[182:185], v[214:217], v[64:67]
	s_setprio 0
	s_barrier
; #define PG8_STAGE(bufoff, gbase, voff) do { _Pragma("unroll") for (int _i = 0; _i < 2; ++_i) \
;         __builtin_amdgcn_global_load_lds((const unsigned*)((const char*)(gbase) + (voff)[_i]), (PG8_LAS unsigned*)(lds + (bufoff) + ldsw + _i * 8192), 16, 0, 0); } while (0)
; #define PG8_LDA(dst, b, h) do { _Pragma("unroll") for (int m = 0; m < 4; ++m) _Pragma("unroll") for (int k = 0; k < 2; ++k) dst[m][k] = *(const PG8_LAS bf16x8*)(lds + PG8_SA(b, h) + aoff + m * 2048 + k * 1024); } while (0)
; #define PG8_MMA(ai, bj, At, Bt) do { __builtin_amdgcn_s_setprio(1); _Pragma("unroll") for (int m = 0; m < 4; ++m) _Pragma("unroll") for (int n = 0; n < 2; ++n) _Pragma("unroll") for (int k = 0; k < 2; ++k) \
;         acc[ai][bj][m][n] = __builtin_amdgcn_mfma_f32_16x16x32_bf16(Bt[n][k], At[m][k], acc[ai][bj][m][n], 0, 0, 0); __builtin_amdgcn_s_setprio(0); } while (0)
; #define PG8_WAIT_V(n) asm volatile("s_waitcnt vmcnt(" #n ")" ::: "memory")
; #define PG8_WAIT_L(n) asm volatile("s_waitcnt lgkmcnt(" #n ")" ::: "memory")
; #define PG8_BAR __builtin_amdgcn_s_barrier()
; #define PG8_SCHED __builtin_amdgcn_sched_barrier(0)
; template <class Epi, class Sched, bool ALIGN_EPI = false, bool SP2 = false>
; __device__ __forceinline__ void gemm_phase(PG8_LAS unsigned char* lds, const Gemm g, const Sched& S, const Epi& E) {
;     ...
;             PG8_LDA(At, 1, 1); PG8_STAGE(PG8_SB(1, 0), b3, voffB); PG8_STAGE(PG8_SB(1, 1), b3 + hstep, voffB); PG8_STAGE(PG8_SA(1, 0), a3, voffA);
;             PG8_WAIT_V(8); PG8_WAIT_L(0); PG8_BAR; PG8_MMA(1, 0, At, B0); PG8_MMA(1, 1, At, B1); PG8_BAR; PG8_SCHED;
	s_add_i32 s22, s45, s26
	v_lshl_add_u64 v[218:219], v[218:219], 0, s[2:3]
	s_mov_b32 m0, s22
	ds_read_b128 v[186:189], v158 offset:49152
	ds_read_b128 v[190:193], v158 offset:50176
	ds_read_b128 v[194:197], v158 offset:51200
	ds_read_b128 v[198:201], v158 offset:52224
	ds_read_b128 v[202:205], v158 offset:53248
	ds_read_b128 v[206:209], v158 offset:54272
	ds_read_b128 v[210:213], v158 offset:55296
	ds_read_b128 v[214:217], v158 offset:56320
	global_load_lds_dwordx4 v[218:219], off
	s_add_i32 m0, s22, 0x2000
	s_add_u32 s20, s20, 0x80080
	v_lshl_add_u64 v[218:219], v[220:221], 0, s[2:3]
	s_addc_u32 s21, s21, 0
	s_add_i32 s22, s46, s26
	global_load_lds_dwordx4 v[218:219], off
	v_lshl_add_u64 v[218:219], s[20:21], 0, v[132:133]
	s_mov_b32 m0, s22
	s_nop 0
	global_load_lds_dwordx4 v[218:219], off
	v_lshl_add_u64 v[218:219], s[20:21], 0, v[128:129]
	s_add_i32 m0, s22, 0x2000
	s_nop 0
	global_load_lds_dwordx4 v[218:219], off
	v_lshl_add_u64 v[218:219], v[222:223], 0, s[2:3]
	v_lshl_add_u64 v[218:219], v[224:225], 0, s[2:3]
	s_waitcnt vmcnt(6)
	s_waitcnt lgkmcnt(0)
	s_barrier
	s_setprio 1
	s_waitcnt lgkmcnt(0)
	v_mfma_f32_16x16x32_bf16 v[60:63], v[144:147], v[186:189], v[60:63]
	v_mfma_f32_16x16x32_bf16 v[56:59], v[160:163], v[186:189], v[56:59]
	v_mfma_f32_16x16x32_bf16 v[44:47], v[144:147], v[194:197], v[44:47]
	v_mfma_f32_16x16x32_bf16 v[40:43], v[160:163], v[194:197], v[40:43]
	v_mfma_f32_16x16x32_bf16 v[28:31], v[144:147], v[202:205], v[28:31]
	v_mfma_f32_16x16x32_bf16 v[24:27], v[160:163], v[202:205], v[24:27]
	v_mfma_f32_16x16x32_bf16 v[12:15], v[144:147], v[210:213], v[12:15]
	v_mfma_f32_16x16x32_bf16 v[8:11], v[160:163], v[210:213], v[8:11]
	v_mfma_f32_16x16x32_bf16 v[60:63], v[148:151], v[190:193], v[60:63]
	v_mfma_f32_16x16x32_bf16 v[56:59], v[164:167], v[190:193], v[56:59]
	v_mfma_f32_16x16x32_bf16 v[44:47], v[148:151], v[198:201], v[44:47]
	v_mfma_f32_16x16x32_bf16 v[40:43], v[164:167], v[198:201], v[40:43]
	v_mfma_f32_16x16x32_bf16 v[28:31], v[148:151], v[206:209], v[28:31]
	v_mfma_f32_16x16x32_bf16 v[24:27], v[164:167], v[206:209], v[24:27]
	v_mfma_f32_16x16x32_bf16 v[12:15], v[148:151], v[214:217], v[12:15]
	v_mfma_f32_16x16x32_bf16 v[8:11], v[164:167], v[214:217], v[8:11]
	s_setprio 0
	s_setprio 1
	v_mfma_f32_16x16x32_bf16 v[52:55], v[168:171], v[186:189], v[52:55]
	v_mfma_f32_16x16x32_bf16 v[48:51], v[178:181], v[186:189], v[48:51]
	v_mfma_f32_16x16x32_bf16 v[36:39], v[168:171], v[194:197], v[36:39]
	v_mfma_f32_16x16x32_bf16 v[32:35], v[178:181], v[194:197], v[32:35]
	v_mfma_f32_16x16x32_bf16 v[20:23], v[168:171], v[202:205], v[20:23]
	v_mfma_f32_16x16x32_bf16 v[16:19], v[178:181], v[202:205], v[16:19]
	v_mfma_f32_16x16x32_bf16 v[4:7], v[168:171], v[210:213], v[4:7]
	v_mfma_f32_16x16x32_bf16 v[0:3], v[178:181], v[210:213], v[0:3]
	v_mfma_f32_16x16x32_bf16 v[52:55], v[174:177], v[190:193], v[52:55]
	v_mfma_f32_16x16x32_bf16 v[48:51], v[182:185], v[190:193], v[48:51]
	v_mfma_f32_16x16x32_bf16 v[36:39], v[174:177], v[198:201], v[36:39]
	v_mfma_f32_16x16x32_bf16 v[32:35], v[182:185], v[198:201], v[32:35]
	v_mfma_f32_16x16x32_bf16 v[20:23], v[174:177], v[206:209], v[20:23]
	v_mfma_f32_16x16x32_bf16 v[16:19], v[182:185], v[206:209], v[16:19]
	v_mfma_f32_16x16x32_bf16 v[4:7], v[174:177], v[214:217], v[4:7]
	v_mfma_f32_16x16x32_bf16 v[0:3], v[182:185], v[214:217], v[0:3]
	s_setprio 0
	s_barrier
	s_add_i32 s44, s44, 2
	s_add_u32 s18, s18, 0x100
	s_addc_u32 s19, s19, 0
	s_add_u32 s42, s42, 0x100
	s_addc_u32 s43, s43, 0
	s_cmp_gt_u32 s44, 29
	s_cbranch_scc0 .LBB0_1712
	s_and_b64 vcc, exec, s[6:7]
	s_cbranch_vccz .LBB0_1715
	s_barrier

; #define PG8_STAGE(bufoff, gbase, voff) do { _Pragma("unroll") for (int _i = 0; _i < 2; ++_i) \
;         __builtin_amdgcn_global_load_lds((const unsigned*)((const char*)(gbase) + (voff)[_i]), (PG8_LAS unsigned*)(lds + (bufoff) + ldsw + _i * 8192), 16, 0, 0); } while (0)
; #define PG8_LDA(dst, b, h) do { _Pragma("unroll") for (int m = 0; m < 4; ++m) _Pragma("unroll") for (int k = 0; k < 2; ++k) dst[m][k] = *(const PG8_LAS bf16x8*)(lds + PG8_SA(b, h) + aoff + m * 2048 + k * 1024); } while (0)
; #define PG8_LDB(dst, b, h) do { _Pragma("unroll") for (int n = 0; n < 2; ++n) _Pragma("unroll") for (int k = 0; k < 2; ++k) dst[n][k] = *(const PG8_LAS bf16x8*)(lds + PG8_SB(b, h) + boff + n * 2048 + k * 1024); } while (0)
; #define PG8_MMA(ai, bj, At, Bt) do { __builtin_amdgcn_s_setprio(1); _Pragma("unroll") for (int m = 0; m < 4; ++m) _Pragma("unroll") for (int n = 0; n < 2; ++n) _Pragma("unroll") for (int k = 0; k < 2; ++k) \
;         acc[ai][bj][m][n] = __builtin_amdgcn_mfma_f32_16x16x32_bf16(Bt[n][k], At[m][k], acc[ai][bj][m][n], 0, 0, 0); __builtin_amdgcn_s_setprio(0); } while (0)
; #define PG8_WAIT_V(n) asm volatile("s_waitcnt vmcnt(" #n ")" ::: "memory")
; #define PG8_BAR __builtin_amdgcn_s_barrier()
; template <class Epi, class Sched, bool ALIGN_EPI = false, bool SP2 = false>
; __device__ __forceinline__ void gemm_phase(PG8_LAS unsigned char* lds, const Gemm g, const Sched& S, const Epi& E) {
;     ...
;         for (int t = 0; t < nt; t += 2) {
;             const bool last = (t == nt - 2);
;             const char* a1 = cA + (size_t)(t + 1) * kstep;
;             const char* a2 = last ? nA : cA + (size_t)(t + 2) * kstep; const char* b2 = last ? nB : cB + (size_t)(t + 2) * kstep;
;             const char* a3 = a2 + kstep; const char* b3 = b2 + kstep;
;             if (last && has_next) S.a_ready(nxt);
;             if constexpr (SP2) {
;             PG8_LDB(B0, 0, 0); PG8_LDB(B1, 0, 1); PG8_SCHED; PG8_LDA(At, 0, 0); PG8_STAGE(PG8_SA(1, 1), a1 + hstep, voffA);
;             PG8_WAIT_V(8); PG8_WAIT_L(0); PG8_BAR; PG8_MMA(0, 0, At, B0); PG8_MMA(0, 1, At, B1); PG8_BAR; PG8_SCHED;
;             PG8_LDA(At, 0, 1); PG8_STAGE(PG8_SB(0, 0), b2, voffB); PG8_STAGE(PG8_SB(0, 1), b2 + hstep, voffB); PG8_STAGE(PG8_SA(0, 0), a2, voffA);
;             PG8_WAIT_V(8); PG8_WAIT_L(0); PG8_BAR; PG8_MMA(1, 0, At, B0); PG8_MMA(1, 1, At, B1); PG8_BAR; PG8_SCHED;
.LBB0_1956:
	ds_read_b128 v[140:143], v149
	ds_read_b128 v[152:155], v149 offset:1024
	ds_read_b128 v[156:159], v149 offset:2048
	ds_read_b128 v[160:163], v149 offset:3072
	ds_read_b128 v[164:167], v150
	ds_read_b128 v[168:171], v150 offset:1024
	ds_read_b128 v[172:175], v150 offset:2048
	ds_read_b128 v[176:179], v150 offset:3072
	s_add_u32 s22, s20, 0x100
	s_addc_u32 s23, s21, 0
	s_cmpk_eq_i32 s47, 0x54
	s_cselect_b32 s27, s5, s23
	s_cselect_b32 s26, s4, s22
	s_cselect_b32 s25, s19, s46
	s_cselect_b32 s24, s18, s45
	s_mov_b32 s52, 0xffea0000
	s_mov_b32 s53, -1
	v_lshl_add_u64 v[144:145], s[20:21], 0, v[132:133]
	v_lshl_add_u64 v[144:145], v[144:145], 0, s[52:53]
	s_mov_b32 m0, s37
	s_nop 0
	global_load_lds_dwordx4 v[144:145], off
	v_lshl_add_u64 v[144:145], s[20:21], 0, v[134:135]
	v_lshl_add_u64 v[144:145], v[144:145], 0, s[52:53]
	s_mov_b32 m0, s38
	s_nop 0
	global_load_lds_dwordx4 v[144:145], off
	v_lshl_add_u64 v[144:145], s[20:21], 0, v[132:133]
	s_add_i32 m0, s31, 0xc000
	ds_read_b128 v[180:183], v151
	ds_read_b128 v[184:187], v151 offset:1024
	ds_read_b128 v[188:191], v151 offset:2048
	ds_read_b128 v[192:195], v151 offset:3072
	ds_read_b128 v[196:199], v151 offset:4096
	ds_read_b128 v[200:203], v151 offset:5120
	ds_read_b128 v[204:207], v151 offset:6144
	ds_read_b128 v[208:211], v151 offset:7168
	global_load_lds_dwordx4 v[144:145], off
	v_lshl_add_u64 v[144:145], s[20:21], 0, v[134:135]
	s_add_i32 m0, s31, 0xe000
	s_nop 0
	global_load_lds_dwordx4 v[144:145], off
	s_waitcnt vmcnt(8)
	s_waitcnt lgkmcnt(0)
	s_barrier
	s_setprio 1
	s_waitcnt lgkmcnt(0)
	v_mfma_f32_16x16x32_bf16 v[124:127], v[140:143], v[180:183], v[124:127]
	v_mfma_f32_16x16x32_bf16 v[120:123], v[156:159], v[180:183], v[120:123]
	v_mfma_f32_16x16x32_bf16 v[108:111], v[140:143], v[188:191], v[108:111]
	v_mfma_f32_16x16x32_bf16 v[104:107], v[156:159], v[188:191], v[104:107]
	v_mfma_f32_16x16x32_bf16 v[92:95], v[140:143], v[196:199], v[92:95]
	v_mfma_f32_16x16x32_bf16 v[88:91], v[156:159], v[196:199], v[88:91]
	v_mfma_f32_16x16x32_bf16 v[76:79], v[140:143], v[204:207], v[76:79]
	v_mfma_f32_16x16x32_bf16 v[72:75], v[156:159], v[204:207], v[72:75]
	v_mfma_f32_16x16x32_bf16 v[124:127], v[152:155], v[184:187], v[124:127]
	v_mfma_f32_16x16x32_bf16 v[120:123], v[160:163], v[184:187], v[120:123]
	v_mfma_f32_16x16x32_bf16 v[108:111], v[152:155], v[192:195], v[108:111]
	v_mfma_f32_16x16x32_bf16 v[104:107], v[160:163], v[192:195], v[104:107]
	v_mfma_f32_16x16x32_bf16 v[92:95], v[152:155], v[200:203], v[92:95]
	v_mfma_f32_16x16x32_bf16 v[88:91], v[160:163], v[200:203], v[88:91]
	v_mfma_f32_16x16x32_bf16 v[76:79], v[152:155], v[208:211], v[76:79]
	v_mfma_f32_16x16x32_bf16 v[72:75], v[160:163], v[208:211], v[72:75]
	s_setprio 0
	s_setprio 1
	v_mfma_f32_16x16x32_bf16 v[116:119], v[164:167], v[180:183], v[116:119]
	v_mfma_f32_16x16x32_bf16 v[112:115], v[172:175], v[180:183], v[112:115]
	v_mfma_f32_16x16x32_bf16 v[100:103], v[164:167], v[188:191], v[100:103]
	v_mfma_f32_16x16x32_bf16 v[96:99], v[172:175], v[188:191], v[96:99]
	v_mfma_f32_16x16x32_bf16 v[84:87], v[164:167], v[196:199], v[84:87]
	v_mfma_f32_16x16x32_bf16 v[80:83], v[172:175], v[196:199], v[80:83]
	v_mfma_f32_16x16x32_bf16 v[68:71], v[164:167], v[204:207], v[68:71]
	v_mfma_f32_16x16x32_bf16 v[64:67], v[172:175], v[204:207], v[64:67]
	v_mfma_f32_16x16x32_bf16 v[116:119], v[168:171], v[184:187], v[116:119]
	v_mfma_f32_16x16x32_bf16 v[112:115], v[176:179], v[184:187], v[112:115]
	v_mfma_f32_16x16x32_bf16 v[100:103], v[168:171], v[192:195], v[100:103]
	v_mfma_f32_16x16x32_bf16 v[96:99], v[176:179], v[192:195], v[96:99]
	v_mfma_f32_16x16x32_bf16 v[84:87], v[168:171], v[200:203], v[84:87]
	v_mfma_f32_16x16x32_bf16 v[80:83], v[176:179], v[200:203], v[80:83]
	v_mfma_f32_16x16x32_bf16 v[68:71], v[168:171], v[208:211], v[68:71]
	v_mfma_f32_16x16x32_bf16 v[64:67], v[176:179], v[208:211], v[64:67]
	s_setprio 0
	s_barrier
	s_add_i32 s20, s39, s30
	v_lshl_add_u64 v[144:145], s[24:25], 0, v[128:129]
	s_mov_b32 m0, s20
	ds_read_b128 v[180:183], v151 offset:16384
	ds_read_b128 v[184:187], v151 offset:17408
	ds_read_b128 v[188:191], v151 offset:18432
	ds_read_b128 v[192:195], v151 offset:19456
	ds_read_b128 v[196:199], v151 offset:20480
	ds_read_b128 v[200:203], v151 offset:21504
	ds_read_b128 v[204:207], v151 offset:22528
	ds_read_b128 v[208:211], v151 offset:23552
	global_load_lds_dwordx4 v[144:145], off
	s_add_i32 m0, s20, 0x2000
	s_add_u32 s20, s24, 0x160000
	v_lshl_add_u64 v[212:213], s[24:25], 0, v[130:131]
	s_addc_u32 s21, s25, 0
	s_add_i32 s48, s40, s30
	global_load_lds_dwordx4 v[212:213], off
	v_lshl_add_u64 v[214:215], s[20:21], 0, v[128:129]
	s_mov_b32 m0, s48
	v_lshl_add_u64 v[216:217], s[26:27], 0, v[130:131]
	global_load_lds_dwordx4 v[214:215], off
	v_lshl_add_u64 v[214:215], s[20:21], 0, v[130:131]
	s_add_i32 m0, s48, 0x2000
	s_nop 0
	global_load_lds_dwordx4 v[214:215], off
	v_lshl_add_u64 v[214:215], s[26:27], 0, v[128:129]
	s_waitcnt vmcnt(6)
	s_waitcnt lgkmcnt(0)
	s_barrier
; #define PG8_STAGE(bufoff, gbase, voff) do { _Pragma("unroll") for (int _i = 0; _i < 2; ++_i) \
;         __builtin_amdgcn_global_load_lds((const unsigned*)((const char*)(gbase) + (voff)[_i]), (PG8_LAS unsigned*)(lds + (bufoff) + ldsw + _i * 8192), 16, 0, 0); } while (0)
; #define PG8_LDA(dst, b, h) do { _Pragma("unroll") for (int m = 0; m < 4; ++m) _Pragma("unroll") for (int k = 0; k < 2; ++k) dst[m][k] = *(const PG8_LAS bf16x8*)(lds + PG8_SA(b, h) + aoff + m * 2048 + k * 1024); } while (0)
; #define PG8_LDB(dst, b, h) do { _Pragma("unroll") for (int n = 0; n < 2; ++n) _Pragma("unroll") for (int k = 0; k < 2; ++k) dst[n][k] = *(const PG8_LAS bf16x8*)(lds + PG8_SB(b, h) + boff + n * 2048 + k * 1024); } while (0)
; #define PG8_MMA(ai, bj, At, Bt) do { __builtin_amdgcn_s_setprio(1); _Pragma("unroll") for (int m = 0; m < 4; ++m) _Pragma("unroll") for (int n = 0; n < 2; ++n) _Pragma("unroll") for (int k = 0; k < 2; ++k) \
;         acc[ai][bj][m][n] = __builtin_amdgcn_mfma_f32_16x16x32_bf16(Bt[n][k], At[m][k], acc[ai][bj][m][n], 0, 0, 0); __builtin_amdgcn_s_setprio(0); } while (0)
; #define PG8_WAIT_V(n) asm volatile("s_waitcnt vmcnt(" #n ")" ::: "memory")
; #define PG8_WAIT_L(n) asm volatile("s_waitcnt lgkmcnt(" #n ")" ::: "memory")
; #define PG8_BAR __builtin_amdgcn_s_barrier()
; #define PG8_SCHED __builtin_amdgcn_sched_barrier(0)
; template <class Epi, class Sched, bool ALIGN_EPI = false, bool SP2 = false>
; __device__ __forceinline__ void gemm_phase(PG8_LAS unsigned char* lds, const Gemm g, const Sched& S, const Epi& E) {
;     ...
;             PG8_LDA(At, 0, 1); PG8_STAGE(PG8_SB(0, 0), b2, voffB); PG8_STAGE(PG8_SB(0, 1), b2 + hstep, voffB); PG8_STAGE(PG8_SA(0, 0), a2, voffA);
;             PG8_WAIT_V(8); PG8_WAIT_L(0); PG8_BAR; PG8_MMA(1, 0, At, B0); PG8_MMA(1, 1, At, B1); PG8_BAR; PG8_SCHED;
;             PG8_LDB(B0, 1, 0); PG8_LDB(B1, 1, 1); PG8_SCHED; PG8_LDA(At, 1, 0); PG8_STAGE(PG8_SA(0, 1), a2 + hstep, voffA);
;             PG8_WAIT_V(8); PG8_WAIT_L(0); PG8_BAR; PG8_MMA(0, 0, At, B0); PG8_MMA(0, 1, At, B1); PG8_BAR; PG8_SCHED;
;             PG8_LDA(At, 1, 1); PG8_STAGE(PG8_SB(1, 0), b3, voffB); PG8_STAGE(PG8_SB(1, 1), b3 + hstep, voffB); PG8_STAGE(PG8_SA(1, 0), a3, voffA);
;             PG8_WAIT_V(8); PG8_WAIT_L(0); PG8_BAR; PG8_MMA(1, 0, At, B0); PG8_MMA(1, 1, At, B1); PG8_BAR; PG8_SCHED;
	s_setprio 1
	s_waitcnt lgkmcnt(0)
	v_mfma_f32_16x16x32_bf16 v[60:63], v[140:143], v[180:183], v[60:63]
	v_mfma_f32_16x16x32_bf16 v[56:59], v[156:159], v[180:183], v[56:59]
	v_mfma_f32_16x16x32_bf16 v[44:47], v[140:143], v[188:191], v[44:47]
	v_mfma_f32_16x16x32_bf16 v[40:43], v[156:159], v[188:191], v[40:43]
	v_mfma_f32_16x16x32_bf16 v[28:31], v[140:143], v[196:199], v[28:31]
	v_mfma_f32_16x16x32_bf16 v[24:27], v[156:159], v[196:199], v[24:27]
	v_mfma_f32_16x16x32_bf16 v[12:15], v[140:143], v[204:207], v[12:15]
	v_mfma_f32_16x16x32_bf16 v[8:11], v[156:159], v[204:207], v[8:11]
	v_mfma_f32_16x16x32_bf16 v[60:63], v[152:155], v[184:187], v[60:63]
	v_mfma_f32_16x16x32_bf16 v[56:59], v[160:163], v[184:187], v[56:59]
	v_mfma_f32_16x16x32_bf16 v[44:47], v[152:155], v[192:195], v[44:47]
	v_mfma_f32_16x16x32_bf16 v[40:43], v[160:163], v[192:195], v[40:43]
	v_mfma_f32_16x16x32_bf16 v[28:31], v[152:155], v[200:203], v[28:31]
	v_mfma_f32_16x16x32_bf16 v[24:27], v[160:163], v[200:203], v[24:27]
	v_mfma_f32_16x16x32_bf16 v[12:15], v[152:155], v[208:211], v[12:15]
	v_mfma_f32_16x16x32_bf16 v[8:11], v[160:163], v[208:211], v[8:11]
	s_setprio 0
	s_setprio 1
	v_mfma_f32_16x16x32_bf16 v[52:55], v[164:167], v[180:183], v[52:55]
	v_mfma_f32_16x16x32_bf16 v[48:51], v[172:175], v[180:183], v[48:51]
	v_mfma_f32_16x16x32_bf16 v[36:39], v[164:167], v[188:191], v[36:39]
	v_mfma_f32_16x16x32_bf16 v[32:35], v[172:175], v[188:191], v[32:35]
	v_mfma_f32_16x16x32_bf16 v[20:23], v[164:167], v[196:199], v[20:23]
	v_mfma_f32_16x16x32_bf16 v[16:19], v[172:175], v[196:199], v[16:19]
	v_mfma_f32_16x16x32_bf16 v[4:7], v[164:167], v[204:207], v[4:7]
	v_mfma_f32_16x16x32_bf16 v[0:3], v[172:175], v[204:207], v[0:3]
	v_mfma_f32_16x16x32_bf16 v[52:55], v[168:171], v[184:187], v[52:55]
	v_mfma_f32_16x16x32_bf16 v[48:51], v[176:179], v[184:187], v[48:51]
	v_mfma_f32_16x16x32_bf16 v[36:39], v[168:171], v[192:195], v[36:39]
	v_mfma_f32_16x16x32_bf16 v[32:35], v[176:179], v[192:195], v[32:35]
	v_mfma_f32_16x16x32_bf16 v[20:23], v[168:171], v[200:203], v[20:23]
	v_mfma_f32_16x16x32_bf16 v[16:19], v[176:179], v[200:203], v[16:19]
	v_mfma_f32_16x16x32_bf16 v[4:7], v[168:171], v[208:211], v[4:7]
	v_mfma_f32_16x16x32_bf16 v[0:3], v[176:179], v[208:211], v[0:3]
	s_setprio 0
	s_barrier
	s_add_i32 s48, 0, 0x18000
	s_add_i32 s49, 0, 0x1c000
	v_add_u32_e32 v160, s48, v147
	v_add_u32_e32 v176, s49, v147
	ds_read_b128 v[140:143], v160
	ds_read_b128 v[152:155], v160 offset:1024
	ds_read_b128 v[156:159], v160 offset:2048
	ds_read_b128 v[160:163], v160 offset:3072
	ds_read_b128 v[164:167], v176
	ds_read_b128 v[168:171], v176 offset:1024
	ds_read_b128 v[172:175], v176 offset:2048
	ds_read_b128 v[176:179], v176 offset:3072
	s_add_u32 s20, s26, 0x160000
	s_addc_u32 s21, s27, 0
	s_mov_b32 m0, s31
	s_nop 0
	global_load_lds_dwordx4 v[214:215], off
	s_mov_b32 m0, s33
	s_nop 0
	global_load_lds_dwordx4 v[216:217], off
	s_mov_b32 m0, s34
	v_lshl_add_u64 v[218:219], s[20:21], 0, v[128:129]
	ds_read_b128 v[180:183], v151 offset:32768
	ds_read_b128 v[184:187], v151 offset:33792
	ds_read_b128 v[188:191], v151 offset:34816
	ds_read_b128 v[192:195], v151 offset:35840
	ds_read_b128 v[196:199], v151 offset:36864
	ds_read_b128 v[200:203], v151 offset:37888
	ds_read_b128 v[204:207], v151 offset:38912
	ds_read_b128 v[208:211], v151 offset:39936
	global_load_lds_dwordx4 v[218:219], off
	v_lshl_add_u64 v[218:219], s[20:21], 0, v[130:131]
	s_mov_b32 m0, s35
	s_nop 0
	global_load_lds_dwordx4 v[218:219], off
	s_waitcnt vmcnt(8)
	s_waitcnt lgkmcnt(0)
	s_barrier
	s_setprio 1
	s_waitcnt lgkmcnt(0)
	v_mfma_f32_16x16x32_bf16 v[124:127], v[140:143], v[180:183], v[124:127]
	v_mfma_f32_16x16x32_bf16 v[120:123], v[156:159], v[180:183], v[120:123]
	v_mfma_f32_16x16x32_bf16 v[108:111], v[140:143], v[188:191], v[108:111]
	v_mfma_f32_16x16x32_bf16 v[104:107], v[156:159], v[188:191], v[104:107]
	v_mfma_f32_16x16x32_bf16 v[92:95], v[140:143], v[196:199], v[92:95]
	v_mfma_f32_16x16x32_bf16 v[88:91], v[156:159], v[196:199], v[88:91]
	v_mfma_f32_16x16x32_bf16 v[76:79], v[140:143], v[204:207], v[76:79]
	v_mfma_f32_16x16x32_bf16 v[72:75], v[156:159], v[204:207], v[72:75]
	v_mfma_f32_16x16x32_bf16 v[124:127], v[152:155], v[184:187], v[124:127]
	v_mfma_f32_16x16x32_bf16 v[120:123], v[160:163], v[184:187], v[120:123]
	v_mfma_f32_16x16x32_bf16 v[108:111], v[152:155], v[192:195], v[108:111]
	v_mfma_f32_16x16x32_bf16 v[104:107], v[160:163], v[192:195], v[104:107]
	v_mfma_f32_16x16x32_bf16 v[92:95], v[152:155], v[200:203], v[92:95]
	v_mfma_f32_16x16x32_bf16 v[88:91], v[160:163], v[200:203], v[88:91]
	v_mfma_f32_16x16x32_bf16 v[76:79], v[152:155], v[208:211], v[76:79]
	v_mfma_f32_16x16x32_bf16 v[72:75], v[160:163], v[208:211], v[72:75]
	s_setprio 0
	s_setprio 1
	v_mfma_f32_16x16x32_bf16 v[116:119], v[164:167], v[180:183], v[116:119]
	v_mfma_f32_16x16x32_bf16 v[112:115], v[172:175], v[180:183], v[112:115]
	v_mfma_f32_16x16x32_bf16 v[100:103], v[164:167], v[188:191], v[100:103]
	v_mfma_f32_16x16x32_bf16 v[96:99], v[172:175], v[188:191], v[96:99]
	v_mfma_f32_16x16x32_bf16 v[84:87], v[164:167], v[196:199], v[84:87]
	v_mfma_f32_16x16x32_bf16 v[80:83], v[172:175], v[196:199], v[80:83]
	v_mfma_f32_16x16x32_bf16 v[68:71], v[164:167], v[204:207], v[68:71]
	v_mfma_f32_16x16x32_bf16 v[64:67], v[172:175], v[204:207], v[64:67]
	v_mfma_f32_16x16x32_bf16 v[116:119], v[168:171], v[184:187], v[116:119]
	v_mfma_f32_16x16x32_bf16 v[112:115], v[176:179], v[184:187], v[112:115]
	v_mfma_f32_16x16x32_bf16 v[100:103], v[168:171], v[192:195], v[100:103]
	v_mfma_f32_16x16x32_bf16 v[96:99], v[176:179], v[192:195], v[96:99]
	v_mfma_f32_16x16x32_bf16 v[84:87], v[168:171], v[200:203], v[84:87]
	v_mfma_f32_16x16x32_bf16 v[80:83], v[176:179], v[200:203], v[80:83]
	v_mfma_f32_16x16x32_bf16 v[68:71], v[168:171], v[208:211], v[68:71]
	v_mfma_f32_16x16x32_bf16 v[64:67], v[176:179], v[208:211], v[64:67]
	s_setprio 0
	s_barrier
; #define PG8_STAGE(bufoff, gbase, voff) do { _Pragma("unroll") for (int _i = 0; _i < 2; ++_i) \
;         __builtin_amdgcn_global_load_lds((const unsigned*)((const char*)(gbase) + (voff)[_i]), (PG8_LAS unsigned*)(lds + (bufoff) + ldsw + _i * 8192), 16, 0, 0); } while (0)
; #define PG8_LDA(dst, b, h) do { _Pragma("unroll") for (int m = 0; m < 4; ++m) _Pragma("unroll") for (int k = 0; k < 2; ++k) dst[m][k] = *(const PG8_LAS bf16x8*)(lds + PG8_SA(b, h) + aoff + m * 2048 + k * 1024); } while (0)
; #define PG8_LDB(dst, b, h) do { _Pragma("unroll") for (int n = 0; n < 2; ++n) _Pragma("unroll") for (int k = 0; k < 2; ++k) dst[n][k] = *(const PG8_LAS bf16x8*)(lds + PG8_SB(b, h) + boff + n * 2048 + k * 1024); } while (0)
; #define PG8_MMA(ai, bj, At, Bt) do { __builtin_amdgcn_s_setprio(1); _Pragma("unroll") for (int m = 0; m < 4; ++m) _Pragma("unroll") for (int n = 0; n < 2; ++n) _Pragma("unroll") for (int k = 0; k < 2; ++k) \
;         acc[ai][bj][m][n] = __builtin_amdgcn_mfma_f32_16x16x32_bf16(Bt[n][k], At[m][k], acc[ai][bj][m][n], 0, 0, 0); __builtin_amdgcn_s_setprio(0); } while (0)
; #define PG8_WAIT_V(n) asm volatile("s_waitcnt vmcnt(" #n ")" ::: "memory")
; #define PG8_WAIT_L(n) asm volatile("s_waitcnt lgkmcnt(" #n ")" ::: "memory")
; #define PG8_BAR __builtin_amdgcn_s_barrier()
; #define PG8_SCHED __builtin_amdgcn_sched_barrier(0)
; template <class Epi, class Sched, bool ALIGN_EPI = false, bool SP2 = false>
; __device__ __forceinline__ void gemm_phase(PG8_LAS unsigned char* lds, const Gemm g, const Sched& S, const Epi& E) {
;     ...
;         for (int t = 0; t < nt; t += 2) {
;     ...
;             PG8_LDB(B0, 1, 0); PG8_LDB(B1, 1, 1); PG8_SCHED; PG8_LDA(At, 1, 0); PG8_STAGE(PG8_SA(0, 1), a2 + hstep, voffA);
;             PG8_WAIT_V(8); PG8_WAIT_L(0); PG8_BAR; PG8_MMA(0, 0, At, B0); PG8_MMA(0, 1, At, B1); PG8_BAR; PG8_SCHED;
;             PG8_LDA(At, 1, 1); PG8_STAGE(PG8_SB(1, 0), b3, voffB); PG8_STAGE(PG8_SB(1, 1), b3 + hstep, voffB); PG8_STAGE(PG8_SA(1, 0), a3, voffA);
;             PG8_WAIT_V(8); PG8_WAIT_L(0); PG8_BAR; PG8_MMA(1, 0, At, B0); PG8_MMA(1, 1, At, B1); PG8_BAR; PG8_SCHED;
	s_add_i32 s20, s48, s30
	v_lshl_add_u64 v[144:145], v[144:145], 0, s[6:7]
	s_mov_b32 m0, s20
	ds_read_b128 v[180:183], v151 offset:49152
	ds_read_b128 v[184:187], v151 offset:50176
	ds_read_b128 v[188:191], v151 offset:51200
	ds_read_b128 v[192:195], v151 offset:52224
	ds_read_b128 v[196:199], v151 offset:53248
	ds_read_b128 v[200:203], v151 offset:54272
	ds_read_b128 v[204:207], v151 offset:55296
	ds_read_b128 v[208:211], v151 offset:56320
	global_load_lds_dwordx4 v[144:145], off
	s_add_i32 m0, s20, 0x2000
	s_add_u32 s20, s24, 0x160080
	v_lshl_add_u64 v[144:145], v[212:213], 0, s[6:7]
	s_addc_u32 s21, s25, 0
	s_add_i32 s24, s49, s30
	global_load_lds_dwordx4 v[144:145], off
	v_lshl_add_u64 v[144:145], s[20:21], 0, v[128:129]
	s_mov_b32 m0, s24
	s_nop 0
	global_load_lds_dwordx4 v[144:145], off
	v_lshl_add_u64 v[144:145], s[20:21], 0, v[130:131]
	s_add_i32 m0, s24, 0x2000
	s_nop 0
	global_load_lds_dwordx4 v[144:145], off
	v_lshl_add_u64 v[144:145], v[214:215], 0, s[6:7]
	v_lshl_add_u64 v[144:145], v[216:217], 0, s[6:7]
	s_waitcnt vmcnt(6)
	s_waitcnt lgkmcnt(0)
	s_barrier
	s_setprio 1
	s_waitcnt lgkmcnt(0)
	v_mfma_f32_16x16x32_bf16 v[60:63], v[140:143], v[180:183], v[60:63]
	v_mfma_f32_16x16x32_bf16 v[56:59], v[156:159], v[180:183], v[56:59]
	v_mfma_f32_16x16x32_bf16 v[44:47], v[140:143], v[188:191], v[44:47]
	v_mfma_f32_16x16x32_bf16 v[40:43], v[156:159], v[188:191], v[40:43]
	v_mfma_f32_16x16x32_bf16 v[28:31], v[140:143], v[196:199], v[28:31]
	v_mfma_f32_16x16x32_bf16 v[24:27], v[156:159], v[196:199], v[24:27]
	v_mfma_f32_16x16x32_bf16 v[12:15], v[140:143], v[204:207], v[12:15]
	v_mfma_f32_16x16x32_bf16 v[8:11], v[156:159], v[204:207], v[8:11]
	v_mfma_f32_16x16x32_bf16 v[60:63], v[152:155], v[184:187], v[60:63]
	v_mfma_f32_16x16x32_bf16 v[56:59], v[160:163], v[184:187], v[56:59]
	v_mfma_f32_16x16x32_bf16 v[44:47], v[152:155], v[192:195], v[44:47]
	v_mfma_f32_16x16x32_bf16 v[40:43], v[160:163], v[192:195], v[40:43]
	v_mfma_f32_16x16x32_bf16 v[28:31], v[152:155], v[200:203], v[28:31]
	v_mfma_f32_16x16x32_bf16 v[24:27], v[160:163], v[200:203], v[24:27]
	v_mfma_f32_16x16x32_bf16 v[12:15], v[152:155], v[208:211], v[12:15]
	v_mfma_f32_16x16x32_bf16 v[8:11], v[160:163], v[208:211], v[8:11]
	s_setprio 0
	s_setprio 1
	v_mfma_f32_16x16x32_bf16 v[52:55], v[164:167], v[180:183], v[52:55]
	v_mfma_f32_16x16x32_bf16 v[48:51], v[172:175], v[180:183], v[48:51]
	v_mfma_f32_16x16x32_bf16 v[36:39], v[164:167], v[188:191], v[36:39]
	v_mfma_f32_16x16x32_bf16 v[32:35], v[172:175], v[188:191], v[32:35]
	v_mfma_f32_16x16x32_bf16 v[20:23], v[164:167], v[196:199], v[20:23]
	v_mfma_f32_16x16x32_bf16 v[16:19], v[172:175], v[196:199], v[16:19]
	v_mfma_f32_16x16x32_bf16 v[4:7], v[164:167], v[204:207], v[4:7]
	v_mfma_f32_16x16x32_bf16 v[0:3], v[172:175], v[204:207], v[0:3]
	v_mfma_f32_16x16x32_bf16 v[52:55], v[168:171], v[184:187], v[52:55]
	v_mfma_f32_16x16x32_bf16 v[48:51], v[176:179], v[184:187], v[48:51]
	v_mfma_f32_16x16x32_bf16 v[36:39], v[168:171], v[192:195], v[36:39]
	v_mfma_f32_16x16x32_bf16 v[32:35], v[176:179], v[192:195], v[32:35]
	v_mfma_f32_16x16x32_bf16 v[20:23], v[168:171], v[200:203], v[20:23]
	v_mfma_f32_16x16x32_bf16 v[16:19], v[176:179], v[200:203], v[16:19]
	v_mfma_f32_16x16x32_bf16 v[4:7], v[168:171], v[208:211], v[4:7]
	v_mfma_f32_16x16x32_bf16 v[0:3], v[176:179], v[208:211], v[0:3]
	s_setprio 0
	s_barrier
	s_add_i32 s47, s47, 2
	s_add_u32 s45, s45, 0x100
	s_addc_u32 s46, s46, 0
	s_cmpk_gt_u32 s47, 0x55
	s_mov_b64 s[20:21], s[22:23]
	s_cbranch_scc0 .LBB0_1956
	s_and_b64 vcc, exec, s[8:9]
	s_cbranch_vccz .LBB0_1959
	s_barrier
